# 16-byte (dwordx4) stores made write-through (sc1) so they leave no dirty L2 lines for the barrier write-back; sample attention one tile per wave
# speedup vs baseline: 1.1350x; 1.0096x over previous
; #define LAS __attribute__((address_space(3)))
; __device__ __forceinline__ unsigned pk2(float lo, float hi) { const f32x2_t v = {lo, hi}; const bf16x2_t b = __builtin_convertvector(v, bf16x2_t); return __builtin_bit_cast(unsigned, b); }
; #define LDS_WAIT() asm volatile("s_waitcnt lgkmcnt(0)" ::: "memory")
; __device__ __forceinline__ void p0_finish(const TDesc& d, float (&wv)[32], LAS float* scr, int lane) {
;     const int nblk = d.N / 32, kb = d.item / nblk, nb = d.item % nblk, k0 = 64 * kb, n0 = 32 * nb, K = d.K;
;     ...
;     for (int i = 0; i < 32; ++i) scr[(2 * i + (lane >> 5)) * 33 + (lane & 31)] = wv[i];
;     LDS_WAIT(); asm volatile("" ::: "memory");
;     const int c = lane & 7;
; #pragma unroll
;     for (int j = 0; j < 4; ++j) { const int n = (lane >> 3) + 8 * j; const LAS float* sp = scr + (8 * c) * 33 + n;
;         u32x4 o; o.x = pk2(sp[0 * 33], sp[1 * 33]); o.y = pk2(sp[2 * 33], sp[3 * 33]); o.z = pk2(sp[4 * 33], sp[5 * 33]); o.w = pk2(sp[6 * 33], sp[7 * 33]);
;         *(u32x4*)(d.WT + (size_t)(n0 + n) * K + k0 + 8 * c) = o; }
.LBB0_26:
	v_add_u32_e32 v5, 0x2000, v77
	ds_write2_b32 v5, v8, v9 offset0:64 offset1:130
	v_add_u32_e32 v5, 0x2200, v77
	ds_write2_b32 v5, v10, v11 offset0:68 offset1:134
	v_add_u32_e32 v5, 0x2400, v77
	ds_write2_b32 v5, v12, v13 offset0:72 offset1:138
	v_add_u32_e32 v5, 0x2600, v77
	ds_write2_b32 v5, v14, v15 offset0:76 offset1:142
	v_add_u32_e32 v5, 0x2800, v77
	ds_write2_b32 v5, v16, v17 offset0:80 offset1:146
	v_add_u32_e32 v5, 0x2a00, v77
	ds_write2_b32 v5, v18, v19 offset0:84 offset1:150
	v_add_u32_e32 v5, 0x2c00, v77
	ds_write2_b32 v5, v20, v21 offset0:88 offset1:154
	v_add_u32_e32 v5, 0x2e00, v77
	ds_write2_b32 v5, v22, v23 offset0:92 offset1:158
	v_add_u32_e32 v5, 0x3000, v77
	ds_write2_b32 v5, v24, v25 offset0:96 offset1:162
	v_add_u32_e32 v5, 0x3200, v77
	ds_write2_b32 v5, v26, v27 offset0:100 offset1:166
	v_add_u32_e32 v5, 0x3400, v77
	ds_write2_b32 v5, v28, v29 offset0:104 offset1:170
	v_add_u32_e32 v5, 0x3600, v77
	ds_write2_b32 v5, v30, v31 offset0:108 offset1:174
	v_add_u32_e32 v5, 0x3800, v77
	ds_write2_b32 v5, v32, v33 offset0:112 offset1:178
	v_add_u32_e32 v5, 0x3a00, v77
	ds_write2_b32 v5, v34, v35 offset0:116 offset1:182
	v_add_u32_e32 v5, 0x3c00, v77
	ds_write2_b32 v5, v36, v37 offset0:120 offset1:186
	v_add_u32_e32 v5, 0x3e00, v77
	ds_write2_b32 v5, v38, v39 offset0:124 offset1:190
	s_waitcnt lgkmcnt(0)
	v_add_u32_e32 v5, 0x2000, v79
	ds_read2_b32 v[44:45], v5 offset0:97 offset1:105
	ds_read2_b32 v[46:47], v5 offset0:64 offset1:72
	ds_read2_b32 v[48:49], v5 offset0:130 offset1:138
	ds_read2_b32 v[50:51], v5 offset0:163 offset1:171
	ds_read2_b32 v[52:53], v5 offset0:196 offset1:204
	ds_read2_b32 v[54:55], v5 offset0:229 offset1:237
	v_add_u32_e32 v62, 0x2400, v79
	s_waitcnt lgkmcnt(4)
	v_cvt_pk_bf16_f32 v40, v46, v44
	v_add_u32_e32 v44, s4, v78
	ds_read2_b32 v[56:57], v62 offset0:6 offset1:14
	ds_read2_b32 v[58:59], v62 offset0:39 offset1:47
	v_ashrrev_i32_e32 v46, 31, v44
	s_waitcnt lgkmcnt(4)
	v_cvt_pk_bf16_f32 v41, v48, v50
	v_mul_lo_u32 v46, s40, v46
	v_mul_lo_u32 v48, s41, v44
	v_mad_u64_u32 v[60:61], s[30:31], s40, v44, 0
	s_ashr_i32 s43, s42, 31
	v_add3_u32 v61, v61, v46, v48
	v_lshl_add_u64 v[60:61], v[60:61], 1, s[38:39]
	s_lshl_b64 s[30:31], s[42:43], 1
	v_lshl_add_u64 v[60:61], v[60:61], 0, s[30:31]
	s_waitcnt lgkmcnt(2)
	v_cvt_pk_bf16_f32 v42, v52, v54
	s_waitcnt lgkmcnt(0)
	v_cvt_pk_bf16_f32 v43, v56, v58
	v_lshl_add_u64 v[60:61], v[60:61], 0, v[2:3]
	v_add_u32_e32 v44, s4, v80
	global_store_dwordx4 v[60:61], v[40:43], off sc1
	s_nop 1
	v_cvt_pk_bf16_f32 v40, v47, v45
	v_ashrrev_i32_e32 v45, 31, v44
	v_mul_lo_u32 v46, s40, v45
	v_mul_lo_u32 v47, s41, v44
	v_mad_u64_u32 v[44:45], s[42:43], s40, v44, 0
	v_add3_u32 v45, v45, v46, v47
	v_lshl_add_u64 v[44:45], v[44:45], 1, s[38:39]
	v_lshl_add_u64 v[44:45], v[44:45], 0, s[30:31]
	v_cvt_pk_bf16_f32 v41, v49, v51
	v_cvt_pk_bf16_f32 v42, v53, v55
	v_cvt_pk_bf16_f32 v43, v57, v59
	v_lshl_add_u64 v[44:45], v[44:45], 0, v[2:3]
	ds_read2_b32 v[46:47], v5 offset0:80 offset1:88
	ds_read2_b32 v[48:49], v5 offset0:113 offset1:121
	ds_read2_b32 v[50:51], v5 offset0:146 offset1:154
	ds_read2_b32 v[52:53], v5 offset0:179 offset1:187
	ds_read2_b32 v[54:55], v5 offset0:212 offset1:220
	ds_read2_b32 v[56:57], v5 offset0:245 offset1:253
	ds_read2_b32 v[58:59], v62 offset0:22 offset1:30
	ds_read2_b32 v[60:61], v62 offset0:55 offset1:63
	v_add_u32_e32 v5, s4, v81
	global_store_dwordx4 v[44:45], v[40:43], off sc1
	v_ashrrev_i32_e32 v44, 31, v5
	s_waitcnt lgkmcnt(6)
	v_cvt_pk_bf16_f32 v40, v46, v48
	v_mul_lo_u32 v46, s40, v44
	v_mul_lo_u32 v48, s41, v5
	v_mad_u64_u32 v[44:45], s[42:43], s40, v5, 0
	v_add3_u32 v45, v45, v46, v48
	v_lshl_add_u64 v[44:45], v[44:45], 1, s[38:39]
	v_lshl_add_u64 v[44:45], v[44:45], 0, s[30:31]
	s_waitcnt lgkmcnt(4)
	v_cvt_pk_bf16_f32 v41, v50, v52
	s_waitcnt lgkmcnt(2)
	v_cvt_pk_bf16_f32 v42, v54, v56
	s_waitcnt lgkmcnt(0)
	v_cvt_pk_bf16_f32 v43, v58, v60
	v_lshl_add_u64 v[44:45], v[44:45], 0, v[2:3]
	v_add_u32_e32 v5, s4, v82
	global_store_dwordx4 v[44:45], v[40:43], off sc1
	v_ashrrev_i32_e32 v44, 31, v5
	v_mul_lo_u32 v46, s40, v44
	v_cvt_pk_bf16_f32 v40, v47, v49
	v_mul_lo_u32 v47, s41, v5
	v_mad_u64_u32 v[44:45], s[4:5], s40, v5, 0
	v_add3_u32 v45, v45, v46, v47
	v_lshl_add_u64 v[44:45], v[44:45], 1, s[38:39]
	v_lshl_add_u64 v[44:45], v[44:45], 0, s[30:31]
	v_cvt_pk_bf16_f32 v41, v51, v53
	v_cvt_pk_bf16_f32 v42, v55, v57
	v_cvt_pk_bf16_f32 v43, v59, v61
	v_lshl_add_u64 v[44:45], v[44:45], 0, v[2:3]
	global_store_dwordx4 v[44:45], v[40:43], off sc1
	s_waitcnt lgkmcnt(0)

; #define LAS __attribute__((address_space(3)))
; __device__ __forceinline__ unsigned pk2(float lo, float hi) { const f32x2_t v = {lo, hi}; const bf16x2_t b = __builtin_convertvector(v, bf16x2_t); return __builtin_bit_cast(unsigned, b); }
; #define LDS_WAIT() asm volatile("s_waitcnt lgkmcnt(0)" ::: "memory")
; __device__ __forceinline__ void p0_load(const TDesc& d, float (&wv)[32], int lane) {
;     const int nblk = d.N / 32, kb = d.item / nblk, nb = d.item % nblk, k0 = 64 * kb, n0 = 32 * nb;
; #pragma unroll
;     for (int i = 0; i < 32; ++i) wv[i] = d.W[(size_t)(k0 + 2 * i + (lane >> 5)) * d.N + n0 + (lane & 31)];
; }
; __device__ __forceinline__ void p0_finish(const TDesc& d, float (&wv)[32], LAS float* scr, int lane) {
;     const int nblk = d.N / 32, kb = d.item / nblk, nb = d.item % nblk, k0 = 64 * kb, n0 = 32 * nb, K = d.K;
;     ...
;     for (int i = 0; i < 32; ++i) scr[(2 * i + (lane >> 5)) * 33 + (lane & 31)] = wv[i];
;     LDS_WAIT(); asm volatile("" ::: "memory");
;     const int c = lane & 7;
; #pragma unroll
;     for (int j = 0; j < 4; ++j) { const int n = (lane >> 3) + 8 * j; const LAS float* sp = scr + (8 * c) * 33 + n;
;         u32x4 o; o.x = pk2(sp[0 * 33], sp[1 * 33]); o.y = pk2(sp[2 * 33], sp[3 * 33]); o.z = pk2(sp[4 * 33], sp[5 * 33]); o.w = pk2(sp[6 * 33], sp[7 * 33]);
;         *(u32x4*)(d.WT + (size_t)(n0 + n) * K + k0 + 8 * c) = o; }
.LBB0_84:
	v_add_u32_e32 v5, 0x400, v77
	s_waitcnt vmcnt(30)
	ds_write2_b32 v77, v40, v41 offset1:66
	s_waitcnt vmcnt(28)
	ds_write2_b32 v77, v42, v43 offset0:132 offset1:198
	s_waitcnt vmcnt(26)
	ds_write2_b32 v5, v44, v45 offset0:8 offset1:74
	s_waitcnt vmcnt(24)
	ds_write2_b32 v5, v46, v47 offset0:140 offset1:206
	v_add_u32_e32 v5, 0x800, v77
	s_waitcnt vmcnt(22)
	ds_write2_b32 v5, v48, v49 offset0:16 offset1:82
	s_waitcnt vmcnt(20)
	ds_write2_b32 v5, v50, v51 offset0:148 offset1:214
	v_add_u32_e32 v5, 0xc00, v77
	s_waitcnt vmcnt(18)
	ds_write2_b32 v5, v52, v53 offset0:24 offset1:90
	s_waitcnt vmcnt(16)
	ds_write2_b32 v5, v54, v55 offset0:156 offset1:222
	v_add_u32_e32 v5, 0x1000, v77
	s_waitcnt vmcnt(14)
	ds_write2_b32 v5, v56, v57 offset0:32 offset1:98
	s_waitcnt vmcnt(12)
	ds_write2_b32 v5, v58, v59 offset0:164 offset1:230
	v_add_u32_e32 v5, 0x1400, v77
	s_waitcnt vmcnt(10)
	ds_write2_b32 v5, v60, v61 offset0:40 offset1:106
	s_waitcnt vmcnt(8)
	ds_write2_b32 v5, v62, v63 offset0:172 offset1:238
	v_add_u32_e32 v5, 0x1800, v77
	s_waitcnt vmcnt(6)
	ds_write2_b32 v5, v64, v65 offset0:48 offset1:114
	s_waitcnt vmcnt(4)
	ds_write2_b32 v5, v66, v67 offset0:180 offset1:246
	v_add_u32_e32 v5, 0x1c00, v77
	s_waitcnt vmcnt(2)
	ds_write2_b32 v5, v68, v69 offset0:56 offset1:122
	s_waitcnt vmcnt(0)
	ds_write2_b32 v5, v70, v71 offset0:188 offset1:254
	s_waitcnt lgkmcnt(0)
	ds_read2_b32 v[44:45], v79 offset0:33 offset1:41
	ds_read2_b32 v[46:47], v79 offset1:8
	ds_read2_b32 v[48:49], v79 offset0:66 offset1:74
	ds_read2_b32 v[50:51], v79 offset0:99 offset1:107
	ds_read2_b32 v[52:53], v79 offset0:132 offset1:140
	ds_read2_b32 v[54:55], v79 offset0:165 offset1:173
	ds_read2_b32 v[56:57], v79 offset0:198 offset1:206
	ds_read2_b32 v[58:59], v79 offset0:231 offset1:239
	v_add_u32_e32 v5, s58, v78
	s_waitcnt lgkmcnt(0)
	v_cvt_pk_bf16_f32 v40, v46, v44
	v_ashrrev_i32_e32 v44, 31, v5
	v_mul_lo_u32 v44, s44, v44
	v_mul_lo_u32 v46, s45, v5
	v_mad_u64_u32 v[60:61], s[48:49], s44, v5, 0
	s_ashr_i32 s61, s60, 31
	v_add3_u32 v61, v61, v44, v46
	v_lshl_add_u64 v[60:61], v[60:61], 1, s[42:43]
	s_lshl_b64 s[48:49], s[60:61], 1
	v_lshl_add_u64 v[60:61], v[60:61], 0, s[48:49]
	v_add_u32_e32 v5, s58, v80
	v_cvt_pk_bf16_f32 v41, v48, v50
	v_cvt_pk_bf16_f32 v42, v52, v54
	v_cvt_pk_bf16_f32 v43, v56, v58
	v_lshl_add_u64 v[60:61], v[60:61], 0, v[2:3]
	v_ashrrev_i32_e32 v44, 31, v5
	global_store_dwordx4 v[60:61], v[40:43], off sc1
	v_mul_lo_u32 v46, s44, v44
	s_and_b64 vcc, exec, s[4:5]
	v_cvt_pk_bf16_f32 v40, v47, v45
	v_mul_lo_u32 v47, s45, v5
	v_mad_u64_u32 v[44:45], s[54:55], s44, v5, 0
	v_add3_u32 v45, v45, v46, v47
	v_lshl_add_u64 v[44:45], v[44:45], 1, s[42:43]
	v_lshl_add_u64 v[44:45], v[44:45], 0, s[48:49]
	v_cvt_pk_bf16_f32 v41, v49, v51
	v_cvt_pk_bf16_f32 v42, v53, v55
	v_cvt_pk_bf16_f32 v43, v57, v59
	v_lshl_add_u64 v[44:45], v[44:45], 0, v[2:3]
	v_add_u32_e32 v5, s58, v81
	ds_read2_b32 v[46:47], v79 offset0:16 offset1:24
	ds_read2_b32 v[48:49], v79 offset0:49 offset1:57
	ds_read2_b32 v[50:51], v79 offset0:82 offset1:90
	ds_read2_b32 v[52:53], v79 offset0:115 offset1:123
	ds_read2_b32 v[54:55], v79 offset0:148 offset1:156
	ds_read2_b32 v[56:57], v79 offset0:181 offset1:189
	ds_read2_b32 v[58:59], v79 offset0:214 offset1:222
	ds_read2_b32 v[60:61], v79 offset0:247 offset1:255
	global_store_dwordx4 v[44:45], v[40:43], off sc1
	v_ashrrev_i32_e32 v44, 31, v5
	s_waitcnt lgkmcnt(6)
	v_cvt_pk_bf16_f32 v40, v46, v48
	v_mul_lo_u32 v46, s44, v44
	v_mul_lo_u32 v48, s45, v5
	v_mad_u64_u32 v[44:45], s[54:55], s44, v5, 0
	v_add3_u32 v45, v45, v46, v48
	v_lshl_add_u64 v[44:45], v[44:45], 1, s[42:43]
	v_lshl_add_u64 v[44:45], v[44:45], 0, s[48:49]
	s_waitcnt lgkmcnt(4)
	v_cvt_pk_bf16_f32 v41, v50, v52
	s_waitcnt lgkmcnt(2)
	v_cvt_pk_bf16_f32 v42, v54, v56
	s_waitcnt lgkmcnt(0)
	v_cvt_pk_bf16_f32 v43, v58, v60
	v_lshl_add_u64 v[44:45], v[44:45], 0, v[2:3]
	v_add_u32_e32 v5, s58, v82
	global_store_dwordx4 v[44:45], v[40:43], off sc1
	v_ashrrev_i32_e32 v44, 31, v5
	v_mul_lo_u32 v46, s44, v44
	v_cvt_pk_bf16_f32 v40, v47, v49
	v_mul_lo_u32 v47, s45, v5
	v_mad_u64_u32 v[44:45], s[44:45], s44, v5, 0
	v_add3_u32 v45, v45, v46, v47
	v_lshl_add_u64 v[44:45], v[44:45], 1, s[42:43]
	v_lshl_add_u64 v[44:45], v[44:45], 0, s[48:49]
	v_cvt_pk_bf16_f32 v41, v51, v53
	v_cvt_pk_bf16_f32 v42, v55, v57
	v_cvt_pk_bf16_f32 v43, v59, v61
	v_lshl_add_u64 v[44:45], v[44:45], 0, v[2:3]
	global_store_dwordx4 v[44:45], v[40:43], off sc1
	s_waitcnt lgkmcnt(0)
	s_cbranch_vccnz .LBB0_27
	s_lshr_b32 s31, s31, 5
	v_cvt_f32_i32_e32 v5, s31
	s_ashr_i32 s4, s33, 30
	s_or_b32 s33, s4, 1
	v_rcp_iflag_f32_e32 v40, v5
	s_nop 0
	v_mul_f32_e32 v40, v84, v40
	v_trunc_f32_e32 v40, v40
	v_fma_f32 v41, -v40, v5, v84
	v_cvt_i32_f32_e32 v40, v40
	v_cmp_ge_f32_e64 s[4:5], |v41|, v5
	s_and_b64 s[4:5], s[4:5], exec
	s_cselect_b32 s4, s33, 0
	v_readfirstlane_b32 s5, v40
	s_add_i32 s4, s5, s4
	s_sext_i32_i16 s44, s4
	s_mul_i32 s4, s4, s31
	s_sub_i32 s4, s30, s4
	s_sext_i32_i16 s4, s4
	s_lshl_b32 s42, s44, 6
	s_lshl_b32 s4, s4, 5
	s_cmp_eq_u64 s[50:51], 0
	s_cbranch_scc1 .LBB0_26
; __device__ __forceinline__ unsigned f2bf(float f) { unsigned u = __builtin_bit_cast(unsigned, f); return (u + 0x7fffu + ((u >> 16) & 1u)) >> 16; }
; __device__ __forceinline__ void p0_finish(const TDesc& d, float (&wv)[32], LAS float* scr, int lane) {
;     ...
;     if (d.gsc) {
;         float c1 = 0.f, c2 = 0.f;
; #pragma unroll
;         for (int i = 0; i < 32; ++i) { const int k = k0 + 2 * i + (lane >> 5); c2 += d.bsc[k] * wv[i]; wv[i] *= d.gsc[k]; c1 += bf2f((unsigned short)f2bf(wv[i])); }
	v_add_u32_e32 v40, s42, v76
	v_ashrrev_i32_e32 v41, 31, v40
	v_lshlrev_b64 v[40:41], 2, v[40:41]
	v_lshl_add_u64 v[42:43], s[52:53], 0, v[40:41]
	v_lshl_add_u64 v[40:41], s[50:51], 0, v[40:41]
	global_load_dword v5, v[42:43], off
	global_load_dword v64, v[42:43], off offset:8
	global_load_dword v44, v[40:41], off
	global_load_dword v45, v[40:41], off offset:8
	global_load_dword v65, v[42:43], off offset:16
	global_load_dword v66, v[42:43], off offset:24
	global_load_dword v46, v[40:41], off offset:16
	global_load_dword v47, v[40:41], off offset:24
	global_load_dword v67, v[42:43], off offset:32
	global_load_dword v68, v[42:43], off offset:40
	global_load_dword v48, v[40:41], off offset:32
	global_load_dword v49, v[40:41], off offset:40
	global_load_dword v69, v[42:43], off offset:48
	global_load_dword v70, v[42:43], off offset:56
	global_load_dword v50, v[40:41], off offset:48
	global_load_dword v51, v[40:41], off offset:56
	global_load_dword v71, v[42:43], off offset:64
	global_load_dword v72, v[42:43], off offset:72
	global_load_dword v52, v[40:41], off offset:64
	global_load_dword v53, v[40:41], off offset:72
	global_load_dword v73, v[42:43], off offset:80
	global_load_dword v74, v[42:43], off offset:88
	global_load_dword v54, v[40:41], off offset:80
	global_load_dword v55, v[40:41], off offset:88
	global_load_dword v75, v[42:43], off offset:96
	global_load_dword v84, v[42:43], off offset:104
	global_load_dword v85, v[42:43], off offset:112
	global_load_dword v86, v[42:43], off offset:120
	global_load_dword v56, v[40:41], off offset:96
	global_load_dword v57, v[40:41], off offset:104
	global_load_dword v58, v[40:41], off offset:112
	global_load_dword v59, v[40:41], off offset:120
	global_load_dword v87, v[42:43], off offset:128
	global_load_dword v88, v[42:43], off offset:136
	global_load_dword v89, v[42:43], off offset:144
	global_load_dword v90, v[42:43], off offset:152
	global_load_dword v60, v[40:41], off offset:128
	global_load_dword v61, v[40:41], off offset:136
	global_load_dword v62, v[40:41], off offset:144
	global_load_dword v63, v[40:41], off offset:152
	s_waitcnt vmcnt(39)
	v_fma_f32 v5, v8, v5, 0
	s_waitcnt vmcnt(38)
	v_fmac_f32_e32 v5, v9, v64
	s_waitcnt vmcnt(36)
	v_pk_mul_f32 v[8:9], v[8:9], v[44:45]
	s_nop 0
	v_bfe_u32 v44, v8, 16, 1
	s_waitcnt vmcnt(35)
	v_fmac_f32_e32 v5, v10, v65
	v_bfe_u32 v45, v9, 16, 1
	v_add3_u32 v44, v8, v44, s28
	s_waitcnt vmcnt(34)
	v_fmac_f32_e32 v5, v11, v66
	s_waitcnt vmcnt(32)
	v_pk_mul_f32 v[10:11], v[10:11], v[46:47]
	v_add3_u32 v45, v9, v45, s28
	v_and_b32_e32 v44, 0xffff0000, v44
	v_bfe_u32 v46, v10, 16, 1
	v_bfe_u32 v47, v11, 16, 1
	s_waitcnt vmcnt(31)
	v_fmac_f32_e32 v5, v12, v67
	v_and_b32_e32 v45, 0xffff0000, v45
	v_add_f32_e32 v44, 0, v44
	v_add3_u32 v46, v10, v46, s28
	v_add3_u32 v47, v11, v47, s28
	s_waitcnt vmcnt(30)
	v_fmac_f32_e32 v5, v13, v68
	s_waitcnt vmcnt(28)
	v_pk_mul_f32 v[12:13], v[12:13], v[48:49]
	v_add_f32_e32 v44, v44, v45
	v_and_b32_e32 v45, 0xffff0000, v46
	v_and_b32_e32 v46, 0xffff0000, v47
	v_bfe_u32 v47, v12, 16, 1
	v_bfe_u32 v48, v13, 16, 1
	s_waitcnt vmcnt(27)
	v_fmac_f32_e32 v5, v14, v69
	v_add_f32_e32 v44, v44, v45
	v_add3_u32 v45, v12, v47, s28
	v_add3_u32 v47, v13, v48, s28
	s_waitcnt vmcnt(26)
	v_fmac_f32_e32 v5, v15, v70
	s_waitcnt vmcnt(24)
	v_pk_mul_f32 v[14:15], v[14:15], v[50:51]
	v_add_f32_e32 v44, v44, v46
	v_and_b32_e32 v45, 0xffff0000, v45
	v_and_b32_e32 v46, 0xffff0000, v47
	v_bfe_u32 v47, v14, 16, 1
	v_bfe_u32 v48, v15, 16, 1
	s_waitcnt vmcnt(23)
	v_fmac_f32_e32 v5, v16, v71
	v_add_f32_e32 v44, v44, v45
	v_add3_u32 v45, v14, v47, s28
	v_add3_u32 v47, v15, v48, s28
	s_waitcnt vmcnt(22)
	v_fmac_f32_e32 v5, v17, v72
	s_waitcnt vmcnt(20)
	v_pk_mul_f32 v[16:17], v[16:17], v[52:53]
	v_add_f32_e32 v44, v44, v46
	v_and_b32_e32 v45, 0xffff0000, v45
	v_and_b32_e32 v46, 0xffff0000, v47
	v_bfe_u32 v47, v16, 16, 1
	v_add_f32_e32 v44, v44, v45
	v_add3_u32 v45, v16, v47, s28
	v_add_f32_e32 v44, v44, v46
	v_and_b32_e32 v45, 0xffff0000, v45
	v_add_f32_e32 v46, v44, v45
	global_load_dword v64, v[42:43], off offset:160
	global_load_dword v65, v[42:43], off offset:168
	global_load_dword v44, v[40:41], off offset:160
	global_load_dword v45, v[40:41], off offset:168
	v_bfe_u32 v48, v17, 16, 1
	v_add3_u32 v47, v17, v48, s28
	s_waitcnt vmcnt(23)
	v_fmac_f32_e32 v5, v18, v73
	v_and_b32_e32 v47, 0xffff0000, v47
	s_waitcnt vmcnt(22)
	v_fmac_f32_e32 v5, v19, v74
	s_waitcnt vmcnt(20)
	v_pk_mul_f32 v[18:19], v[18:19], v[54:55]
	v_add_f32_e32 v48, v46, v47
	v_bfe_u32 v46, v18, 16, 1
	v_add3_u32 v49, v18, v46, s28
	global_load_dword v54, v[42:43], off offset:176
	global_load_dword v55, v[42:43], off offset:184
	global_load_dword v46, v[40:41], off offset:176
	global_load_dword v47, v[40:41], off offset:184
	v_and_b32_e32 v49, 0xffff0000, v49
	v_add_f32_e32 v48, v48, v49
	v_bfe_u32 v49, v19, 16, 1
	v_add3_u32 v49, v19, v49, s28
	v_and_b32_e32 v49, 0xffff0000, v49
	v_add_f32_e32 v50, v48, v49
	global_load_dword v66, v[42:43], off offset:192
	global_load_dword v67, v[42:43], off offset:200
	global_load_dword v48, v[40:41], off offset:192
	global_load_dword v49, v[40:41], off offset:200
	s_waitcnt vmcnt(27)
	v_fmac_f32_e32 v5, v20, v75
	s_waitcnt vmcnt(26)
	v_fmac_f32_e32 v5, v21, v84
	s_waitcnt vmcnt(22)
; __device__ __forceinline__ unsigned f2bf(float f) { unsigned u = __builtin_bit_cast(unsigned, f); return (u + 0x7fffu + ((u >> 16) & 1u)) >> 16; }
; __device__ __forceinline__ void p0_finish(const TDesc& d, float (&wv)[32], LAS float* scr, int lane) {
;     ...
;     if (d.gsc) {
;         float c1 = 0.f, c2 = 0.f;
; #pragma unroll
;         for (int i = 0; i < 32; ++i) { const int k = k0 + 2 * i + (lane >> 5); c2 += d.bsc[k] * wv[i]; wv[i] *= d.gsc[k]; c1 += bf2f((unsigned short)f2bf(wv[i])); }
;         c1 += __shfl_xor(c1, 32); c2 += __shfl_xor(c2, 32);
;         if (lane < 32) { float* p = d.cvp + (size_t)kb * 2 * 4096 + n0 + lane; p[0] = c1; p[4096] = c2; }
	v_pk_mul_f32 v[20:21], v[20:21], v[56:57]
	v_fmac_f32_e32 v5, v22, v85
	v_bfe_u32 v51, v20, 16, 1
	v_add3_u32 v51, v20, v51, s28
	v_and_b32_e32 v51, 0xffff0000, v51
	v_add_f32_e32 v52, v50, v51
	global_load_dword v56, v[42:43], off offset:208
	global_load_dword v57, v[42:43], off offset:216
	global_load_dword v50, v[40:41], off offset:208
	global_load_dword v51, v[40:41], off offset:216
	v_bfe_u32 v53, v21, 16, 1
	v_add3_u32 v53, v21, v53, s28
	v_and_b32_e32 v53, 0xffff0000, v53
	v_fmac_f32_e32 v5, v23, v86
	s_waitcnt vmcnt(24)
	v_pk_mul_f32 v[22:23], v[22:23], v[58:59]
	v_add_f32_e32 v68, v52, v53
	v_bfe_u32 v58, v22, 16, 1
	global_load_dword v59, v[42:43], off offset:224
	global_load_dword v69, v[42:43], off offset:232
	global_load_dword v52, v[40:41], off offset:224
	global_load_dword v53, v[40:41], off offset:232
	v_add3_u32 v58, v22, v58, s28
	v_and_b32_e32 v58, 0xffff0000, v58
	v_add_f32_e32 v58, v68, v58
	v_bfe_u32 v68, v23, 16, 1
	v_add3_u32 v68, v23, v68, s28
	v_and_b32_e32 v68, 0xffff0000, v68
	v_add_f32_e32 v58, v58, v68
	global_load_dword v68, v[42:43], off offset:240
	global_load_dword v70, v[42:43], off offset:248
	s_nop 0
	global_load_dword v42, v[40:41], off offset:240
	global_load_dword v43, v[40:41], off offset:248
	s_waitcnt vmcnt(31)
	v_fmac_f32_e32 v5, v24, v87
	s_waitcnt vmcnt(30)
	v_fmac_f32_e32 v5, v25, v88
	s_waitcnt vmcnt(26)
	v_pk_mul_f32 v[24:25], v[24:25], v[60:61]
	v_fmac_f32_e32 v5, v26, v89
	v_bfe_u32 v40, v24, 16, 1
	v_add3_u32 v40, v24, v40, s28
	v_bfe_u32 v41, v25, 16, 1
	v_and_b32_e32 v40, 0xffff0000, v40
	v_add3_u32 v41, v25, v41, s28
	v_add_f32_e32 v40, v58, v40
	v_and_b32_e32 v41, 0xffff0000, v41
	v_fmac_f32_e32 v5, v27, v90
	s_waitcnt vmcnt(24)
	v_pk_mul_f32 v[26:27], v[26:27], v[62:63]
	v_add_f32_e32 v40, v40, v41
	v_bfe_u32 v41, v26, 16, 1
	v_add3_u32 v41, v26, v41, s28
	v_and_b32_e32 v41, 0xffff0000, v41
	v_add_f32_e32 v40, v40, v41
	v_bfe_u32 v41, v27, 16, 1
	v_add3_u32 v41, v27, v41, s28
	v_and_b32_e32 v41, 0xffff0000, v41
	v_add_f32_e32 v40, v40, v41
	s_waitcnt vmcnt(23)
	v_fmac_f32_e32 v5, v28, v64
	s_waitcnt vmcnt(22)
	v_fmac_f32_e32 v5, v29, v65
	s_waitcnt vmcnt(20)
	v_pk_mul_f32 v[28:29], v[28:29], v[44:45]
	s_nop 0
	v_bfe_u32 v41, v28, 16, 1
	v_add3_u32 v41, v28, v41, s28
	v_and_b32_e32 v41, 0xffff0000, v41
	v_add_f32_e32 v40, v40, v41
	v_bfe_u32 v41, v29, 16, 1
	v_add3_u32 v41, v29, v41, s28
	s_waitcnt vmcnt(19)
	v_fmac_f32_e32 v5, v30, v54
	v_and_b32_e32 v41, 0xffff0000, v41
	s_waitcnt vmcnt(18)
	v_fmac_f32_e32 v5, v31, v55
	s_waitcnt vmcnt(16)
	v_pk_mul_f32 v[30:31], v[30:31], v[46:47]
	v_add_f32_e32 v40, v40, v41
	v_bfe_u32 v41, v30, 16, 1
	v_add3_u32 v41, v30, v41, s28
	v_and_b32_e32 v41, 0xffff0000, v41
	v_add_f32_e32 v40, v40, v41
	v_bfe_u32 v41, v31, 16, 1
	v_add3_u32 v41, v31, v41, s28
	s_waitcnt vmcnt(15)
	v_fmac_f32_e32 v5, v32, v66
	v_and_b32_e32 v41, 0xffff0000, v41
	s_waitcnt vmcnt(14)
	v_fmac_f32_e32 v5, v33, v67
	s_waitcnt vmcnt(12)
	v_pk_mul_f32 v[32:33], v[32:33], v[48:49]
	v_add_f32_e32 v40, v40, v41
	v_bfe_u32 v41, v32, 16, 1
	v_add3_u32 v41, v32, v41, s28
	v_and_b32_e32 v41, 0xffff0000, v41
	v_add_f32_e32 v40, v40, v41
	v_bfe_u32 v41, v33, 16, 1
	v_add3_u32 v41, v33, v41, s28
	s_waitcnt vmcnt(11)
	v_fmac_f32_e32 v5, v34, v56
	v_and_b32_e32 v41, 0xffff0000, v41
	s_waitcnt vmcnt(10)
	v_fmac_f32_e32 v5, v35, v57
	s_waitcnt vmcnt(8)
	v_pk_mul_f32 v[34:35], v[34:35], v[50:51]
	v_add_f32_e32 v40, v40, v41
	v_bfe_u32 v41, v34, 16, 1
	v_add3_u32 v41, v34, v41, s28
	v_and_b32_e32 v41, 0xffff0000, v41
	v_add_f32_e32 v40, v40, v41
	v_bfe_u32 v41, v35, 16, 1
	v_add3_u32 v41, v35, v41, s28
	s_waitcnt vmcnt(7)
	v_fmac_f32_e32 v5, v36, v59
	v_and_b32_e32 v41, 0xffff0000, v41
	s_waitcnt vmcnt(6)
	v_fmac_f32_e32 v5, v37, v69
	s_waitcnt vmcnt(4)
	v_pk_mul_f32 v[36:37], v[36:37], v[52:53]
	v_add_f32_e32 v40, v40, v41
	v_bfe_u32 v41, v36, 16, 1
	v_add3_u32 v41, v36, v41, s28
	v_and_b32_e32 v41, 0xffff0000, v41
	v_add_f32_e32 v40, v40, v41
	v_bfe_u32 v41, v37, 16, 1
	v_add3_u32 v41, v37, v41, s28
	s_waitcnt vmcnt(3)
	v_fmac_f32_e32 v5, v38, v68
	v_and_b32_e32 v41, 0xffff0000, v41
	s_waitcnt vmcnt(2)
	v_fmac_f32_e32 v5, v39, v70
	s_waitcnt vmcnt(0)
	v_pk_mul_f32 v[38:39], v[38:39], v[42:43]
	v_add_f32_e32 v40, v40, v41
	v_bfe_u32 v41, v38, 16, 1
	v_add3_u32 v41, v38, v41, s28
	v_and_b32_e32 v41, 0xffff0000, v41
	v_add_f32_e32 v40, v40, v41
	v_bfe_u32 v41, v39, 16, 1
	v_add3_u32 v41, v39, v41, s28
	v_and_b32_e32 v41, 0xffff0000, v41
	v_and_b32_e32 v42, 64, v83
	v_add_f32_e32 v40, v40, v41
	v_xor_b32_e32 v41, 32, v83
	v_add_u32_e32 v42, 64, v42
	v_cmp_lt_i32_e32 vcc, v41, v42
	s_nop 1
	v_cndmask_b32_e32 v41, v83, v41, vcc
	v_lshlrev_b32_e32 v42, 2, v41
	ds_bpermute_b32 v41, v42, v40
	ds_bpermute_b32 v42, v42, v5
	s_and_saveexec_b64 s[48:49], s[0:1]
	s_cbranch_execz .LBB0_25
	s_ashr_i32 s45, s44, 31
	s_lshl_b64 s[30:31], s[44:45], 15
	s_add_u32 s33, s46, s30
	s_addc_u32 s36, s47, s31
	s_ashr_i32 s5, s4, 31
	s_lshl_b64 s[30:31], s[4:5], 2
	s_add_u32 s30, s33, s30
	s_addc_u32 s31, s36, s31
	s_waitcnt lgkmcnt(0)
	v_add_f32_e32 v5, v5, v42
	v_add_f32_e32 v42, v40, v41
	v_lshl_add_u64 v[40:41], v[0:1], 2, s[30:31]
	global_store_dword v[40:41], v42, off
	v_add_co_u32_e32 v40, vcc, 0x4000, v40
	s_nop 1
	v_addc_co_u32_e32 v41, vcc, 0, v41, vcc
	global_store_dword v[40:41], v5, off
	s_branch .LBB0_25

;     __device__ __forceinline__ void kvout(int row, int c, int kv, f32x4 v) const {
;         const int head = c >> 6, g = head >> 2, hs = head & 3, dd = c & 63;
;         if (row < MP) {
;             const int b = row >> 11, t = row & 2047;
;             const int win = g == 0 ? 128 : (g == 1 ? 512 : 2048);
;             const int tw = t - (2048 - win);
;             if (tw >= 0) {
;                 const size_t base = g == 0 ? O2 : (g == 1 ? O3 : O4);
;                 *(f32x4*)(out + base + ((((size_t)l * NB + b) * win + tw) * 2 + kv) * 256 + hs * 64 + dd) = v;
;             }
;         } else if (row < MR) {
;             const int r = row - MP;
;             const size_t base = g == 0 ? O6 : (g == 1 ? O7 : O8);
;             *(f32x4*)(out + base + (((size_t)l * MS + r) * 2 + kv) * 256 + hs * 64 + dd) = v;
;         }
.LBB0_248:
	v_lshlrev_b32_e32 v168, 2, v142
	v_mov_b32_e32 v169, v2
	v_lshl_add_u64 v[168:169], v[182:183], 0, v[168:169]
	v_lshlrev_b32_e32 v182, 2, v144
	v_mov_b32_e32 v183, v2
	v_lshl_add_u64 v[168:169], v[168:169], 0, v[182:183]
	global_store_dwordx4 v[168:169], v[136:139], off offset:1024 sc1

;     __device__ __forceinline__ void kvout(int row, int c, int kv, f32x4 v) const {
;         const int head = c >> 6, g = head >> 2, hs = head & 3, dd = c & 63;
;         if (row < MP) {
;             const int b = row >> 11, t = row & 2047;
;             const int win = g == 0 ? 128 : (g == 1 ? 512 : 2048);
;             const int tw = t - (2048 - win);
;             if (tw >= 0) {
;                 const size_t base = g == 0 ? O2 : (g == 1 ? O3 : O4);
;                 *(f32x4*)(out + base + ((((size_t)l * NB + b) * win + tw) * 2 + kv) * 256 + hs * 64 + dd) = v;
;             }
;         } else if (row < MR) {
;             const int r = row - MP;
;             const size_t base = g == 0 ? O6 : (g == 1 ? O7 : O8);
;             *(f32x4*)(out + base + (((size_t)l * MS + r) * 2 + kv) * 256 + hs * 64 + dd) = v;
;         }
.LBB0_260:
	v_lshlrev_b32_e32 v168, 2, v142
	v_mov_b32_e32 v169, v2
	v_lshl_add_u64 v[168:169], v[182:183], 0, v[168:169]
	v_lshlrev_b32_e32 v182, 2, v144
	v_mov_b32_e32 v183, v2
	v_lshl_add_u64 v[168:169], v[168:169], 0, v[182:183]
	global_store_dwordx4 v[168:169], v[136:139], off sc1

;     __device__ __forceinline__ void kvout(int row, int c, int kv, f32x4 v) const {
;         const int head = c >> 6, g = head >> 2, hs = head & 3, dd = c & 63;
;         if (row < MP) {
;             const int b = row >> 11, t = row & 2047;
;             const int win = g == 0 ? 128 : (g == 1 ? 512 : 2048);
;             const int tw = t - (2048 - win);
;             if (tw >= 0) {
;                 const size_t base = g == 0 ? O2 : (g == 1 ? O3 : O4);
;                 *(f32x4*)(out + base + ((((size_t)l * NB + b) * win + tw) * 2 + kv) * 256 + hs * 64 + dd) = v;
;             }
;         } else if (row < MR) {
;             const int r = row - MP;
;             const size_t base = g == 0 ? O6 : (g == 1 ? O7 : O8);
;             *(f32x4*)(out + base + (((size_t)l * MS + r) * 2 + kv) * 256 + hs * 64 + dd) = v;
;         }
.LBB0_274:
	v_lshlrev_b32_e32 v138, 2, v142
	v_mov_b32_e32 v139, v2
	v_lshl_add_u64 v[136:137], v[136:137], 0, v[138:139]
	v_lshlrev_b32_e32 v138, 2, v144
	v_lshl_add_u64 v[136:137], v[136:137], 0, v[138:139]
	global_store_dwordx4 v[136:137], v[132:135], off offset:1024 sc1

;     __device__ __forceinline__ void kvout(int row, int c, int kv, f32x4 v) const {
;         const int head = c >> 6, g = head >> 2, hs = head & 3, dd = c & 63;
;         if (row < MP) {
;             const int b = row >> 11, t = row & 2047;
;             const int win = g == 0 ? 128 : (g == 1 ? 512 : 2048);
;             const int tw = t - (2048 - win);
;             if (tw >= 0) {
;                 const size_t base = g == 0 ? O2 : (g == 1 ? O3 : O4);
;                 *(f32x4*)(out + base + ((((size_t)l * NB + b) * win + tw) * 2 + kv) * 256 + hs * 64 + dd) = v;
;             }
;         } else if (row < MR) {
;             const int r = row - MP;
;             const size_t base = g == 0 ? O6 : (g == 1 ? O7 : O8);
;             *(f32x4*)(out + base + (((size_t)l * MS + r) * 2 + kv) * 256 + hs * 64 + dd) = v;
;         }
.LBB0_286:
	v_lshlrev_b32_e32 v138, 2, v142
	v_mov_b32_e32 v139, v2
	v_lshl_add_u64 v[136:137], v[136:137], 0, v[138:139]
	v_lshlrev_b32_e32 v138, 2, v144
	v_lshl_add_u64 v[136:137], v[136:137], 0, v[138:139]
	global_store_dwordx4 v[136:137], v[132:135], off sc1

;     __device__ __forceinline__ void kvout(int row, int c, int kv, f32x4 v) const {
;         const int head = c >> 6, g = head >> 2, hs = head & 3, dd = c & 63;
;         if (row < MP) {
;             const int b = row >> 11, t = row & 2047;
;             const int win = g == 0 ? 128 : (g == 1 ? 512 : 2048);
;             const int tw = t - (2048 - win);
;             if (tw >= 0) {
;                 const size_t base = g == 0 ? O2 : (g == 1 ? O3 : O4);
;                 *(f32x4*)(out + base + ((((size_t)l * NB + b) * win + tw) * 2 + kv) * 256 + hs * 64 + dd) = v;
;             }
;         } else if (row < MR) {
;             const int r = row - MP;
;             const size_t base = g == 0 ? O6 : (g == 1 ? O7 : O8);
;             *(f32x4*)(out + base + (((size_t)l * MS + r) * 2 + kv) * 256 + hs * 64 + dd) = v;
;         }
.LBB0_300:
	v_lshlrev_b32_e32 v134, 2, v142
	v_mov_b32_e32 v135, v2
	v_lshl_add_u64 v[132:133], v[132:133], 0, v[134:135]
	v_lshlrev_b32_e32 v134, 2, v144
	v_lshl_add_u64 v[132:133], v[132:133], 0, v[134:135]
	global_store_dwordx4 v[132:133], v[128:131], off offset:1024 sc1

;     __device__ __forceinline__ void kvout(int row, int c, int kv, f32x4 v) const {
;         const int head = c >> 6, g = head >> 2, hs = head & 3, dd = c & 63;
;         if (row < MP) {
;             const int b = row >> 11, t = row & 2047;
;             const int win = g == 0 ? 128 : (g == 1 ? 512 : 2048);
;             const int tw = t - (2048 - win);
;             if (tw >= 0) {
;                 const size_t base = g == 0 ? O2 : (g == 1 ? O3 : O4);
;                 *(f32x4*)(out + base + ((((size_t)l * NB + b) * win + tw) * 2 + kv) * 256 + hs * 64 + dd) = v;
;             }
;         } else if (row < MR) {
;             const int r = row - MP;
;             const size_t base = g == 0 ? O6 : (g == 1 ? O7 : O8);
;             *(f32x4*)(out + base + (((size_t)l * MS + r) * 2 + kv) * 256 + hs * 64 + dd) = v;
;         }
.LBB0_312:
	v_lshlrev_b32_e32 v134, 2, v142
	v_mov_b32_e32 v135, v2
	v_lshl_add_u64 v[132:133], v[132:133], 0, v[134:135]
	v_lshlrev_b32_e32 v134, 2, v144
	v_lshl_add_u64 v[132:133], v[132:133], 0, v[134:135]
	global_store_dwordx4 v[132:133], v[128:131], off sc1

;     __device__ __forceinline__ void kvout(int row, int c, int kv, f32x4 v) const {
;         const int head = c >> 6, g = head >> 2, hs = head & 3, dd = c & 63;
;         if (row < MP) {
;             const int b = row >> 11, t = row & 2047;
;             const int win = g == 0 ? 128 : (g == 1 ? 512 : 2048);
;             const int tw = t - (2048 - win);
;             if (tw >= 0) {
;                 const size_t base = g == 0 ? O2 : (g == 1 ? O3 : O4);
;                 *(f32x4*)(out + base + ((((size_t)l * NB + b) * win + tw) * 2 + kv) * 256 + hs * 64 + dd) = v;
;             }
;         } else if (row < MR) {
;             const int r = row - MP;
;             const size_t base = g == 0 ? O6 : (g == 1 ? O7 : O8);
;             *(f32x4*)(out + base + (((size_t)l * MS + r) * 2 + kv) * 256 + hs * 64 + dd) = v;
;         }
.LBB0_326:
	v_lshlrev_b32_e32 v130, 2, v142
	v_mov_b32_e32 v131, v2
	v_lshl_add_u64 v[128:129], v[128:129], 0, v[130:131]
	v_lshlrev_b32_e32 v130, 2, v144
	v_lshl_add_u64 v[128:129], v[128:129], 0, v[130:131]
	global_store_dwordx4 v[128:129], v[124:127], off offset:1024 sc1

;     __device__ __forceinline__ void kvout(int row, int c, int kv, f32x4 v) const {
;         const int head = c >> 6, g = head >> 2, hs = head & 3, dd = c & 63;
;         if (row < MP) {
;             const int b = row >> 11, t = row & 2047;
;             const int win = g == 0 ? 128 : (g == 1 ? 512 : 2048);
;             const int tw = t - (2048 - win);
;             if (tw >= 0) {
;                 const size_t base = g == 0 ? O2 : (g == 1 ? O3 : O4);
;                 *(f32x4*)(out + base + ((((size_t)l * NB + b) * win + tw) * 2 + kv) * 256 + hs * 64 + dd) = v;
;             }
;         } else if (row < MR) {
;             const int r = row - MP;
;             const size_t base = g == 0 ? O6 : (g == 1 ? O7 : O8);
;             *(f32x4*)(out + base + (((size_t)l * MS + r) * 2 + kv) * 256 + hs * 64 + dd) = v;
;         }
.LBB0_338:
	v_lshlrev_b32_e32 v130, 2, v142
	v_mov_b32_e32 v131, v2
	v_lshl_add_u64 v[128:129], v[128:129], 0, v[130:131]
	v_lshlrev_b32_e32 v130, 2, v144
	v_lshl_add_u64 v[128:129], v[128:129], 0, v[130:131]
	global_store_dwordx4 v[128:129], v[124:127], off sc1

;     __device__ __forceinline__ void kvout(int row, int c, int kv, f32x4 v) const {
;         const int head = c >> 6, g = head >> 2, hs = head & 3, dd = c & 63;
;         if (row < MP) {
;             const int b = row >> 11, t = row & 2047;
;             const int win = g == 0 ? 128 : (g == 1 ? 512 : 2048);
;             const int tw = t - (2048 - win);
;             if (tw >= 0) {
;                 const size_t base = g == 0 ? O2 : (g == 1 ? O3 : O4);
;                 *(f32x4*)(out + base + ((((size_t)l * NB + b) * win + tw) * 2 + kv) * 256 + hs * 64 + dd) = v;
;             }
;         } else if (row < MR) {
;             const int r = row - MP;
;             const size_t base = g == 0 ? O6 : (g == 1 ? O7 : O8);
;             *(f32x4*)(out + base + (((size_t)l * MS + r) * 2 + kv) * 256 + hs * 64 + dd) = v;
;         }
.LBB0_352:
	v_lshlrev_b32_e32 v126, 2, v142
	v_mov_b32_e32 v127, v2
	v_lshl_add_u64 v[124:125], v[124:125], 0, v[126:127]
	v_lshlrev_b32_e32 v126, 2, v144
	v_lshl_add_u64 v[124:125], v[124:125], 0, v[126:127]
	global_store_dwordx4 v[124:125], v[112:115], off offset:1024 sc1

;     __device__ __forceinline__ void kvout(int row, int c, int kv, f32x4 v) const {
;         const int head = c >> 6, g = head >> 2, hs = head & 3, dd = c & 63;
;         if (row < MP) {
;             const int b = row >> 11, t = row & 2047;
;             const int win = g == 0 ? 128 : (g == 1 ? 512 : 2048);
;             const int tw = t - (2048 - win);
;             if (tw >= 0) {
;                 const size_t base = g == 0 ? O2 : (g == 1 ? O3 : O4);
;                 *(f32x4*)(out + base + ((((size_t)l * NB + b) * win + tw) * 2 + kv) * 256 + hs * 64 + dd) = v;
;             }
;         } else if (row < MR) {
;             const int r = row - MP;
;             const size_t base = g == 0 ? O6 : (g == 1 ? O7 : O8);
;             *(f32x4*)(out + base + (((size_t)l * MS + r) * 2 + kv) * 256 + hs * 64 + dd) = v;
;         }
.LBB0_364:
	v_lshlrev_b32_e32 v126, 2, v142
	v_mov_b32_e32 v127, v2
	v_lshl_add_u64 v[124:125], v[124:125], 0, v[126:127]
	v_lshlrev_b32_e32 v126, 2, v144
	v_lshl_add_u64 v[124:125], v[124:125], 0, v[126:127]
	global_store_dwordx4 v[124:125], v[112:115], off sc1

;     __device__ __forceinline__ void kvout(int row, int c, int kv, f32x4 v) const {
;         const int head = c >> 6, g = head >> 2, hs = head & 3, dd = c & 63;
;         if (row < MP) {
;             const int b = row >> 11, t = row & 2047;
;             const int win = g == 0 ? 128 : (g == 1 ? 512 : 2048);
;             const int tw = t - (2048 - win);
;             if (tw >= 0) {
;                 const size_t base = g == 0 ? O2 : (g == 1 ? O3 : O4);
;                 *(f32x4*)(out + base + ((((size_t)l * NB + b) * win + tw) * 2 + kv) * 256 + hs * 64 + dd) = v;
;             }
;         } else if (row < MR) {
;             const int r = row - MP;
;             const size_t base = g == 0 ? O6 : (g == 1 ? O7 : O8);
;             *(f32x4*)(out + base + (((size_t)l * MS + r) * 2 + kv) * 256 + hs * 64 + dd) = v;
;         }
.LBB0_378:
	v_lshlrev_b32_e32 v114, 2, v142
	v_mov_b32_e32 v115, v2
	v_lshl_add_u64 v[112:113], v[112:113], 0, v[114:115]
	v_lshlrev_b32_e32 v114, 2, v144
	v_lshl_add_u64 v[112:113], v[112:113], 0, v[114:115]
	global_store_dwordx4 v[112:113], v[108:111], off offset:1024 sc1

;     __device__ __forceinline__ void kvout(int row, int c, int kv, f32x4 v) const {
;         const int head = c >> 6, g = head >> 2, hs = head & 3, dd = c & 63;
;         if (row < MP) {
;             const int b = row >> 11, t = row & 2047;
;             const int win = g == 0 ? 128 : (g == 1 ? 512 : 2048);
;             const int tw = t - (2048 - win);
;             if (tw >= 0) {
;                 const size_t base = g == 0 ? O2 : (g == 1 ? O3 : O4);
;                 *(f32x4*)(out + base + ((((size_t)l * NB + b) * win + tw) * 2 + kv) * 256 + hs * 64 + dd) = v;
;             }
;         } else if (row < MR) {
;             const int r = row - MP;
;             const size_t base = g == 0 ? O6 : (g == 1 ? O7 : O8);
;             *(f32x4*)(out + base + (((size_t)l * MS + r) * 2 + kv) * 256 + hs * 64 + dd) = v;
;         }
.LBB0_390:
	v_lshlrev_b32_e32 v114, 2, v142
	v_mov_b32_e32 v115, v2
	v_lshl_add_u64 v[112:113], v[112:113], 0, v[114:115]
	v_lshlrev_b32_e32 v114, 2, v144
	v_lshl_add_u64 v[112:113], v[112:113], 0, v[114:115]
	global_store_dwordx4 v[112:113], v[108:111], off sc1

;     __device__ __forceinline__ void kvout(int row, int c, int kv, f32x4 v) const {
;         const int head = c >> 6, g = head >> 2, hs = head & 3, dd = c & 63;
;         if (row < MP) {
;             const int b = row >> 11, t = row & 2047;
;             const int win = g == 0 ? 128 : (g == 1 ? 512 : 2048);
;             const int tw = t - (2048 - win);
;             if (tw >= 0) {
;                 const size_t base = g == 0 ? O2 : (g == 1 ? O3 : O4);
;                 *(f32x4*)(out + base + ((((size_t)l * NB + b) * win + tw) * 2 + kv) * 256 + hs * 64 + dd) = v;
;             }
;         } else if (row < MR) {
;             const int r = row - MP;
;             const size_t base = g == 0 ? O6 : (g == 1 ? O7 : O8);
;             *(f32x4*)(out + base + (((size_t)l * MS + r) * 2 + kv) * 256 + hs * 64 + dd) = v;
;         }
.LBB0_404:
	v_lshlrev_b32_e32 v110, 2, v142
	v_mov_b32_e32 v111, v2
	v_lshl_add_u64 v[108:109], v[108:109], 0, v[110:111]
	v_lshlrev_b32_e32 v110, 2, v144
	v_lshl_add_u64 v[108:109], v[108:109], 0, v[110:111]
	global_store_dwordx4 v[108:109], v[104:107], off offset:1024 sc1

;     __device__ __forceinline__ void kvout(int row, int c, int kv, f32x4 v) const {
;         const int head = c >> 6, g = head >> 2, hs = head & 3, dd = c & 63;
;         if (row < MP) {
;             const int b = row >> 11, t = row & 2047;
;             const int win = g == 0 ? 128 : (g == 1 ? 512 : 2048);
;             const int tw = t - (2048 - win);
;             if (tw >= 0) {
;                 const size_t base = g == 0 ? O2 : (g == 1 ? O3 : O4);
;                 *(f32x4*)(out + base + ((((size_t)l * NB + b) * win + tw) * 2 + kv) * 256 + hs * 64 + dd) = v;
;             }
;         } else if (row < MR) {
;             const int r = row - MP;
;             const size_t base = g == 0 ? O6 : (g == 1 ? O7 : O8);
;             *(f32x4*)(out + base + (((size_t)l * MS + r) * 2 + kv) * 256 + hs * 64 + dd) = v;
;         }
.LBB0_416:
	v_lshlrev_b32_e32 v110, 2, v142
	v_mov_b32_e32 v111, v2
	v_lshl_add_u64 v[108:109], v[108:109], 0, v[110:111]
	v_lshlrev_b32_e32 v110, 2, v144
	v_lshl_add_u64 v[108:109], v[108:109], 0, v[110:111]
	global_store_dwordx4 v[108:109], v[104:107], off sc1

;     __device__ __forceinline__ void kvout(int row, int c, int kv, f32x4 v) const {
;         const int head = c >> 6, g = head >> 2, hs = head & 3, dd = c & 63;
;         if (row < MP) {
;             const int b = row >> 11, t = row & 2047;
;             const int win = g == 0 ? 128 : (g == 1 ? 512 : 2048);
;             const int tw = t - (2048 - win);
;             if (tw >= 0) {
;                 const size_t base = g == 0 ? O2 : (g == 1 ? O3 : O4);
;                 *(f32x4*)(out + base + ((((size_t)l * NB + b) * win + tw) * 2 + kv) * 256 + hs * 64 + dd) = v;
;             }
;         } else if (row < MR) {
;             const int r = row - MP;
;             const size_t base = g == 0 ? O6 : (g == 1 ? O7 : O8);
;             *(f32x4*)(out + base + (((size_t)l * MS + r) * 2 + kv) * 256 + hs * 64 + dd) = v;
;         }
.LBB0_430:
	v_lshlrev_b32_e32 v106, 2, v142
	v_mov_b32_e32 v107, v2
	v_lshl_add_u64 v[104:105], v[104:105], 0, v[106:107]
	v_lshlrev_b32_e32 v106, 2, v144
	v_lshl_add_u64 v[104:105], v[104:105], 0, v[106:107]
	global_store_dwordx4 v[104:105], v[100:103], off offset:1024 sc1

;     __device__ __forceinline__ void kvout(int row, int c, int kv, f32x4 v) const {
;         const int head = c >> 6, g = head >> 2, hs = head & 3, dd = c & 63;
;         if (row < MP) {
;             const int b = row >> 11, t = row & 2047;
;             const int win = g == 0 ? 128 : (g == 1 ? 512 : 2048);
;             const int tw = t - (2048 - win);
;             if (tw >= 0) {
;                 const size_t base = g == 0 ? O2 : (g == 1 ? O3 : O4);
;                 *(f32x4*)(out + base + ((((size_t)l * NB + b) * win + tw) * 2 + kv) * 256 + hs * 64 + dd) = v;
;             }
;         } else if (row < MR) {
;             const int r = row - MP;
;             const size_t base = g == 0 ? O6 : (g == 1 ? O7 : O8);
;             *(f32x4*)(out + base + (((size_t)l * MS + r) * 2 + kv) * 256 + hs * 64 + dd) = v;
;         }
.LBB0_442:
	v_lshlrev_b32_e32 v106, 2, v142
	v_mov_b32_e32 v107, v2
	v_lshl_add_u64 v[104:105], v[104:105], 0, v[106:107]
	v_lshlrev_b32_e32 v106, 2, v144
	v_lshl_add_u64 v[104:105], v[104:105], 0, v[106:107]
	global_store_dwordx4 v[104:105], v[100:103], off sc1

;     __device__ __forceinline__ void kvout(int row, int c, int kv, f32x4 v) const {
;         const int head = c >> 6, g = head >> 2, hs = head & 3, dd = c & 63;
;         if (row < MP) {
;             const int b = row >> 11, t = row & 2047;
;             const int win = g == 0 ? 128 : (g == 1 ? 512 : 2048);
;             const int tw = t - (2048 - win);
;             if (tw >= 0) {
;                 const size_t base = g == 0 ? O2 : (g == 1 ? O3 : O4);
;                 *(f32x4*)(out + base + ((((size_t)l * NB + b) * win + tw) * 2 + kv) * 256 + hs * 64 + dd) = v;
;             }
;         } else if (row < MR) {
;             const int r = row - MP;
;             const size_t base = g == 0 ? O6 : (g == 1 ? O7 : O8);
;             *(f32x4*)(out + base + (((size_t)l * MS + r) * 2 + kv) * 256 + hs * 64 + dd) = v;
;         }
.LBB0_458:
	v_lshlrev_b32_e32 v168, 2, v111
	v_mov_b32_e32 v169, v2
	v_lshl_add_u64 v[168:169], v[212:213], 0, v[168:169]
	v_lshlrev_b32_e32 v212, 2, v3
	v_mov_b32_e32 v213, v2
	v_lshl_add_u64 v[168:169], v[168:169], 0, v[212:213]
	global_store_dwordx4 v[168:169], v[96:99], off offset:1024 sc1

;     __device__ __forceinline__ void kvout(int row, int c, int kv, f32x4 v) const {
;         const int head = c >> 6, g = head >> 2, hs = head & 3, dd = c & 63;
;         if (row < MP) {
;             const int b = row >> 11, t = row & 2047;
;             const int win = g == 0 ? 128 : (g == 1 ? 512 : 2048);
;             const int tw = t - (2048 - win);
;             if (tw >= 0) {
;                 const size_t base = g == 0 ? O2 : (g == 1 ? O3 : O4);
;                 *(f32x4*)(out + base + ((((size_t)l * NB + b) * win + tw) * 2 + kv) * 256 + hs * 64 + dd) = v;
;             }
;         } else if (row < MR) {
;             const int r = row - MP;
;             const size_t base = g == 0 ? O6 : (g == 1 ? O7 : O8);
;             *(f32x4*)(out + base + (((size_t)l * MS + r) * 2 + kv) * 256 + hs * 64 + dd) = v;
;         }
.LBB0_470:
	v_lshlrev_b32_e32 v168, 2, v111
	v_mov_b32_e32 v169, v2
	v_lshl_add_u64 v[168:169], v[212:213], 0, v[168:169]
	v_lshlrev_b32_e32 v212, 2, v3
	v_mov_b32_e32 v213, v2
	v_lshl_add_u64 v[168:169], v[168:169], 0, v[212:213]
	global_store_dwordx4 v[168:169], v[96:99], off sc1

;     __device__ __forceinline__ void kvout(int row, int c, int kv, f32x4 v) const {
;         const int head = c >> 6, g = head >> 2, hs = head & 3, dd = c & 63;
;         if (row < MP) {
;             const int b = row >> 11, t = row & 2047;
;             const int win = g == 0 ? 128 : (g == 1 ? 512 : 2048);
;             const int tw = t - (2048 - win);
;             if (tw >= 0) {
;                 const size_t base = g == 0 ? O2 : (g == 1 ? O3 : O4);
;                 *(f32x4*)(out + base + ((((size_t)l * NB + b) * win + tw) * 2 + kv) * 256 + hs * 64 + dd) = v;
;             }
;         } else if (row < MR) {
;             const int r = row - MP;
;             const size_t base = g == 0 ? O6 : (g == 1 ? O7 : O8);
;             *(f32x4*)(out + base + (((size_t)l * MS + r) * 2 + kv) * 256 + hs * 64 + dd) = v;
;         }
.LBB0_484:
	v_lshlrev_b32_e32 v168, 2, v111
	v_mov_b32_e32 v169, v2
	v_lshl_add_u64 v[98:99], v[98:99], 0, v[168:169]
	v_lshlrev_b32_e32 v168, 2, v3
	v_lshl_add_u64 v[98:99], v[98:99], 0, v[168:169]
	global_store_dwordx4 v[98:99], v[92:95], off offset:1024 sc1

;     __device__ __forceinline__ void kvout(int row, int c, int kv, f32x4 v) const {
;         const int head = c >> 6, g = head >> 2, hs = head & 3, dd = c & 63;
;         if (row < MP) {
;             const int b = row >> 11, t = row & 2047;
;             const int win = g == 0 ? 128 : (g == 1 ? 512 : 2048);
;             const int tw = t - (2048 - win);
;             if (tw >= 0) {
;                 const size_t base = g == 0 ? O2 : (g == 1 ? O3 : O4);
;                 *(f32x4*)(out + base + ((((size_t)l * NB + b) * win + tw) * 2 + kv) * 256 + hs * 64 + dd) = v;
;             }
;         } else if (row < MR) {
;             const int r = row - MP;
;             const size_t base = g == 0 ? O6 : (g == 1 ? O7 : O8);
;             *(f32x4*)(out + base + (((size_t)l * MS + r) * 2 + kv) * 256 + hs * 64 + dd) = v;
;         }
.LBB0_496:
	v_lshlrev_b32_e32 v168, 2, v111
	v_mov_b32_e32 v169, v2
	v_lshl_add_u64 v[98:99], v[98:99], 0, v[168:169]
	v_lshlrev_b32_e32 v168, 2, v3
	v_lshl_add_u64 v[98:99], v[98:99], 0, v[168:169]
	global_store_dwordx4 v[98:99], v[92:95], off sc1

;     __device__ __forceinline__ void kvout(int row, int c, int kv, f32x4 v) const {
;         const int head = c >> 6, g = head >> 2, hs = head & 3, dd = c & 63;
;         if (row < MP) {
;             const int b = row >> 11, t = row & 2047;
;             const int win = g == 0 ? 128 : (g == 1 ? 512 : 2048);
;             const int tw = t - (2048 - win);
;             if (tw >= 0) {
;                 const size_t base = g == 0 ? O2 : (g == 1 ? O3 : O4);
;                 *(f32x4*)(out + base + ((((size_t)l * NB + b) * win + tw) * 2 + kv) * 256 + hs * 64 + dd) = v;
;             }
;         } else if (row < MR) {
;             const int r = row - MP;
;             const size_t base = g == 0 ? O6 : (g == 1 ? O7 : O8);
;             *(f32x4*)(out + base + (((size_t)l * MS + r) * 2 + kv) * 256 + hs * 64 + dd) = v;
;         }
.LBB0_510:
	v_lshlrev_b32_e32 v98, 2, v111
	v_mov_b32_e32 v99, v2
	v_lshl_add_u64 v[94:95], v[94:95], 0, v[98:99]
	v_lshlrev_b32_e32 v98, 2, v3
	v_lshl_add_u64 v[94:95], v[94:95], 0, v[98:99]
	global_store_dwordx4 v[94:95], v[88:91], off offset:1024 sc1

;     __device__ __forceinline__ void kvout(int row, int c, int kv, f32x4 v) const {
;         const int head = c >> 6, g = head >> 2, hs = head & 3, dd = c & 63;
;         if (row < MP) {
;             const int b = row >> 11, t = row & 2047;
;             const int win = g == 0 ? 128 : (g == 1 ? 512 : 2048);
;             const int tw = t - (2048 - win);
;             if (tw >= 0) {
;                 const size_t base = g == 0 ? O2 : (g == 1 ? O3 : O4);
;                 *(f32x4*)(out + base + ((((size_t)l * NB + b) * win + tw) * 2 + kv) * 256 + hs * 64 + dd) = v;
;             }
;         } else if (row < MR) {
;             const int r = row - MP;
;             const size_t base = g == 0 ? O6 : (g == 1 ? O7 : O8);
;             *(f32x4*)(out + base + (((size_t)l * MS + r) * 2 + kv) * 256 + hs * 64 + dd) = v;
;         }
.LBB0_522:
	v_lshlrev_b32_e32 v98, 2, v111
	v_mov_b32_e32 v99, v2
	v_lshl_add_u64 v[94:95], v[94:95], 0, v[98:99]
	v_lshlrev_b32_e32 v98, 2, v3
	v_lshl_add_u64 v[94:95], v[94:95], 0, v[98:99]
	global_store_dwordx4 v[94:95], v[88:91], off sc1

;     __device__ __forceinline__ void kvout(int row, int c, int kv, f32x4 v) const {
;         const int head = c >> 6, g = head >> 2, hs = head & 3, dd = c & 63;
;         if (row < MP) {
;             const int b = row >> 11, t = row & 2047;
;             const int win = g == 0 ? 128 : (g == 1 ? 512 : 2048);
;             const int tw = t - (2048 - win);
;             if (tw >= 0) {
;                 const size_t base = g == 0 ? O2 : (g == 1 ? O3 : O4);
;                 *(f32x4*)(out + base + ((((size_t)l * NB + b) * win + tw) * 2 + kv) * 256 + hs * 64 + dd) = v;
;             }
;         } else if (row < MR) {
;             const int r = row - MP;
;             const size_t base = g == 0 ? O6 : (g == 1 ? O7 : O8);
;             *(f32x4*)(out + base + (((size_t)l * MS + r) * 2 + kv) * 256 + hs * 64 + dd) = v;
;         }
.LBB0_536:
	v_lshlrev_b32_e32 v94, 2, v111
	v_mov_b32_e32 v95, v2
	v_lshl_add_u64 v[90:91], v[90:91], 0, v[94:95]
	v_lshlrev_b32_e32 v94, 2, v3
	v_lshl_add_u64 v[90:91], v[90:91], 0, v[94:95]
	global_store_dwordx4 v[90:91], v[84:87], off offset:1024 sc1

;     __device__ __forceinline__ void kvout(int row, int c, int kv, f32x4 v) const {
;         const int head = c >> 6, g = head >> 2, hs = head & 3, dd = c & 63;
;         if (row < MP) {
;             const int b = row >> 11, t = row & 2047;
;             const int win = g == 0 ? 128 : (g == 1 ? 512 : 2048);
;             const int tw = t - (2048 - win);
;             if (tw >= 0) {
;                 const size_t base = g == 0 ? O2 : (g == 1 ? O3 : O4);
;                 *(f32x4*)(out + base + ((((size_t)l * NB + b) * win + tw) * 2 + kv) * 256 + hs * 64 + dd) = v;
;             }
;         } else if (row < MR) {
;             const int r = row - MP;
;             const size_t base = g == 0 ? O6 : (g == 1 ? O7 : O8);
;             *(f32x4*)(out + base + (((size_t)l * MS + r) * 2 + kv) * 256 + hs * 64 + dd) = v;
;         }
.LBB0_548:
	v_lshlrev_b32_e32 v94, 2, v111
	v_mov_b32_e32 v95, v2
	v_lshl_add_u64 v[90:91], v[90:91], 0, v[94:95]
	v_lshlrev_b32_e32 v94, 2, v3
	v_lshl_add_u64 v[90:91], v[90:91], 0, v[94:95]
	global_store_dwordx4 v[90:91], v[84:87], off sc1

;     __device__ __forceinline__ void kvout(int row, int c, int kv, f32x4 v) const {
;         const int head = c >> 6, g = head >> 2, hs = head & 3, dd = c & 63;
;         if (row < MP) {
;             const int b = row >> 11, t = row & 2047;
;             const int win = g == 0 ? 128 : (g == 1 ? 512 : 2048);
;             const int tw = t - (2048 - win);
;             if (tw >= 0) {
;                 const size_t base = g == 0 ? O2 : (g == 1 ? O3 : O4);
;                 *(f32x4*)(out + base + ((((size_t)l * NB + b) * win + tw) * 2 + kv) * 256 + hs * 64 + dd) = v;
;             }
;         } else if (row < MR) {
;             const int r = row - MP;
;             const size_t base = g == 0 ? O6 : (g == 1 ? O7 : O8);
;             *(f32x4*)(out + base + (((size_t)l * MS + r) * 2 + kv) * 256 + hs * 64 + dd) = v;
;         }
.LBB0_562:
	v_lshlrev_b32_e32 v90, 2, v111
	v_mov_b32_e32 v91, v2
	v_lshl_add_u64 v[86:87], v[86:87], 0, v[90:91]
	v_lshlrev_b32_e32 v90, 2, v3
	v_lshl_add_u64 v[86:87], v[86:87], 0, v[90:91]
	global_store_dwordx4 v[86:87], v[80:83], off offset:1024 sc1

;     __device__ __forceinline__ void kvout(int row, int c, int kv, f32x4 v) const {
;         const int head = c >> 6, g = head >> 2, hs = head & 3, dd = c & 63;
;         if (row < MP) {
;             const int b = row >> 11, t = row & 2047;
;             const int win = g == 0 ? 128 : (g == 1 ? 512 : 2048);
;             const int tw = t - (2048 - win);
;             if (tw >= 0) {
;                 const size_t base = g == 0 ? O2 : (g == 1 ? O3 : O4);
;                 *(f32x4*)(out + base + ((((size_t)l * NB + b) * win + tw) * 2 + kv) * 256 + hs * 64 + dd) = v;
;             }
;         } else if (row < MR) {
;             const int r = row - MP;
;             const size_t base = g == 0 ? O6 : (g == 1 ? O7 : O8);
;             *(f32x4*)(out + base + (((size_t)l * MS + r) * 2 + kv) * 256 + hs * 64 + dd) = v;
;         }
.LBB0_574:
	v_lshlrev_b32_e32 v90, 2, v111
	v_mov_b32_e32 v91, v2
	v_lshl_add_u64 v[86:87], v[86:87], 0, v[90:91]
	v_lshlrev_b32_e32 v90, 2, v3
	v_lshl_add_u64 v[86:87], v[86:87], 0, v[90:91]
	global_store_dwordx4 v[86:87], v[80:83], off sc1

;     __device__ __forceinline__ void kvout(int row, int c, int kv, f32x4 v) const {
;         const int head = c >> 6, g = head >> 2, hs = head & 3, dd = c & 63;
;         if (row < MP) {
;             const int b = row >> 11, t = row & 2047;
;             const int win = g == 0 ? 128 : (g == 1 ? 512 : 2048);
;             const int tw = t - (2048 - win);
;             if (tw >= 0) {
;                 const size_t base = g == 0 ? O2 : (g == 1 ? O3 : O4);
;                 *(f32x4*)(out + base + ((((size_t)l * NB + b) * win + tw) * 2 + kv) * 256 + hs * 64 + dd) = v;
;             }
;         } else if (row < MR) {
;             const int r = row - MP;
;             const size_t base = g == 0 ? O6 : (g == 1 ? O7 : O8);
;             *(f32x4*)(out + base + (((size_t)l * MS + r) * 2 + kv) * 256 + hs * 64 + dd) = v;
;         }
.LBB0_588:
	v_lshlrev_b32_e32 v86, 2, v111
	v_mov_b32_e32 v87, v2
	v_lshl_add_u64 v[82:83], v[82:83], 0, v[86:87]
	v_lshlrev_b32_e32 v86, 2, v3
	v_lshl_add_u64 v[82:83], v[82:83], 0, v[86:87]
	global_store_dwordx4 v[82:83], v[76:79], off offset:1024 sc1

;     __device__ __forceinline__ void kvout(int row, int c, int kv, f32x4 v) const {
;         const int head = c >> 6, g = head >> 2, hs = head & 3, dd = c & 63;
;         if (row < MP) {
;             const int b = row >> 11, t = row & 2047;
;             const int win = g == 0 ? 128 : (g == 1 ? 512 : 2048);
;             const int tw = t - (2048 - win);
;             if (tw >= 0) {
;                 const size_t base = g == 0 ? O2 : (g == 1 ? O3 : O4);
;                 *(f32x4*)(out + base + ((((size_t)l * NB + b) * win + tw) * 2 + kv) * 256 + hs * 64 + dd) = v;
;             }
;         } else if (row < MR) {
;             const int r = row - MP;
;             const size_t base = g == 0 ? O6 : (g == 1 ? O7 : O8);
;             *(f32x4*)(out + base + (((size_t)l * MS + r) * 2 + kv) * 256 + hs * 64 + dd) = v;
;         }
.LBB0_600:
	v_lshlrev_b32_e32 v86, 2, v111
	v_mov_b32_e32 v87, v2
	v_lshl_add_u64 v[82:83], v[82:83], 0, v[86:87]
	v_lshlrev_b32_e32 v86, 2, v3
	v_lshl_add_u64 v[82:83], v[82:83], 0, v[86:87]
	global_store_dwordx4 v[82:83], v[76:79], off sc1

;     __device__ __forceinline__ void kvout(int row, int c, int kv, f32x4 v) const {
;         const int head = c >> 6, g = head >> 2, hs = head & 3, dd = c & 63;
;         if (row < MP) {
;             const int b = row >> 11, t = row & 2047;
;             const int win = g == 0 ? 128 : (g == 1 ? 512 : 2048);
;             const int tw = t - (2048 - win);
;             if (tw >= 0) {
;                 const size_t base = g == 0 ? O2 : (g == 1 ? O3 : O4);
;                 *(f32x4*)(out + base + ((((size_t)l * NB + b) * win + tw) * 2 + kv) * 256 + hs * 64 + dd) = v;
;             }
;         } else if (row < MR) {
;             const int r = row - MP;
;             const size_t base = g == 0 ? O6 : (g == 1 ? O7 : O8);
;             *(f32x4*)(out + base + (((size_t)l * MS + r) * 2 + kv) * 256 + hs * 64 + dd) = v;
;         }
.LBB0_614:
	v_lshlrev_b32_e32 v82, 2, v111
	v_mov_b32_e32 v83, v2
	v_lshl_add_u64 v[76:77], v[76:77], 0, v[82:83]
	v_lshlrev_b32_e32 v82, 2, v3
	v_lshl_add_u64 v[76:77], v[76:77], 0, v[82:83]
	global_store_dwordx4 v[76:77], v[72:75], off offset:1024 sc1

;     __device__ __forceinline__ void kvout(int row, int c, int kv, f32x4 v) const {
;         const int head = c >> 6, g = head >> 2, hs = head & 3, dd = c & 63;
;         if (row < MP) {
;             const int b = row >> 11, t = row & 2047;
;             const int win = g == 0 ? 128 : (g == 1 ? 512 : 2048);
;             const int tw = t - (2048 - win);
;             if (tw >= 0) {
;                 const size_t base = g == 0 ? O2 : (g == 1 ? O3 : O4);
;                 *(f32x4*)(out + base + ((((size_t)l * NB + b) * win + tw) * 2 + kv) * 256 + hs * 64 + dd) = v;
;             }
;         } else if (row < MR) {
;             const int r = row - MP;
;             const size_t base = g == 0 ? O6 : (g == 1 ? O7 : O8);
;             *(f32x4*)(out + base + (((size_t)l * MS + r) * 2 + kv) * 256 + hs * 64 + dd) = v;
;         }
.LBB0_626:
	v_lshlrev_b32_e32 v82, 2, v111
	v_mov_b32_e32 v83, v2
	v_lshl_add_u64 v[76:77], v[76:77], 0, v[82:83]
	v_lshlrev_b32_e32 v82, 2, v3
	v_lshl_add_u64 v[76:77], v[76:77], 0, v[82:83]
	global_store_dwordx4 v[76:77], v[72:75], off sc1

;     __device__ __forceinline__ void kvout(int row, int c, int kv, f32x4 v) const {
;         const int head = c >> 6, g = head >> 2, hs = head & 3, dd = c & 63;
;         if (row < MP) {
;             const int b = row >> 11, t = row & 2047;
;             const int win = g == 0 ? 128 : (g == 1 ? 512 : 2048);
;             const int tw = t - (2048 - win);
;             if (tw >= 0) {
;                 const size_t base = g == 0 ? O2 : (g == 1 ? O3 : O4);
;                 *(f32x4*)(out + base + ((((size_t)l * NB + b) * win + tw) * 2 + kv) * 256 + hs * 64 + dd) = v;
;             }
;         } else if (row < MR) {
;             const int r = row - MP;
;             const size_t base = g == 0 ? O6 : (g == 1 ? O7 : O8);
;             *(f32x4*)(out + base + (((size_t)l * MS + r) * 2 + kv) * 256 + hs * 64 + dd) = v;
;         }
.LBB0_640:
	v_lshlrev_b32_e32 v74, 2, v111
	v_mov_b32_e32 v75, v2
	v_lshl_add_u64 v[72:73], v[72:73], 0, v[74:75]
	v_lshlrev_b32_e32 v74, 2, v3
	v_lshl_add_u64 v[72:73], v[72:73], 0, v[74:75]
	global_store_dwordx4 v[72:73], v[68:71], off offset:1024 sc1

;     __device__ __forceinline__ void kvout(int row, int c, int kv, f32x4 v) const {
;         const int head = c >> 6, g = head >> 2, hs = head & 3, dd = c & 63;
;         if (row < MP) {
;             const int b = row >> 11, t = row & 2047;
;             const int win = g == 0 ? 128 : (g == 1 ? 512 : 2048);
;             const int tw = t - (2048 - win);
;             if (tw >= 0) {
;                 const size_t base = g == 0 ? O2 : (g == 1 ? O3 : O4);
;                 *(f32x4*)(out + base + ((((size_t)l * NB + b) * win + tw) * 2 + kv) * 256 + hs * 64 + dd) = v;
;             }
;         } else if (row < MR) {
;             const int r = row - MP;
;             const size_t base = g == 0 ? O6 : (g == 1 ? O7 : O8);
;             *(f32x4*)(out + base + (((size_t)l * MS + r) * 2 + kv) * 256 + hs * 64 + dd) = v;
;         }
.LBB0_652:
	v_lshlrev_b32_e32 v74, 2, v111
	v_mov_b32_e32 v75, v2
	v_lshl_add_u64 v[72:73], v[72:73], 0, v[74:75]
	v_lshlrev_b32_e32 v74, 2, v3
	v_lshl_add_u64 v[72:73], v[72:73], 0, v[74:75]
	global_store_dwordx4 v[72:73], v[68:71], off sc1

;     __device__ __forceinline__ void kvout(int row, int c, int kv, f32x4 v) const {
;         const int head = c >> 6, g = head >> 2, hs = head & 3, dd = c & 63;
;         if (row < MP) {
;             const int b = row >> 11, t = row & 2047;
;             const int win = g == 0 ? 128 : (g == 1 ? 512 : 2048);
;             const int tw = t - (2048 - win);
;             if (tw >= 0) {
;                 const size_t base = g == 0 ? O2 : (g == 1 ? O3 : O4);
;                 *(f32x4*)(out + base + ((((size_t)l * NB + b) * win + tw) * 2 + kv) * 256 + hs * 64 + dd) = v;
;             }
;         } else if (row < MR) {
;             const int r = row - MP;
;             const size_t base = g == 0 ? O6 : (g == 1 ? O7 : O8);
;             *(f32x4*)(out + base + (((size_t)l * MS + r) * 2 + kv) * 256 + hs * 64 + dd) = v;
;         }
.LBB0_668:
	v_lshlrev_b32_e32 v98, 2, v3
	v_mov_b32_e32 v99, v2
	v_lshl_add_u64 v[94:95], v[94:95], 0, v[98:99]
	v_lshlrev_b32_e32 v98, 2, v144
	v_lshl_add_u64 v[94:95], v[94:95], 0, v[98:99]
	global_store_dwordx4 v[94:95], v[64:67], off offset:1024 sc1

;     __device__ __forceinline__ void kvout(int row, int c, int kv, f32x4 v) const {
;         const int head = c >> 6, g = head >> 2, hs = head & 3, dd = c & 63;
;         if (row < MP) {
;             const int b = row >> 11, t = row & 2047;
;             const int win = g == 0 ? 128 : (g == 1 ? 512 : 2048);
;             const int tw = t - (2048 - win);
;             if (tw >= 0) {
;                 const size_t base = g == 0 ? O2 : (g == 1 ? O3 : O4);
;                 *(f32x4*)(out + base + ((((size_t)l * NB + b) * win + tw) * 2 + kv) * 256 + hs * 64 + dd) = v;
;             }
;         } else if (row < MR) {
;             const int r = row - MP;
;             const size_t base = g == 0 ? O6 : (g == 1 ? O7 : O8);
;             *(f32x4*)(out + base + (((size_t)l * MS + r) * 2 + kv) * 256 + hs * 64 + dd) = v;
;         }
.LBB0_680:
	v_lshlrev_b32_e32 v98, 2, v3
	v_mov_b32_e32 v99, v2
	v_lshl_add_u64 v[94:95], v[94:95], 0, v[98:99]
	v_lshlrev_b32_e32 v98, 2, v144
	v_lshl_add_u64 v[94:95], v[94:95], 0, v[98:99]
	global_store_dwordx4 v[94:95], v[64:67], off sc1

;     __device__ __forceinline__ void kvout(int row, int c, int kv, f32x4 v) const {
;         const int head = c >> 6, g = head >> 2, hs = head & 3, dd = c & 63;
;         if (row < MP) {
;             const int b = row >> 11, t = row & 2047;
;             const int win = g == 0 ? 128 : (g == 1 ? 512 : 2048);
;             const int tw = t - (2048 - win);
;             if (tw >= 0) {
;                 const size_t base = g == 0 ? O2 : (g == 1 ? O3 : O4);
;                 *(f32x4*)(out + base + ((((size_t)l * NB + b) * win + tw) * 2 + kv) * 256 + hs * 64 + dd) = v;
;             }
;         } else if (row < MR) {
;             const int r = row - MP;
;             const size_t base = g == 0 ? O6 : (g == 1 ? O7 : O8);
;             *(f32x4*)(out + base + (((size_t)l * MS + r) * 2 + kv) * 256 + hs * 64 + dd) = v;
;         }
.LBB0_694:
	v_lshlrev_b32_e32 v66, 2, v3
	v_mov_b32_e32 v67, v2
	v_lshl_add_u64 v[64:65], v[64:65], 0, v[66:67]
	v_lshlrev_b32_e32 v66, 2, v144
	v_lshl_add_u64 v[64:65], v[64:65], 0, v[66:67]
	global_store_dwordx4 v[64:65], v[60:63], off offset:1024 sc1

;     __device__ __forceinline__ void kvout(int row, int c, int kv, f32x4 v) const {
;         const int head = c >> 6, g = head >> 2, hs = head & 3, dd = c & 63;
;         if (row < MP) {
;             const int b = row >> 11, t = row & 2047;
;             const int win = g == 0 ? 128 : (g == 1 ? 512 : 2048);
;             const int tw = t - (2048 - win);
;             if (tw >= 0) {
;                 const size_t base = g == 0 ? O2 : (g == 1 ? O3 : O4);
;                 *(f32x4*)(out + base + ((((size_t)l * NB + b) * win + tw) * 2 + kv) * 256 + hs * 64 + dd) = v;
;             }
;         } else if (row < MR) {
;             const int r = row - MP;
;             const size_t base = g == 0 ? O6 : (g == 1 ? O7 : O8);
;             *(f32x4*)(out + base + (((size_t)l * MS + r) * 2 + kv) * 256 + hs * 64 + dd) = v;
;         }
.LBB0_706:
	v_lshlrev_b32_e32 v66, 2, v3
	v_mov_b32_e32 v67, v2
	v_lshl_add_u64 v[64:65], v[64:65], 0, v[66:67]
	v_lshlrev_b32_e32 v66, 2, v144
	v_lshl_add_u64 v[64:65], v[64:65], 0, v[66:67]
	global_store_dwordx4 v[64:65], v[60:63], off sc1

;     __device__ __forceinline__ void kvout(int row, int c, int kv, f32x4 v) const {
;         const int head = c >> 6, g = head >> 2, hs = head & 3, dd = c & 63;
;         if (row < MP) {
;             const int b = row >> 11, t = row & 2047;
;             const int win = g == 0 ? 128 : (g == 1 ? 512 : 2048);
;             const int tw = t - (2048 - win);
;             if (tw >= 0) {
;                 const size_t base = g == 0 ? O2 : (g == 1 ? O3 : O4);
;                 *(f32x4*)(out + base + ((((size_t)l * NB + b) * win + tw) * 2 + kv) * 256 + hs * 64 + dd) = v;
;             }
;         } else if (row < MR) {
;             const int r = row - MP;
;             const size_t base = g == 0 ? O6 : (g == 1 ? O7 : O8);
;             *(f32x4*)(out + base + (((size_t)l * MS + r) * 2 + kv) * 256 + hs * 64 + dd) = v;
;         }
.LBB0_720:
	v_lshlrev_b32_e32 v62, 2, v3
	v_mov_b32_e32 v63, v2
	v_lshl_add_u64 v[60:61], v[60:61], 0, v[62:63]
	v_lshlrev_b32_e32 v62, 2, v144
	v_lshl_add_u64 v[60:61], v[60:61], 0, v[62:63]
	global_store_dwordx4 v[60:61], v[56:59], off offset:1024 sc1

;     __device__ __forceinline__ void kvout(int row, int c, int kv, f32x4 v) const {
;         const int head = c >> 6, g = head >> 2, hs = head & 3, dd = c & 63;
;         if (row < MP) {
;             const int b = row >> 11, t = row & 2047;
;             const int win = g == 0 ? 128 : (g == 1 ? 512 : 2048);
;             const int tw = t - (2048 - win);
;             if (tw >= 0) {
;                 const size_t base = g == 0 ? O2 : (g == 1 ? O3 : O4);
;                 *(f32x4*)(out + base + ((((size_t)l * NB + b) * win + tw) * 2 + kv) * 256 + hs * 64 + dd) = v;
;             }
;         } else if (row < MR) {
;             const int r = row - MP;
;             const size_t base = g == 0 ? O6 : (g == 1 ? O7 : O8);
;             *(f32x4*)(out + base + (((size_t)l * MS + r) * 2 + kv) * 256 + hs * 64 + dd) = v;
;         }
.LBB0_732:
	v_lshlrev_b32_e32 v62, 2, v3
	v_mov_b32_e32 v63, v2
	v_lshl_add_u64 v[60:61], v[60:61], 0, v[62:63]
	v_lshlrev_b32_e32 v62, 2, v144
	v_lshl_add_u64 v[60:61], v[60:61], 0, v[62:63]
	global_store_dwordx4 v[60:61], v[56:59], off sc1

;     __device__ __forceinline__ void kvout(int row, int c, int kv, f32x4 v) const {
;         const int head = c >> 6, g = head >> 2, hs = head & 3, dd = c & 63;
;         if (row < MP) {
;             const int b = row >> 11, t = row & 2047;
;             const int win = g == 0 ? 128 : (g == 1 ? 512 : 2048);
;             const int tw = t - (2048 - win);
;             if (tw >= 0) {
;                 const size_t base = g == 0 ? O2 : (g == 1 ? O3 : O4);
;                 *(f32x4*)(out + base + ((((size_t)l * NB + b) * win + tw) * 2 + kv) * 256 + hs * 64 + dd) = v;
;             }
;         } else if (row < MR) {
;             const int r = row - MP;
;             const size_t base = g == 0 ? O6 : (g == 1 ? O7 : O8);
;             *(f32x4*)(out + base + (((size_t)l * MS + r) * 2 + kv) * 256 + hs * 64 + dd) = v;
;         }
.LBB0_746:
	v_lshlrev_b32_e32 v58, 2, v3
	v_mov_b32_e32 v59, v2
	v_lshl_add_u64 v[56:57], v[56:57], 0, v[58:59]
	v_lshlrev_b32_e32 v58, 2, v144
	v_lshl_add_u64 v[56:57], v[56:57], 0, v[58:59]
	global_store_dwordx4 v[56:57], v[52:55], off offset:1024 sc1

;     __device__ __forceinline__ void kvout(int row, int c, int kv, f32x4 v) const {
;         const int head = c >> 6, g = head >> 2, hs = head & 3, dd = c & 63;
;         if (row < MP) {
;             const int b = row >> 11, t = row & 2047;
;             const int win = g == 0 ? 128 : (g == 1 ? 512 : 2048);
;             const int tw = t - (2048 - win);
;             if (tw >= 0) {
;                 const size_t base = g == 0 ? O2 : (g == 1 ? O3 : O4);
;                 *(f32x4*)(out + base + ((((size_t)l * NB + b) * win + tw) * 2 + kv) * 256 + hs * 64 + dd) = v;
;             }
;         } else if (row < MR) {
;             const int r = row - MP;
;             const size_t base = g == 0 ? O6 : (g == 1 ? O7 : O8);
;             *(f32x4*)(out + base + (((size_t)l * MS + r) * 2 + kv) * 256 + hs * 64 + dd) = v;
;         }
.LBB0_758:
	v_lshlrev_b32_e32 v58, 2, v3
	v_mov_b32_e32 v59, v2
	v_lshl_add_u64 v[56:57], v[56:57], 0, v[58:59]
	v_lshlrev_b32_e32 v58, 2, v144
	v_lshl_add_u64 v[56:57], v[56:57], 0, v[58:59]
	global_store_dwordx4 v[56:57], v[52:55], off sc1

;     __device__ __forceinline__ void kvout(int row, int c, int kv, f32x4 v) const {
;         const int head = c >> 6, g = head >> 2, hs = head & 3, dd = c & 63;
;         if (row < MP) {
;             const int b = row >> 11, t = row & 2047;
;             const int win = g == 0 ? 128 : (g == 1 ? 512 : 2048);
;             const int tw = t - (2048 - win);
;             if (tw >= 0) {
;                 const size_t base = g == 0 ? O2 : (g == 1 ? O3 : O4);
;                 *(f32x4*)(out + base + ((((size_t)l * NB + b) * win + tw) * 2 + kv) * 256 + hs * 64 + dd) = v;
;             }
;         } else if (row < MR) {
;             const int r = row - MP;
;             const size_t base = g == 0 ? O6 : (g == 1 ? O7 : O8);
;             *(f32x4*)(out + base + (((size_t)l * MS + r) * 2 + kv) * 256 + hs * 64 + dd) = v;
;         }
.LBB0_772:
	v_lshlrev_b32_e32 v54, 2, v3
	v_mov_b32_e32 v55, v2
	v_lshl_add_u64 v[52:53], v[52:53], 0, v[54:55]
	v_lshlrev_b32_e32 v54, 2, v144
	v_lshl_add_u64 v[52:53], v[52:53], 0, v[54:55]
	global_store_dwordx4 v[52:53], v[48:51], off offset:1024 sc1

;     __device__ __forceinline__ void kvout(int row, int c, int kv, f32x4 v) const {
;         const int head = c >> 6, g = head >> 2, hs = head & 3, dd = c & 63;
;         if (row < MP) {
;             const int b = row >> 11, t = row & 2047;
;             const int win = g == 0 ? 128 : (g == 1 ? 512 : 2048);
;             const int tw = t - (2048 - win);
;             if (tw >= 0) {
;                 const size_t base = g == 0 ? O2 : (g == 1 ? O3 : O4);
;                 *(f32x4*)(out + base + ((((size_t)l * NB + b) * win + tw) * 2 + kv) * 256 + hs * 64 + dd) = v;
;             }
;         } else if (row < MR) {
;             const int r = row - MP;
;             const size_t base = g == 0 ? O6 : (g == 1 ? O7 : O8);
;             *(f32x4*)(out + base + (((size_t)l * MS + r) * 2 + kv) * 256 + hs * 64 + dd) = v;
;         }
.LBB0_784:
	v_lshlrev_b32_e32 v54, 2, v3
	v_mov_b32_e32 v55, v2
	v_lshl_add_u64 v[52:53], v[52:53], 0, v[54:55]
	v_lshlrev_b32_e32 v54, 2, v144
	v_lshl_add_u64 v[52:53], v[52:53], 0, v[54:55]
	global_store_dwordx4 v[52:53], v[48:51], off sc1

;     __device__ __forceinline__ void kvout(int row, int c, int kv, f32x4 v) const {
;         const int head = c >> 6, g = head >> 2, hs = head & 3, dd = c & 63;
;         if (row < MP) {
;             const int b = row >> 11, t = row & 2047;
;             const int win = g == 0 ? 128 : (g == 1 ? 512 : 2048);
;             const int tw = t - (2048 - win);
;             if (tw >= 0) {
;                 const size_t base = g == 0 ? O2 : (g == 1 ? O3 : O4);
;                 *(f32x4*)(out + base + ((((size_t)l * NB + b) * win + tw) * 2 + kv) * 256 + hs * 64 + dd) = v;
;             }
;         } else if (row < MR) {
;             const int r = row - MP;
;             const size_t base = g == 0 ? O6 : (g == 1 ? O7 : O8);
;             *(f32x4*)(out + base + (((size_t)l * MS + r) * 2 + kv) * 256 + hs * 64 + dd) = v;
;         }
.LBB0_798:
	v_lshlrev_b32_e32 v50, 2, v3
	v_mov_b32_e32 v51, v2
	v_lshl_add_u64 v[48:49], v[48:49], 0, v[50:51]
	v_lshlrev_b32_e32 v50, 2, v144
	v_lshl_add_u64 v[48:49], v[48:49], 0, v[50:51]
	global_store_dwordx4 v[48:49], v[44:47], off offset:1024 sc1

;     __device__ __forceinline__ void kvout(int row, int c, int kv, f32x4 v) const {
;         const int head = c >> 6, g = head >> 2, hs = head & 3, dd = c & 63;
;         if (row < MP) {
;             const int b = row >> 11, t = row & 2047;
;             const int win = g == 0 ? 128 : (g == 1 ? 512 : 2048);
;             const int tw = t - (2048 - win);
;             if (tw >= 0) {
;                 const size_t base = g == 0 ? O2 : (g == 1 ? O3 : O4);
;                 *(f32x4*)(out + base + ((((size_t)l * NB + b) * win + tw) * 2 + kv) * 256 + hs * 64 + dd) = v;
;             }
;         } else if (row < MR) {
;             const int r = row - MP;
;             const size_t base = g == 0 ? O6 : (g == 1 ? O7 : O8);
;             *(f32x4*)(out + base + (((size_t)l * MS + r) * 2 + kv) * 256 + hs * 64 + dd) = v;
;         }
.LBB0_810:
	v_lshlrev_b32_e32 v50, 2, v3
	v_mov_b32_e32 v51, v2
	v_lshl_add_u64 v[48:49], v[48:49], 0, v[50:51]
	v_lshlrev_b32_e32 v50, 2, v144
	v_lshl_add_u64 v[48:49], v[48:49], 0, v[50:51]
	global_store_dwordx4 v[48:49], v[44:47], off sc1

;     __device__ __forceinline__ void kvout(int row, int c, int kv, f32x4 v) const {
;         const int head = c >> 6, g = head >> 2, hs = head & 3, dd = c & 63;
;         if (row < MP) {
;             const int b = row >> 11, t = row & 2047;
;             const int win = g == 0 ? 128 : (g == 1 ? 512 : 2048);
;             const int tw = t - (2048 - win);
;             if (tw >= 0) {
;                 const size_t base = g == 0 ? O2 : (g == 1 ? O3 : O4);
;                 *(f32x4*)(out + base + ((((size_t)l * NB + b) * win + tw) * 2 + kv) * 256 + hs * 64 + dd) = v;
;             }
;         } else if (row < MR) {
;             const int r = row - MP;
;             const size_t base = g == 0 ? O6 : (g == 1 ? O7 : O8);
;             *(f32x4*)(out + base + (((size_t)l * MS + r) * 2 + kv) * 256 + hs * 64 + dd) = v;
;         }
.LBB0_824:
	v_lshlrev_b32_e32 v46, 2, v3
	v_mov_b32_e32 v47, v2
	v_lshl_add_u64 v[44:45], v[44:45], 0, v[46:47]
	v_lshlrev_b32_e32 v46, 2, v144
	v_lshl_add_u64 v[44:45], v[44:45], 0, v[46:47]
	global_store_dwordx4 v[44:45], v[40:43], off offset:1024 sc1

;     __device__ __forceinline__ void kvout(int row, int c, int kv, f32x4 v) const {
;         const int head = c >> 6, g = head >> 2, hs = head & 3, dd = c & 63;
;         if (row < MP) {
;             const int b = row >> 11, t = row & 2047;
;             const int win = g == 0 ? 128 : (g == 1 ? 512 : 2048);
;             const int tw = t - (2048 - win);
;             if (tw >= 0) {
;                 const size_t base = g == 0 ? O2 : (g == 1 ? O3 : O4);
;                 *(f32x4*)(out + base + ((((size_t)l * NB + b) * win + tw) * 2 + kv) * 256 + hs * 64 + dd) = v;
;             }
;         } else if (row < MR) {
;             const int r = row - MP;
;             const size_t base = g == 0 ? O6 : (g == 1 ? O7 : O8);
;             *(f32x4*)(out + base + (((size_t)l * MS + r) * 2 + kv) * 256 + hs * 64 + dd) = v;
;         }
.LBB0_836:
	v_lshlrev_b32_e32 v46, 2, v3
	v_mov_b32_e32 v47, v2
	v_lshl_add_u64 v[44:45], v[44:45], 0, v[46:47]
	v_lshlrev_b32_e32 v46, 2, v144
	v_lshl_add_u64 v[44:45], v[44:45], 0, v[46:47]
	global_store_dwordx4 v[44:45], v[40:43], off sc1

;     __device__ __forceinline__ void kvout(int row, int c, int kv, f32x4 v) const {
;         const int head = c >> 6, g = head >> 2, hs = head & 3, dd = c & 63;
;         if (row < MP) {
;             const int b = row >> 11, t = row & 2047;
;             const int win = g == 0 ? 128 : (g == 1 ? 512 : 2048);
;             const int tw = t - (2048 - win);
;             if (tw >= 0) {
;                 const size_t base = g == 0 ? O2 : (g == 1 ? O3 : O4);
;                 *(f32x4*)(out + base + ((((size_t)l * NB + b) * win + tw) * 2 + kv) * 256 + hs * 64 + dd) = v;
;             }
;         } else if (row < MR) {
;             const int r = row - MP;
;             const size_t base = g == 0 ? O6 : (g == 1 ? O7 : O8);
;             *(f32x4*)(out + base + (((size_t)l * MS + r) * 2 + kv) * 256 + hs * 64 + dd) = v;
;         }
.LBB0_850:
	v_lshlrev_b32_e32 v42, 2, v3
	v_mov_b32_e32 v43, v2
	v_lshl_add_u64 v[40:41], v[40:41], 0, v[42:43]
	v_lshlrev_b32_e32 v42, 2, v144
	v_lshl_add_u64 v[40:41], v[40:41], 0, v[42:43]
	global_store_dwordx4 v[40:41], v[36:39], off offset:1024 sc1

;     __device__ __forceinline__ void kvout(int row, int c, int kv, f32x4 v) const {
;         const int head = c >> 6, g = head >> 2, hs = head & 3, dd = c & 63;
;         if (row < MP) {
;             const int b = row >> 11, t = row & 2047;
;             const int win = g == 0 ? 128 : (g == 1 ? 512 : 2048);
;             const int tw = t - (2048 - win);
;             if (tw >= 0) {
;                 const size_t base = g == 0 ? O2 : (g == 1 ? O3 : O4);
;                 *(f32x4*)(out + base + ((((size_t)l * NB + b) * win + tw) * 2 + kv) * 256 + hs * 64 + dd) = v;
;             }
;         } else if (row < MR) {
;             const int r = row - MP;
;             const size_t base = g == 0 ? O6 : (g == 1 ? O7 : O8);
;             *(f32x4*)(out + base + (((size_t)l * MS + r) * 2 + kv) * 256 + hs * 64 + dd) = v;
;         }
.LBB0_862:
	v_lshlrev_b32_e32 v42, 2, v3
	v_mov_b32_e32 v43, v2
	v_lshl_add_u64 v[40:41], v[40:41], 0, v[42:43]
	v_lshlrev_b32_e32 v42, 2, v144
	v_lshl_add_u64 v[40:41], v[40:41], 0, v[42:43]
	global_store_dwordx4 v[40:41], v[36:39], off sc1

;     __device__ __forceinline__ void kvout(int row, int c, int kv, f32x4 v) const {
;         const int head = c >> 6, g = head >> 2, hs = head & 3, dd = c & 63;
;         if (row < MP) {
;             const int b = row >> 11, t = row & 2047;
;             const int win = g == 0 ? 128 : (g == 1 ? 512 : 2048);
;             const int tw = t - (2048 - win);
;             if (tw >= 0) {
;                 const size_t base = g == 0 ? O2 : (g == 1 ? O3 : O4);
;                 *(f32x4*)(out + base + ((((size_t)l * NB + b) * win + tw) * 2 + kv) * 256 + hs * 64 + dd) = v;
;             }
;         } else if (row < MR) {
;             const int r = row - MP;
;             const size_t base = g == 0 ? O6 : (g == 1 ? O7 : O8);
;             *(f32x4*)(out + base + (((size_t)l * MS + r) * 2 + kv) * 256 + hs * 64 + dd) = v;
;         }
.LBB0_878:
	v_lshlrev_b32_e32 v52, 2, v54
	v_mov_b32_e32 v53, v2
	v_lshl_add_u64 v[50:51], v[50:51], 0, v[52:53]
	v_lshlrev_b32_e32 v52, 2, v3
	v_lshl_add_u64 v[50:51], v[50:51], 0, v[52:53]
	global_store_dwordx4 v[50:51], v[32:35], off offset:1024 sc1

;     __device__ __forceinline__ void kvout(int row, int c, int kv, f32x4 v) const {
;         const int head = c >> 6, g = head >> 2, hs = head & 3, dd = c & 63;
;         if (row < MP) {
;             const int b = row >> 11, t = row & 2047;
;             const int win = g == 0 ? 128 : (g == 1 ? 512 : 2048);
;             const int tw = t - (2048 - win);
;             if (tw >= 0) {
;                 const size_t base = g == 0 ? O2 : (g == 1 ? O3 : O4);
;                 *(f32x4*)(out + base + ((((size_t)l * NB + b) * win + tw) * 2 + kv) * 256 + hs * 64 + dd) = v;
;             }
;         } else if (row < MR) {
;             const int r = row - MP;
;             const size_t base = g == 0 ? O6 : (g == 1 ? O7 : O8);
;             *(f32x4*)(out + base + (((size_t)l * MS + r) * 2 + kv) * 256 + hs * 64 + dd) = v;
;         }
.LBB0_890:
	v_lshlrev_b32_e32 v52, 2, v54
	v_mov_b32_e32 v53, v2
	v_lshl_add_u64 v[50:51], v[50:51], 0, v[52:53]
	v_lshlrev_b32_e32 v52, 2, v3
	v_lshl_add_u64 v[50:51], v[50:51], 0, v[52:53]
	global_store_dwordx4 v[50:51], v[32:35], off sc1

;     __device__ __forceinline__ void kvout(int row, int c, int kv, f32x4 v) const {
;         const int head = c >> 6, g = head >> 2, hs = head & 3, dd = c & 63;
;         if (row < MP) {
;             const int b = row >> 11, t = row & 2047;
;             const int win = g == 0 ? 128 : (g == 1 ? 512 : 2048);
;             const int tw = t - (2048 - win);
;             if (tw >= 0) {
;                 const size_t base = g == 0 ? O2 : (g == 1 ? O3 : O4);
;                 *(f32x4*)(out + base + ((((size_t)l * NB + b) * win + tw) * 2 + kv) * 256 + hs * 64 + dd) = v;
;             }
;         } else if (row < MR) {
;             const int r = row - MP;
;             const size_t base = g == 0 ? O6 : (g == 1 ? O7 : O8);
;             *(f32x4*)(out + base + (((size_t)l * MS + r) * 2 + kv) * 256 + hs * 64 + dd) = v;
;         }
.LBB0_904:
	v_lshlrev_b32_e32 v34, 2, v54
	v_mov_b32_e32 v35, v2
	v_lshl_add_u64 v[32:33], v[32:33], 0, v[34:35]
	v_lshlrev_b32_e32 v34, 2, v3
	v_lshl_add_u64 v[32:33], v[32:33], 0, v[34:35]
	global_store_dwordx4 v[32:33], v[28:31], off offset:1024 sc1

;     __device__ __forceinline__ void kvout(int row, int c, int kv, f32x4 v) const {
;         const int head = c >> 6, g = head >> 2, hs = head & 3, dd = c & 63;
;         if (row < MP) {
;             const int b = row >> 11, t = row & 2047;
;             const int win = g == 0 ? 128 : (g == 1 ? 512 : 2048);
;             const int tw = t - (2048 - win);
;             if (tw >= 0) {
;                 const size_t base = g == 0 ? O2 : (g == 1 ? O3 : O4);
;                 *(f32x4*)(out + base + ((((size_t)l * NB + b) * win + tw) * 2 + kv) * 256 + hs * 64 + dd) = v;
;             }
;         } else if (row < MR) {
;             const int r = row - MP;
;             const size_t base = g == 0 ? O6 : (g == 1 ? O7 : O8);
;             *(f32x4*)(out + base + (((size_t)l * MS + r) * 2 + kv) * 256 + hs * 64 + dd) = v;
;         }
.LBB0_916:
	v_lshlrev_b32_e32 v34, 2, v54
	v_mov_b32_e32 v35, v2
	v_lshl_add_u64 v[32:33], v[32:33], 0, v[34:35]
	v_lshlrev_b32_e32 v34, 2, v3
	v_lshl_add_u64 v[32:33], v[32:33], 0, v[34:35]
	global_store_dwordx4 v[32:33], v[28:31], off sc1

;     __device__ __forceinline__ void kvout(int row, int c, int kv, f32x4 v) const {
;         const int head = c >> 6, g = head >> 2, hs = head & 3, dd = c & 63;
;         if (row < MP) {
;             const int b = row >> 11, t = row & 2047;
;             const int win = g == 0 ? 128 : (g == 1 ? 512 : 2048);
;             const int tw = t - (2048 - win);
;             if (tw >= 0) {
;                 const size_t base = g == 0 ? O2 : (g == 1 ? O3 : O4);
;                 *(f32x4*)(out + base + ((((size_t)l * NB + b) * win + tw) * 2 + kv) * 256 + hs * 64 + dd) = v;
;             }
;         } else if (row < MR) {
;             const int r = row - MP;
;             const size_t base = g == 0 ? O6 : (g == 1 ? O7 : O8);
;             *(f32x4*)(out + base + (((size_t)l * MS + r) * 2 + kv) * 256 + hs * 64 + dd) = v;
;         }
.LBB0_930:
	v_lshlrev_b32_e32 v30, 2, v54
	v_mov_b32_e32 v31, v2
	v_lshl_add_u64 v[28:29], v[28:29], 0, v[30:31]
	v_lshlrev_b32_e32 v30, 2, v3
	v_lshl_add_u64 v[28:29], v[28:29], 0, v[30:31]
	global_store_dwordx4 v[28:29], v[24:27], off offset:1024 sc1

;     __device__ __forceinline__ void kvout(int row, int c, int kv, f32x4 v) const {
;         const int head = c >> 6, g = head >> 2, hs = head & 3, dd = c & 63;
;         if (row < MP) {
;             const int b = row >> 11, t = row & 2047;
;             const int win = g == 0 ? 128 : (g == 1 ? 512 : 2048);
;             const int tw = t - (2048 - win);
;             if (tw >= 0) {
;                 const size_t base = g == 0 ? O2 : (g == 1 ? O3 : O4);
;                 *(f32x4*)(out + base + ((((size_t)l * NB + b) * win + tw) * 2 + kv) * 256 + hs * 64 + dd) = v;
;             }
;         } else if (row < MR) {
;             const int r = row - MP;
;             const size_t base = g == 0 ? O6 : (g == 1 ? O7 : O8);
;             *(f32x4*)(out + base + (((size_t)l * MS + r) * 2 + kv) * 256 + hs * 64 + dd) = v;
;         }
.LBB0_942:
	v_lshlrev_b32_e32 v30, 2, v54
	v_mov_b32_e32 v31, v2
	v_lshl_add_u64 v[28:29], v[28:29], 0, v[30:31]
	v_lshlrev_b32_e32 v30, 2, v3
	v_lshl_add_u64 v[28:29], v[28:29], 0, v[30:31]
	global_store_dwordx4 v[28:29], v[24:27], off sc1

;     __device__ __forceinline__ void kvout(int row, int c, int kv, f32x4 v) const {
;         const int head = c >> 6, g = head >> 2, hs = head & 3, dd = c & 63;
;         if (row < MP) {
;             const int b = row >> 11, t = row & 2047;
;             const int win = g == 0 ? 128 : (g == 1 ? 512 : 2048);
;             const int tw = t - (2048 - win);
;             if (tw >= 0) {
;                 const size_t base = g == 0 ? O2 : (g == 1 ? O3 : O4);
;                 *(f32x4*)(out + base + ((((size_t)l * NB + b) * win + tw) * 2 + kv) * 256 + hs * 64 + dd) = v;
;             }
;         } else if (row < MR) {
;             const int r = row - MP;
;             const size_t base = g == 0 ? O6 : (g == 1 ? O7 : O8);
;             *(f32x4*)(out + base + (((size_t)l * MS + r) * 2 + kv) * 256 + hs * 64 + dd) = v;
;         }
.LBB0_956:
	v_lshlrev_b32_e32 v26, 2, v54
	v_mov_b32_e32 v27, v2
	v_lshl_add_u64 v[24:25], v[24:25], 0, v[26:27]
	v_lshlrev_b32_e32 v26, 2, v3
	v_lshl_add_u64 v[24:25], v[24:25], 0, v[26:27]
	global_store_dwordx4 v[24:25], v[20:23], off offset:1024 sc1

;     __device__ __forceinline__ void kvout(int row, int c, int kv, f32x4 v) const {
;         const int head = c >> 6, g = head >> 2, hs = head & 3, dd = c & 63;
;         if (row < MP) {
;             const int b = row >> 11, t = row & 2047;
;             const int win = g == 0 ? 128 : (g == 1 ? 512 : 2048);
;             const int tw = t - (2048 - win);
;             if (tw >= 0) {
;                 const size_t base = g == 0 ? O2 : (g == 1 ? O3 : O4);
;                 *(f32x4*)(out + base + ((((size_t)l * NB + b) * win + tw) * 2 + kv) * 256 + hs * 64 + dd) = v;
;             }
;         } else if (row < MR) {
;             const int r = row - MP;
;             const size_t base = g == 0 ? O6 : (g == 1 ? O7 : O8);
;             *(f32x4*)(out + base + (((size_t)l * MS + r) * 2 + kv) * 256 + hs * 64 + dd) = v;
;         }
.LBB0_968:
	v_lshlrev_b32_e32 v26, 2, v54
	v_mov_b32_e32 v27, v2
	v_lshl_add_u64 v[24:25], v[24:25], 0, v[26:27]
	v_lshlrev_b32_e32 v26, 2, v3
	v_lshl_add_u64 v[24:25], v[24:25], 0, v[26:27]
	global_store_dwordx4 v[24:25], v[20:23], off sc1

;     __device__ __forceinline__ void kvout(int row, int c, int kv, f32x4 v) const {
;         const int head = c >> 6, g = head >> 2, hs = head & 3, dd = c & 63;
;         if (row < MP) {
;             const int b = row >> 11, t = row & 2047;
;             const int win = g == 0 ? 128 : (g == 1 ? 512 : 2048);
;             const int tw = t - (2048 - win);
;             if (tw >= 0) {
;                 const size_t base = g == 0 ? O2 : (g == 1 ? O3 : O4);
;                 *(f32x4*)(out + base + ((((size_t)l * NB + b) * win + tw) * 2 + kv) * 256 + hs * 64 + dd) = v;
;             }
;         } else if (row < MR) {
;             const int r = row - MP;
;             const size_t base = g == 0 ? O6 : (g == 1 ? O7 : O8);
;             *(f32x4*)(out + base + (((size_t)l * MS + r) * 2 + kv) * 256 + hs * 64 + dd) = v;
;         }
.LBB0_982:
	v_lshlrev_b32_e32 v22, 2, v54
	v_mov_b32_e32 v23, v2
	v_lshl_add_u64 v[20:21], v[20:21], 0, v[22:23]
	v_lshlrev_b32_e32 v22, 2, v3
	v_lshl_add_u64 v[20:21], v[20:21], 0, v[22:23]
	global_store_dwordx4 v[20:21], v[16:19], off offset:1024 sc1

;     __device__ __forceinline__ void kvout(int row, int c, int kv, f32x4 v) const {
;         const int head = c >> 6, g = head >> 2, hs = head & 3, dd = c & 63;
;         if (row < MP) {
;             const int b = row >> 11, t = row & 2047;
;             const int win = g == 0 ? 128 : (g == 1 ? 512 : 2048);
;             const int tw = t - (2048 - win);
;             if (tw >= 0) {
;                 const size_t base = g == 0 ? O2 : (g == 1 ? O3 : O4);
;                 *(f32x4*)(out + base + ((((size_t)l * NB + b) * win + tw) * 2 + kv) * 256 + hs * 64 + dd) = v;
;             }
;         } else if (row < MR) {
;             const int r = row - MP;
;             const size_t base = g == 0 ? O6 : (g == 1 ? O7 : O8);
;             *(f32x4*)(out + base + (((size_t)l * MS + r) * 2 + kv) * 256 + hs * 64 + dd) = v;
;         }
.LBB0_994:
	v_lshlrev_b32_e32 v22, 2, v54
	v_mov_b32_e32 v23, v2
	v_lshl_add_u64 v[20:21], v[20:21], 0, v[22:23]
	v_lshlrev_b32_e32 v22, 2, v3
	v_lshl_add_u64 v[20:21], v[20:21], 0, v[22:23]
	global_store_dwordx4 v[20:21], v[16:19], off sc1

;     __device__ __forceinline__ void kvout(int row, int c, int kv, f32x4 v) const {
;         const int head = c >> 6, g = head >> 2, hs = head & 3, dd = c & 63;
;         if (row < MP) {
;             const int b = row >> 11, t = row & 2047;
;             const int win = g == 0 ? 128 : (g == 1 ? 512 : 2048);
;             const int tw = t - (2048 - win);
;             if (tw >= 0) {
;                 const size_t base = g == 0 ? O2 : (g == 1 ? O3 : O4);
;                 *(f32x4*)(out + base + ((((size_t)l * NB + b) * win + tw) * 2 + kv) * 256 + hs * 64 + dd) = v;
;             }
;         } else if (row < MR) {
;             const int r = row - MP;
;             const size_t base = g == 0 ? O6 : (g == 1 ? O7 : O8);
;             *(f32x4*)(out + base + (((size_t)l * MS + r) * 2 + kv) * 256 + hs * 64 + dd) = v;
;         }
.LBB0_1008:
	v_lshlrev_b32_e32 v18, 2, v54
	v_mov_b32_e32 v19, v2
	v_lshl_add_u64 v[16:17], v[16:17], 0, v[18:19]
	v_lshlrev_b32_e32 v18, 2, v3
	v_lshl_add_u64 v[16:17], v[16:17], 0, v[18:19]
	global_store_dwordx4 v[16:17], v[12:15], off offset:1024 sc1

;     __device__ __forceinline__ void kvout(int row, int c, int kv, f32x4 v) const {
;         const int head = c >> 6, g = head >> 2, hs = head & 3, dd = c & 63;
;         if (row < MP) {
;             const int b = row >> 11, t = row & 2047;
;             const int win = g == 0 ? 128 : (g == 1 ? 512 : 2048);
;             const int tw = t - (2048 - win);
;             if (tw >= 0) {
;                 const size_t base = g == 0 ? O2 : (g == 1 ? O3 : O4);
;                 *(f32x4*)(out + base + ((((size_t)l * NB + b) * win + tw) * 2 + kv) * 256 + hs * 64 + dd) = v;
;             }
;         } else if (row < MR) {
;             const int r = row - MP;
;             const size_t base = g == 0 ? O6 : (g == 1 ? O7 : O8);
;             *(f32x4*)(out + base + (((size_t)l * MS + r) * 2 + kv) * 256 + hs * 64 + dd) = v;
;         }
.LBB0_1020:
	v_lshlrev_b32_e32 v18, 2, v54
	v_mov_b32_e32 v19, v2
	v_lshl_add_u64 v[16:17], v[16:17], 0, v[18:19]
	v_lshlrev_b32_e32 v18, 2, v3
	v_lshl_add_u64 v[16:17], v[16:17], 0, v[18:19]
	global_store_dwordx4 v[16:17], v[12:15], off sc1

;     __device__ __forceinline__ void kvout(int row, int c, int kv, f32x4 v) const {
;         const int head = c >> 6, g = head >> 2, hs = head & 3, dd = c & 63;
;         if (row < MP) {
;             const int b = row >> 11, t = row & 2047;
;             const int win = g == 0 ? 128 : (g == 1 ? 512 : 2048);
;             const int tw = t - (2048 - win);
;             if (tw >= 0) {
;                 const size_t base = g == 0 ? O2 : (g == 1 ? O3 : O4);
;                 *(f32x4*)(out + base + ((((size_t)l * NB + b) * win + tw) * 2 + kv) * 256 + hs * 64 + dd) = v;
;             }
;         } else if (row < MR) {
;             const int r = row - MP;
;             const size_t base = g == 0 ? O6 : (g == 1 ? O7 : O8);
;             *(f32x4*)(out + base + (((size_t)l * MS + r) * 2 + kv) * 256 + hs * 64 + dd) = v;
;         }
.LBB0_1034:
	v_lshlrev_b32_e32 v14, 2, v54
	v_mov_b32_e32 v15, v2
	v_lshl_add_u64 v[12:13], v[12:13], 0, v[14:15]
	v_lshlrev_b32_e32 v14, 2, v3
	v_lshl_add_u64 v[12:13], v[12:13], 0, v[14:15]
	global_store_dwordx4 v[12:13], v[8:11], off offset:1024 sc1

;     __device__ __forceinline__ void kvout(int row, int c, int kv, f32x4 v) const {
;         const int head = c >> 6, g = head >> 2, hs = head & 3, dd = c & 63;
;         if (row < MP) {
;             const int b = row >> 11, t = row & 2047;
;             const int win = g == 0 ? 128 : (g == 1 ? 512 : 2048);
;             const int tw = t - (2048 - win);
;             if (tw >= 0) {
;                 const size_t base = g == 0 ? O2 : (g == 1 ? O3 : O4);
;                 *(f32x4*)(out + base + ((((size_t)l * NB + b) * win + tw) * 2 + kv) * 256 + hs * 64 + dd) = v;
;             }
;         } else if (row < MR) {
;             const int r = row - MP;
;             const size_t base = g == 0 ? O6 : (g == 1 ? O7 : O8);
;             *(f32x4*)(out + base + (((size_t)l * MS + r) * 2 + kv) * 256 + hs * 64 + dd) = v;
;         }
.LBB0_1046:
	v_lshlrev_b32_e32 v14, 2, v54
	v_mov_b32_e32 v15, v2
	v_lshl_add_u64 v[12:13], v[12:13], 0, v[14:15]
	v_lshlrev_b32_e32 v14, 2, v3
	v_lshl_add_u64 v[12:13], v[12:13], 0, v[14:15]
	global_store_dwordx4 v[12:13], v[8:11], off sc1

;     __device__ __forceinline__ void kvout(int row, int c, int kv, f32x4 v) const {
;         const int head = c >> 6, g = head >> 2, hs = head & 3, dd = c & 63;
;         if (row < MP) {
;             const int b = row >> 11, t = row & 2047;
;             const int win = g == 0 ? 128 : (g == 1 ? 512 : 2048);
;             const int tw = t - (2048 - win);
;             if (tw >= 0) {
;                 const size_t base = g == 0 ? O2 : (g == 1 ? O3 : O4);
;                 *(f32x4*)(out + base + ((((size_t)l * NB + b) * win + tw) * 2 + kv) * 256 + hs * 64 + dd) = v;
;             }
;         } else if (row < MR) {
;             const int r = row - MP;
;             const size_t base = g == 0 ? O6 : (g == 1 ? O7 : O8);
;             *(f32x4*)(out + base + (((size_t)l * MS + r) * 2 + kv) * 256 + hs * 64 + dd) = v;
;         }
.LBB0_1063:
	v_lshlrev_b32_e32 v10, 2, v54
	v_mov_b32_e32 v11, v2
	v_lshl_add_u64 v[8:9], v[8:9], 0, v[10:11]
	v_lshlrev_b32_e32 v10, 2, v3
	v_lshl_add_u64 v[8:9], v[8:9], 0, v[10:11]
	global_store_dwordx4 v[8:9], v[4:7], off offset:1024 sc1

;     __device__ __forceinline__ void kvout(int row, int c, int kv, f32x4 v) const {
;         const int head = c >> 6, g = head >> 2, hs = head & 3, dd = c & 63;
;         if (row < MP) {
;             const int b = row >> 11, t = row & 2047;
;             const int win = g == 0 ? 128 : (g == 1 ? 512 : 2048);
;             const int tw = t - (2048 - win);
;             if (tw >= 0) {
;                 const size_t base = g == 0 ? O2 : (g == 1 ? O3 : O4);
;                 *(f32x4*)(out + base + ((((size_t)l * NB + b) * win + tw) * 2 + kv) * 256 + hs * 64 + dd) = v;
;             }
;         } else if (row < MR) {
;             const int r = row - MP;
;             const size_t base = g == 0 ? O6 : (g == 1 ? O7 : O8);
;             *(f32x4*)(out + base + (((size_t)l * MS + r) * 2 + kv) * 256 + hs * 64 + dd) = v;
;         }
.LBB0_1074:
	v_lshlrev_b32_e32 v10, 2, v54
	v_mov_b32_e32 v11, v2
	v_lshl_add_u64 v[8:9], v[8:9], 0, v[10:11]
	v_lshlrev_b32_e32 v10, 2, v3
	v_lshl_add_u64 v[8:9], v[8:9], 0, v[10:11]
	global_store_dwordx4 v[8:9], v[4:7], off sc1

; __device__ __forceinline__ u32x2 pk4(f32x4 v) { u32x2 r; r.x = pk2(v.x, v.y); r.y = pk2(v.z, v.w); return r; }
;     __device__ __forceinline__ void kvout(int row, int c, int kv, f32x4 v) const {
;     ...
;         } else if (row < MR) {
;             const int r = row - MP;
;             const size_t base = g == 0 ? O6 : (g == 1 ? O7 : O8);
;             *(f32x4*)(out + base + (((size_t)l * MS + r) * 2 + kv) * 256 + hs * 64 + dd) = v;
;         }
;     __device__ __forceinline__ void operator()(int row, int col, f32x4 v, int fq, float& s1, float& s2) const {
;     ...
;             else { *(u32x2*)(Kb + (size_t)row * ATT + c) = pk4(v); kvout(row, c, 0, v); }
;         } else if (col < 2304) {
;             const int c = col - 1536;
;             *(u32x2*)(Vb + (size_t)row * ATT + c) = pk4(v); kvout(row, c, 1, v);
.LBB0_1496:
	s_andn2_saveexec_b64 s[0:1], s[42:43]
	s_cbranch_execz .LBB0_1498
	v_add_u32_e32 v30, 0xfffffa00, v28
	v_mov_b32_e32 v31, v2
	v_cvt_pk_bf16_f32 v32, v4, v5
	v_cvt_pk_bf16_f32 v33, v6, v7
	v_lshl_add_u64 v[34:35], v[30:31], 1, v[12:13]
	global_store_dwordx2 v[34:35], v[32:33], off
	v_and_b32_e32 v25, 0xc0, v28
	v_and_b32_e32 v32, 60, v28
	v_and_b32_e32 v28, 0xffffff00, v30
	v_cmp_eq_u32_e32 vcc, s3, v28
	s_movk_i32 s4, 0xff
	v_mov_b32_e32 v29, v2
	v_cndmask_b32_e32 v28, v223, v224, vcc
	v_cmp_lt_u32_e32 vcc, s4, v30
	v_lshlrev_b32_e32 v30, 2, v25
	s_nop 0
	v_cndmask_b32_e32 v28, v225, v28, vcc
	v_lshlrev_b32_e32 v28, 2, v28
	v_lshl_add_u64 v[28:29], v[14:15], 0, v[28:29]
	v_lshl_add_u64 v[28:29], v[28:29], 0, v[30:31]
	v_lshlrev_b32_e32 v30, 2, v32
	v_lshl_add_u64 v[28:29], v[28:29], 0, v[30:31]
	global_store_dwordx4 v[28:29], v[4:7], off offset:1024 sc1

; __device__ __forceinline__ u32x2 pk4(f32x4 v) { u32x2 r; r.x = pk2(v.x, v.y); r.y = pk2(v.z, v.w); return r; }
;     __device__ __forceinline__ void kvout(int row, int c, int kv, f32x4 v) const {
;     ...
;         } else if (row < MR) {
;             const int r = row - MP;
;             const size_t base = g == 0 ? O6 : (g == 1 ? O7 : O8);
;             *(f32x4*)(out + base + (((size_t)l * MS + r) * 2 + kv) * 256 + hs * 64 + dd) = v;
;         }
;     __device__ __forceinline__ void operator()(int row, int col, f32x4 v, int fq, float& s1, float& s2) const {
;     ...
;             else { *(u32x2*)(Kb + (size_t)row * ATT + c) = pk4(v); kvout(row, c, 0, v); }
;         } else if (col < 2304) {
;             const int c = col - 1536;
;             *(u32x2*)(Vb + (size_t)row * ATT + c) = pk4(v); kvout(row, c, 1, v);
.LBB0_1504:
	s_andn2_saveexec_b64 s[0:1], s[0:1]
	s_cbranch_execz .LBB0_1483
	v_add_u32_e32 v30, 0xfffffd00, v28
	v_mov_b32_e32 v31, v2
	v_cvt_pk_bf16_f32 v32, v4, v5
	v_cvt_pk_bf16_f32 v33, v6, v7
	v_lshl_add_u64 v[34:35], v[30:31], 1, v[20:21]
	global_store_dwordx2 v[34:35], v[32:33], off
	v_and_b32_e32 v25, 0xc0, v28
	v_and_b32_e32 v32, 60, v28
	v_and_b32_e32 v28, 0xffffff00, v30
	v_cmp_eq_u32_e32 vcc, s3, v28
	s_movk_i32 s4, 0xff
	v_mov_b32_e32 v29, v2
	v_cndmask_b32_e32 v28, v223, v224, vcc
	v_cmp_lt_u32_e32 vcc, s4, v30
	v_lshlrev_b32_e32 v30, 2, v25
	s_nop 0
	v_cndmask_b32_e32 v28, v225, v28, vcc
	v_lshlrev_b32_e32 v28, 2, v28
	v_lshl_add_u64 v[28:29], v[14:15], 0, v[28:29]
	v_lshl_add_u64 v[28:29], v[28:29], 0, v[30:31]
	v_lshlrev_b32_e32 v30, 2, v32
	v_lshl_add_u64 v[28:29], v[28:29], 0, v[30:31]
	global_store_dwordx4 v[28:29], v[4:7], off sc1
	s_branch .LBB0_1483

; __device__ __forceinline__ u32x2 pk4(f32x4 v) { u32x2 r; r.x = pk2(v.x, v.y); r.y = pk2(v.z, v.w); return r; }
;     __device__ __forceinline__ void operator()(int row, int col, f32x4 v, int, float&, float&) const { *(u32x2*)(O + (size_t)row * ldc + col) = pk4(v * s); }
;     __device__ __forceinline__ void operator()(const f32x4 (&acc)[2][2][4][2], const Unit& u, int wr, int wc, int fr, int fq) const {
; #pragma unroll
;         for (int bj = 0; bj < 2; ++bj)
; #pragma unroll
;             for (int n = 0; n < 2; ++n) {
;                 const int col = u.pn * BM + bj * HALF + wc * 32 + n * 16 + fq * 4;
; #pragma unroll
;                 for (int ai = 0; ai < 2; ++ai)
; #pragma unroll
;                     for (int m = 0; m < 4; ++m) f(u.pm * BM + ai * HALF + wr * 64 + m * 16 + fr, col, acc[ai][bj][m][n], fq);
;             }
;     __device__ __forceinline__ void operator()(int row, int col, f32x4 v, int) const {
;         const int c = col;
;         *(f32x4*)(out + O5 + ((size_t)l * 2048 + row) * 2048 + c) = v;
;         *(u32x2*)(mkv + ((size_t)l * 2048 + row) * 2048 + c) = pk4(v);
;     }
.LBB0_1523:
	v_lshl_add_u32 v144, s23, 8, v3
	v_lshl_add_u32 v142, s22, 8, v139
	v_ashrrev_i32_e32 v145, 31, v144
	v_ashrrev_i32_e32 v143, 31, v142
	v_lshlrev_b64 v[146:147], 13, v[144:145]
	v_lshl_add_u64 v[146:147], s[6:7], 0, v[146:147]
	v_lshlrev_b64 v[148:149], 2, v[142:143]
	v_lshl_add_u64 v[146:147], v[146:147], 0, v[148:149]
	global_store_dwordx4 v[146:147], v[128:131], off sc1
	v_lshlrev_b64 v[142:143], 1, v[142:143]
	s_andn2_b64 vcc, exec, s[40:41]
	v_cvt_pk_bf16_f32 v128, v128, v129
	v_cvt_pk_bf16_f32 v129, v130, v131
	v_lshlrev_b64 v[130:131], 12, v[144:145]
	v_lshl_add_u64 v[130:131], s[38:39], 0, v[130:131]
	v_lshl_add_u64 v[130:131], v[130:131], 0, v[142:143]
	global_store_dwordx2 v[130:131], v[128:129], off
	v_or_b32_e32 v128, 16, v144
	v_ashrrev_i32_e32 v129, 31, v128
	v_lshlrev_b64 v[150:151], 13, v[128:129]
	v_lshl_add_u64 v[150:151], s[6:7], 0, v[150:151]
	v_lshl_add_u64 v[150:151], v[150:151], 0, v[148:149]
	global_store_dwordx4 v[150:151], v[124:127], off sc1
	s_mov_b64 s[0:1], -1
	s_nop 0
	v_cvt_pk_bf16_f32 v124, v124, v125
	v_cvt_pk_bf16_f32 v125, v126, v127
	v_lshlrev_b64 v[126:127], 12, v[128:129]
	v_lshl_add_u64 v[126:127], s[38:39], 0, v[126:127]
	v_lshl_add_u64 v[126:127], v[126:127], 0, v[142:143]
	global_store_dwordx2 v[126:127], v[124:125], off
	v_or_b32_e32 v124, 32, v144
	v_ashrrev_i32_e32 v125, 31, v124
	v_lshlrev_b64 v[128:129], 13, v[124:125]
	v_lshl_add_u64 v[128:129], s[6:7], 0, v[128:129]
	v_lshl_add_u64 v[128:129], v[128:129], 0, v[148:149]
	global_store_dwordx4 v[128:129], v[120:123], off sc1
	s_nop 1
	v_cvt_pk_bf16_f32 v120, v120, v121
	v_cvt_pk_bf16_f32 v121, v122, v123
	v_lshlrev_b64 v[122:123], 12, v[124:125]
	v_lshl_add_u64 v[122:123], s[38:39], 0, v[122:123]
	v_lshl_add_u64 v[122:123], v[122:123], 0, v[142:143]
	global_store_dwordx2 v[122:123], v[120:121], off
	v_or_b32_e32 v120, 48, v144
	v_ashrrev_i32_e32 v121, 31, v120
	v_lshlrev_b64 v[124:125], 13, v[120:121]
	v_lshl_add_u64 v[124:125], s[6:7], 0, v[124:125]
	v_lshl_add_u64 v[124:125], v[124:125], 0, v[148:149]
	global_store_dwordx4 v[124:125], v[116:119], off sc1
	s_nop 1
	v_cvt_pk_bf16_f32 v116, v116, v117
	v_cvt_pk_bf16_f32 v117, v118, v119
	v_lshlrev_b64 v[118:119], 12, v[120:121]
	v_lshl_add_u64 v[118:119], s[38:39], 0, v[118:119]
	v_lshl_add_u64 v[118:119], v[118:119], 0, v[142:143]
	global_store_dwordx2 v[118:119], v[116:117], off
	v_add_u32_e32 v116, 0x80, v144
	v_ashrrev_i32_e32 v117, 31, v116
	v_lshlrev_b64 v[120:121], 13, v[116:117]
	v_lshl_add_u64 v[120:121], s[6:7], 0, v[120:121]
	v_lshl_add_u64 v[120:121], v[120:121], 0, v[148:149]
	global_store_dwordx4 v[120:121], v[108:111], off sc1
	s_nop 1
	v_cvt_pk_bf16_f32 v108, v108, v109
	v_cvt_pk_bf16_f32 v109, v110, v111
	v_lshlrev_b64 v[110:111], 12, v[116:117]
	v_lshl_add_u64 v[110:111], s[38:39], 0, v[110:111]
	v_lshl_add_u64 v[110:111], v[110:111], 0, v[142:143]
	global_store_dwordx2 v[110:111], v[108:109], off
	v_add_u32_e32 v108, 0x90, v144
	v_ashrrev_i32_e32 v109, 31, v108
	v_lshlrev_b64 v[116:117], 13, v[108:109]
	v_lshl_add_u64 v[116:117], s[6:7], 0, v[116:117]
	v_lshl_add_u64 v[116:117], v[116:117], 0, v[148:149]
	global_store_dwordx4 v[116:117], v[100:103], off sc1
	s_nop 1
	v_cvt_pk_bf16_f32 v100, v100, v101
	v_cvt_pk_bf16_f32 v101, v102, v103
	v_lshlrev_b64 v[102:103], 12, v[108:109]
	v_lshl_add_u64 v[102:103], s[38:39], 0, v[102:103]
	v_lshl_add_u64 v[102:103], v[102:103], 0, v[142:143]
	global_store_dwordx2 v[102:103], v[100:101], off
	v_add_u32_e32 v100, 0xa0, v144
	v_ashrrev_i32_e32 v101, 31, v100
	v_lshlrev_b64 v[108:109], 13, v[100:101]
	v_lshl_add_u64 v[108:109], s[6:7], 0, v[108:109]
	v_lshl_add_u64 v[108:109], v[108:109], 0, v[148:149]
	global_store_dwordx4 v[108:109], v[88:91], off sc1
	s_nop 1
	v_cvt_pk_bf16_f32 v88, v88, v89
	v_cvt_pk_bf16_f32 v89, v90, v91
	v_lshlrev_b64 v[90:91], 12, v[100:101]
	v_lshl_add_u64 v[90:91], s[38:39], 0, v[90:91]
	v_lshl_add_u64 v[90:91], v[90:91], 0, v[142:143]
	global_store_dwordx2 v[90:91], v[88:89], off
	v_add_u32_e32 v88, 0xb0, v144
	v_ashrrev_i32_e32 v89, 31, v88
	v_lshlrev_b64 v[100:101], 13, v[88:89]
	v_lshl_add_u64 v[100:101], s[6:7], 0, v[100:101]
	v_lshl_add_u64 v[100:101], v[100:101], 0, v[148:149]
	global_store_dwordx4 v[100:101], v[84:87], off sc1
	s_nop 1
	v_cvt_pk_bf16_f32 v84, v84, v85
	v_cvt_pk_bf16_f32 v85, v86, v87
	v_lshlrev_b64 v[86:87], 12, v[88:89]
	v_lshl_add_u64 v[86:87], s[38:39], 0, v[86:87]
	v_lshl_add_u64 v[86:87], v[86:87], 0, v[142:143]
	global_store_dwordx2 v[86:87], v[84:85], off
	global_store_dwordx4 v[146:147], v[112:115], off offset:64 sc1
	v_cvt_pk_bf16_f32 v84, v112, v113
; __device__ __forceinline__ u32x2 pk4(f32x4 v) { u32x2 r; r.x = pk2(v.x, v.y); r.y = pk2(v.z, v.w); return r; }
;     __device__ __forceinline__ void operator()(int row, int col, f32x4 v, int, float&, float&) const { *(u32x2*)(O + (size_t)row * ldc + col) = pk4(v * s); }
;     __device__ __forceinline__ void operator()(const f32x4 (&acc)[2][2][4][2], const Unit& u, int wr, int wc, int fr, int fq) const {
; #pragma unroll
;         for (int bj = 0; bj < 2; ++bj)
; #pragma unroll
;             for (int n = 0; n < 2; ++n) {
;                 const int col = u.pn * BM + bj * HALF + wc * 32 + n * 16 + fq * 4;
; #pragma unroll
;                 for (int ai = 0; ai < 2; ++ai)
; #pragma unroll
;                     for (int m = 0; m < 4; ++m) f(u.pm * BM + ai * HALF + wr * 64 + m * 16 + fr, col, acc[ai][bj][m][n], fq);
;             }
;     __device__ __forceinline__ void operator()(int row, int col, f32x4 v, int) const {
;         const int c = col;
;         *(f32x4*)(out + O5 + ((size_t)l * 2048 + row) * 2048 + c) = v;
;         *(u32x2*)(mkv + ((size_t)l * 2048 + row) * 2048 + c) = pk4(v);
;     }
	v_cvt_pk_bf16_f32 v85, v114, v115
	global_store_dwordx2 v[130:131], v[84:85], off offset:32
	global_store_dwordx4 v[150:151], v[104:107], off offset:64 sc1
	v_cvt_pk_bf16_f32 v84, v104, v105
	v_cvt_pk_bf16_f32 v85, v106, v107
	global_store_dwordx2 v[126:127], v[84:85], off offset:32
	global_store_dwordx4 v[128:129], v[96:99], off offset:64 sc1
	v_cvt_pk_bf16_f32 v84, v96, v97
	v_cvt_pk_bf16_f32 v85, v98, v99
	global_store_dwordx2 v[122:123], v[84:85], off offset:32
	global_store_dwordx4 v[124:125], v[92:95], off offset:64 sc1
	v_cvt_pk_bf16_f32 v84, v92, v93
	v_cvt_pk_bf16_f32 v85, v94, v95
	global_store_dwordx2 v[118:119], v[84:85], off offset:32
	global_store_dwordx4 v[120:121], v[76:79], off offset:64 sc1
	s_nop 1
	v_cvt_pk_bf16_f32 v76, v76, v77
	v_cvt_pk_bf16_f32 v77, v78, v79
	global_store_dwordx2 v[110:111], v[76:77], off offset:32
	global_store_dwordx4 v[116:117], v[68:71], off offset:64 sc1
	s_nop 1
	v_cvt_pk_bf16_f32 v68, v68, v69
	v_cvt_pk_bf16_f32 v69, v70, v71
	global_store_dwordx2 v[102:103], v[68:69], off offset:32
	global_store_dwordx4 v[108:109], v[60:63], off offset:64 sc1
	s_nop 1
	v_cvt_pk_bf16_f32 v60, v60, v61
	v_cvt_pk_bf16_f32 v61, v62, v63
	global_store_dwordx2 v[90:91], v[60:61], off offset:32
	global_store_dwordx4 v[100:101], v[48:51], off offset:64 sc1
	s_nop 1
	v_cvt_pk_bf16_f32 v48, v48, v49
	v_cvt_pk_bf16_f32 v49, v50, v51
	global_store_dwordx2 v[86:87], v[48:49], off offset:32
	global_store_dwordx4 v[146:147], v[80:83], off offset:512 sc1
	v_cvt_pk_bf16_f32 v48, v80, v81
	v_cvt_pk_bf16_f32 v49, v82, v83
	global_store_dwordx2 v[130:131], v[48:49], off offset:256
	global_store_dwordx4 v[150:151], v[72:75], off offset:512 sc1
	v_cvt_pk_bf16_f32 v48, v72, v73
	v_cvt_pk_bf16_f32 v49, v74, v75
	global_store_dwordx2 v[126:127], v[48:49], off offset:256
	global_store_dwordx4 v[128:129], v[64:67], off offset:512 sc1
	v_cvt_pk_bf16_f32 v48, v64, v65
	v_cvt_pk_bf16_f32 v49, v66, v67
	global_store_dwordx2 v[122:123], v[48:49], off offset:256
	global_store_dwordx4 v[124:125], v[56:59], off offset:512 sc1
	v_cvt_pk_bf16_f32 v48, v56, v57
	v_cvt_pk_bf16_f32 v49, v58, v59
	global_store_dwordx2 v[118:119], v[48:49], off offset:256
	global_store_dwordx4 v[120:121], v[36:39], off offset:512 sc1
	s_nop 1
	v_cvt_pk_bf16_f32 v36, v36, v37
	v_cvt_pk_bf16_f32 v37, v38, v39
	global_store_dwordx2 v[110:111], v[36:37], off offset:256
	global_store_dwordx4 v[116:117], v[28:31], off offset:512 sc1
	s_nop 1
	v_cvt_pk_bf16_f32 v28, v28, v29
	v_cvt_pk_bf16_f32 v29, v30, v31
	global_store_dwordx2 v[102:103], v[28:29], off offset:256
	global_store_dwordx4 v[108:109], v[24:27], off offset:512 sc1
	s_nop 1
	v_cvt_pk_bf16_f32 v24, v24, v25
	v_cvt_pk_bf16_f32 v25, v26, v27
	global_store_dwordx2 v[90:91], v[24:25], off offset:256
	global_store_dwordx4 v[100:101], v[20:23], off offset:512 sc1
	s_nop 1
	v_cvt_pk_bf16_f32 v20, v20, v21
	v_cvt_pk_bf16_f32 v21, v22, v23
	global_store_dwordx2 v[86:87], v[20:21], off offset:256
	global_store_dwordx4 v[146:147], v[52:55], off offset:576 sc1
	v_cvt_pk_bf16_f32 v20, v52, v53
	v_cvt_pk_bf16_f32 v21, v54, v55
	global_store_dwordx2 v[130:131], v[20:21], off offset:288
	global_store_dwordx4 v[150:151], v[44:47], off offset:576 sc1
	v_cvt_pk_bf16_f32 v20, v44, v45
	v_cvt_pk_bf16_f32 v21, v46, v47
	global_store_dwordx2 v[126:127], v[20:21], off offset:288
	global_store_dwordx4 v[128:129], v[40:43], off offset:576 sc1
	v_cvt_pk_bf16_f32 v20, v40, v41
	v_cvt_pk_bf16_f32 v21, v42, v43
	global_store_dwordx2 v[122:123], v[20:21], off offset:288
	global_store_dwordx4 v[124:125], v[32:35], off offset:576 sc1
	v_cvt_pk_bf16_f32 v20, v32, v33
	v_cvt_pk_bf16_f32 v21, v34, v35
	global_store_dwordx2 v[118:119], v[20:21], off offset:288
	global_store_dwordx4 v[120:121], v[16:19], off offset:576 sc1
	s_nop 1
	v_cvt_pk_bf16_f32 v16, v16, v17
	v_cvt_pk_bf16_f32 v17, v18, v19
	global_store_dwordx2 v[110:111], v[16:17], off offset:288
	global_store_dwordx4 v[116:117], v[12:15], off offset:576 sc1
	s_nop 1
	v_cvt_pk_bf16_f32 v12, v12, v13
	v_cvt_pk_bf16_f32 v13, v14, v15
	global_store_dwordx2 v[102:103], v[12:13], off offset:288
	global_store_dwordx4 v[108:109], v[8:11], off offset:576 sc1
	s_nop 1
	v_cvt_pk_bf16_f32 v8, v8, v9
	v_cvt_pk_bf16_f32 v9, v10, v11
	global_store_dwordx2 v[90:91], v[8:9], off offset:288
	global_store_dwordx4 v[100:101], v[4:7], off offset:576 sc1
	s_nop 1
	v_cvt_pk_bf16_f32 v4, v4, v5
	v_cvt_pk_bf16_f32 v5, v6, v7
	global_store_dwordx2 v[86:87], v[4:5], off offset:288
	s_cbranch_vccnz .LBB0_1512
	s_and_b64 vcc, exec, s[36:37]
	s_cbranch_vccnz .LBB0_1511
	s_barrier
	s_branch .LBB0_1511

; __global__ void __launch_bounds__(NWAVES * 64, 2) mega(Args args) {
;     ...
;             for (int u = bx; u < DECB * 4; u += G) {
;                 const int b = u >> 2, hs = u & 3;
;                 __syncthreads();
;                 for (int j = wave; j < 12; j += NWAVES) {
;                     const int g = j >> 2, qi = j & 3;
;                     attn_tile<true>(Qb, Kb, Vb, args.in[2], args.in[3], args.in[4], l, otile + j * 128, lsel + g * 4 + qi, vl, b, g * 4 + hs, qi, 0, lane);
;                 }
.LBB0_1586:
	s_and_b32 s9, s8, 3
	s_andn2_b64 vcc, exec, s[26:27]
	s_waitcnt vmcnt(0)
	s_barrier
	s_cbranch_vccnz .LBB0_1708
	s_cmp_gt_u32 s86, 5
	s_cbranch_scc1 .LBB0_1708
	s_and_b32 s33, s86, 1
	s_and_b32 s0, s91, 1
	s_lshl_b32 s0, s0, 1
	s_or_b32 s33, s33, s0
	v_and_b32_e32 v1, 64, v219
	v_xor_b32_e32 v0, 16, v219
	v_add_u32_e32 v1, 64, v1
	s_and_b32 s1, s8, -4
	v_cmp_lt_i32_e32 vcc, v0, v1
	s_ashr_i32 s0, s8, 2
	s_ashr_i32 s4, s1, 31
	v_cndmask_b32_e32 v0, v219, v0, vcc
	s_add_u32 s6, s1, 0x4000
	v_lshlrev_b32_e32 v155, 2, v0
	v_xor_b32_e32 v0, 32, v219
	s_addc_u32 s7, s4, 0
	s_add_i32 s52, s0, s2
	v_cmp_lt_i32_e32 vcc, v0, v1
	s_or_b32 s0, s6, s33
	s_mul_i32 s4, s7, 0x600
	v_cndmask_b32_e32 v0, v219, v0, vcc
	v_mad_u64_u32 v[156:157], s[0:1], s0, v231, v[152:153]
	s_ashr_i32 s53, s52, 31
	v_lshlrev_b32_e32 v208, 2, v0
	v_add_u32_e32 v157, s4, v157
	s_nop 0
	s_lshr_b32 s21, s86, 1
	s_lshl_b32 s20, s21, 1
	s_lshl_b32 s21, s21, 2
	s_or_b32 s21, s21, s33
	s_sub_i32 s0, s21, s86
	s_lshl_b32 s0, s0, 7
	v_add_u32_e32 v209, s0, v204
	s_branch .LBB0_1589
.LBB0_1588:
	s_or_b64 exec, exec, s[54:55]
	s_add_i32 s0, s21, 8
	s_add_i32 s20, s20, 4
	v_add_u32_e32 v209, 0x400, v209
	s_cmp_ge_u32 s21, 0
	s_mov_b32 s21, s0
	s_cbranch_scc1 .LBB0_1708

; __device__ __forceinline__ unsigned pk2(float lo, float hi) { const f32x2_t v = {lo, hi}; const bf16x2_t b = __builtin_convertvector(v, bf16x2_t); return __builtin_bit_cast(unsigned, b); }
; template <bool SAMPLE> ...
;     ...
;     for (int kt = 0; kt < 9; ++kt) {
;         S[kt] = (f32x4){-1e30f, -1e30f, -1e30f, -1e30f};
;         if (kt >= kt0) {
;             bf16x8 k0, k1;
;             if (SAMPLE) {
;                 int j = 16 * kt + fr; j = j > 128 ? 128 : j;
;                 const int rr = npre + qi - (j << dsh);
;                 if (rr >= npre) { const bf16_t* kp = Kb + ((size_t)MP + b * 4 + (rr - npre)) * ATT + h * 64 + fq * 8; k0 = *(const bf16x8*)kp; k1 = *(const bf16x8*)(kp + 32); }
;                 else { const float* kp = cbase + (size_t)rr * 512 + hs * 64 + fq * 8;
;                     const f32x4 a0 = __builtin_nontemporal_load((const f32x4*)kp), a1 = __builtin_nontemporal_load((const f32x4*)(kp + 4)), a2 = __builtin_nontemporal_load((const f32x4*)(kp + 32)), a3 = __builtin_nontemporal_load((const f32x4*)(kp + 36));
;                     u32x4 w0, w1; w0.x = pk2(a0.x, a0.y); w0.y = pk2(a0.z, a0.w); w0.z = pk2(a1.x, a1.y); w0.w = pk2(a1.z, a1.w);
;                     w1.x = pk2(a2.x, a2.y); w1.y = pk2(a2.z, a2.w); w1.z = pk2(a3.x, a3.y); w1.w = pk2(a3.z, a3.w);
;                     k0 = __builtin_bit_cast(bf16x8, w0); k1 = __builtin_bit_cast(bf16x8, w1); }
;             } else {
;                 const int sk = s0 - 128 + 16 * kt + fr;
;                 const bf16_t* kp = Kb + ((size_t)b * SEQ + ((sk << dsh) + r)) * ATT + h * 64 + fq * 8;
;                 k0 = *(const bf16x8*)kp; k1 = *(const bf16x8*)(kp + 32);
;             }
;             f32x4 a = (f32x4){0.f, 0.f, 0.f, 0.f};
;             a = __builtin_amdgcn_mfma_f32_16x16x32_bf16(k0, q0, a, 0, 0, 0);
;             a = __builtin_amdgcn_mfma_f32_16x16x32_bf16(k1, q1, a, 0, 0, 0);
;             S[kt] = a;
;         }
.LBB0_1673:
	s_or_b64 exec, exec, s[50:51]
	v_lshrrev_b32_e32 v255, 2, v219
	v_and_b32_e32 v3, 15, v219
	v_sub_u32_e32 v255, v3, v255
	v_lshlrev_b32_e32 v255, s20, v255
	v_lshlrev_b32_e32 v255, 11, v255
	v_and_b32_e32 v3, 3, v219
	v_lshrrev_b32_e32 v168, 4, v219
	v_sub_u32_e32 v3, v3, v168
	v_lshl_add_u32 v168, v3, 5, v255
	v_ashrrev_i32_e32 v169, 31, v168
	v_lshl_add_u64 v[168:169], v[168:169], 0, v[158:159]
	v_and_b32_e32 v255, 15, v219
	v_lshrrev_b32_e32 v3, 4, v219
	v_lshl_add_u32 v255, v255, 2, v3
	v_lshlrev_b32_e32 v255, 2, v255
	v_lshlrev_b32_e32 v214, s20, v195
	v_sub_u32_e32 v214, s29, v214
	v_lshlrev_b32_e32 v214, 11, v214
	v_mov_b32_e32 v215, 0
	v_lshl_add_u64 v[214:215], v[214:215], 0, v[168:169]
	global_load_dwordx4 v[124:127], v[214:215], off nt
	global_load_dwordx4 v[128:131], v[214:215], off offset:16 nt
	global_load_dwordx4 v[210:213], v[214:215], off offset:128 nt
	global_load_dwordx4 v[214:217], v[214:215], off offset:144 nt
	v_lshlrev_b32_e32 v246, s20, v196
	v_sub_u32_e32 v246, s29, v246
	v_lshlrev_b32_e32 v246, 11, v246
	v_mov_b32_e32 v247, 0
	v_lshl_add_u64 v[246:247], v[246:247], 0, v[168:169]
	global_load_dwordx4 v[234:237], v[246:247], off nt
	global_load_dwordx4 v[238:241], v[246:247], off offset:16 nt
	global_load_dwordx4 v[242:245], v[246:247], off offset:128 nt
	global_load_dwordx4 v[246:249], v[246:247], off offset:144 nt
	s_waitcnt vmcnt(9)
	v_mfma_f32_16x16x32_bf16 v[92:95], v[92:95], v[20:23], 0
	s_waitcnt vmcnt(8)
	v_mfma_f32_16x16x32_bf16 v[92:95], v[96:99], v[16:19], v[92:95]
	s_waitcnt vmcnt(4)
	v_cvt_pk_bf16_f32 v124, v124, v125
	v_cvt_pk_bf16_f32 v125, v126, v127
	v_cvt_pk_bf16_f32 v126, v128, v129
	v_cvt_pk_bf16_f32 v127, v130, v131
	v_cvt_pk_bf16_f32 v210, v210, v211
	v_cvt_pk_bf16_f32 v211, v212, v213
	v_cvt_pk_bf16_f32 v212, v214, v215
	v_cvt_pk_bf16_f32 v213, v216, v217
	ds_bpermute_b32 v124, v255, v124
	ds_bpermute_b32 v125, v255, v125
	ds_bpermute_b32 v126, v255, v126
	ds_bpermute_b32 v127, v255, v127
	ds_bpermute_b32 v210, v255, v210
	ds_bpermute_b32 v211, v255, v211
	ds_bpermute_b32 v212, v255, v212
	ds_bpermute_b32 v213, v255, v213
	s_waitcnt lgkmcnt(0)
	v_mfma_f32_16x16x32_bf16 v[96:99], v[124:127], v[20:23], 0
	v_mfma_f32_16x16x32_bf16 v[96:99], v[210:213], v[16:19], v[96:99]
	v_lshlrev_b32_e32 v214, s20, v197
	v_sub_u32_e32 v214, s29, v214
	v_lshlrev_b32_e32 v214, 11, v214
	v_mov_b32_e32 v215, 0
	v_lshl_add_u64 v[214:215], v[214:215], 0, v[168:169]
	global_load_dwordx4 v[124:127], v[214:215], off nt
	global_load_dwordx4 v[128:131], v[214:215], off offset:16 nt
	global_load_dwordx4 v[210:213], v[214:215], off offset:128 nt
	global_load_dwordx4 v[214:217], v[214:215], off offset:144 nt
	s_waitcnt vmcnt(4)
	v_cvt_pk_bf16_f32 v234, v234, v235
	v_cvt_pk_bf16_f32 v235, v236, v237
	v_cvt_pk_bf16_f32 v236, v238, v239
	v_cvt_pk_bf16_f32 v237, v240, v241
	v_cvt_pk_bf16_f32 v242, v242, v243
	v_cvt_pk_bf16_f32 v243, v244, v245
	v_cvt_pk_bf16_f32 v244, v246, v247
	v_cvt_pk_bf16_f32 v245, v248, v249
	ds_bpermute_b32 v234, v255, v234
	ds_bpermute_b32 v235, v255, v235
	ds_bpermute_b32 v236, v255, v236
	ds_bpermute_b32 v237, v255, v237
	ds_bpermute_b32 v242, v255, v242
	ds_bpermute_b32 v243, v255, v243
	ds_bpermute_b32 v244, v255, v244
	ds_bpermute_b32 v245, v255, v245
	s_waitcnt lgkmcnt(0)
	v_mfma_f32_16x16x32_bf16 v[100:103], v[234:237], v[20:23], 0
	v_mfma_f32_16x16x32_bf16 v[100:103], v[242:245], v[16:19], v[100:103]
	v_lshlrev_b32_e32 v246, s20, v198
	v_sub_u32_e32 v246, s29, v246
	v_lshlrev_b32_e32 v246, 11, v246
	v_mov_b32_e32 v247, 0
	v_lshl_add_u64 v[246:247], v[246:247], 0, v[168:169]
	global_load_dwordx4 v[234:237], v[246:247], off nt
	global_load_dwordx4 v[238:241], v[246:247], off offset:16 nt
	global_load_dwordx4 v[242:245], v[246:247], off offset:128 nt
	global_load_dwordx4 v[246:249], v[246:247], off offset:144 nt
	s_waitcnt vmcnt(4)
	v_cvt_pk_bf16_f32 v124, v124, v125
	v_cvt_pk_bf16_f32 v125, v126, v127
	v_cvt_pk_bf16_f32 v126, v128, v129
	v_cvt_pk_bf16_f32 v127, v130, v131
	v_cvt_pk_bf16_f32 v210, v210, v211
	v_cvt_pk_bf16_f32 v211, v212, v213
	v_cvt_pk_bf16_f32 v212, v214, v215
	v_cvt_pk_bf16_f32 v213, v216, v217
	ds_bpermute_b32 v124, v255, v124
	ds_bpermute_b32 v125, v255, v125
	ds_bpermute_b32 v126, v255, v126
	ds_bpermute_b32 v127, v255, v127
	ds_bpermute_b32 v210, v255, v210
	ds_bpermute_b32 v211, v255, v211
	ds_bpermute_b32 v212, v255, v212
	ds_bpermute_b32 v213, v255, v213
	s_waitcnt lgkmcnt(0)
; __device__ __forceinline__ unsigned pk2(float lo, float hi) { const f32x2_t v = {lo, hi}; const bf16x2_t b = __builtin_convertvector(v, bf16x2_t); return __builtin_bit_cast(unsigned, b); }
; template <bool SAMPLE> ...
;     ...
;     for (int kt = 0; kt < 9; ++kt) {
;         S[kt] = (f32x4){-1e30f, -1e30f, -1e30f, -1e30f};
;         if (kt >= kt0) {
;             bf16x8 k0, k1;
;             if (SAMPLE) {
;                 int j = 16 * kt + fr; j = j > 128 ? 128 : j;
;                 const int rr = npre + qi - (j << dsh);
;                 if (rr >= npre) { const bf16_t* kp = Kb + ((size_t)MP + b * 4 + (rr - npre)) * ATT + h * 64 + fq * 8; k0 = *(const bf16x8*)kp; k1 = *(const bf16x8*)(kp + 32); }
;                 else { const float* kp = cbase + (size_t)rr * 512 + hs * 64 + fq * 8;
;                     const f32x4 a0 = __builtin_nontemporal_load((const f32x4*)kp), a1 = __builtin_nontemporal_load((const f32x4*)(kp + 4)), a2 = __builtin_nontemporal_load((const f32x4*)(kp + 32)), a3 = __builtin_nontemporal_load((const f32x4*)(kp + 36));
;                     u32x4 w0, w1; w0.x = pk2(a0.x, a0.y); w0.y = pk2(a0.z, a0.w); w0.z = pk2(a1.x, a1.y); w0.w = pk2(a1.z, a1.w);
;                     w1.x = pk2(a2.x, a2.y); w1.y = pk2(a2.z, a2.w); w1.z = pk2(a3.x, a3.y); w1.w = pk2(a3.z, a3.w);
;                     k0 = __builtin_bit_cast(bf16x8, w0); k1 = __builtin_bit_cast(bf16x8, w1); }
;             } else {
;                 const int sk = s0 - 128 + 16 * kt + fr;
;                 const bf16_t* kp = Kb + ((size_t)b * SEQ + ((sk << dsh) + r)) * ATT + h * 64 + fq * 8;
;                 k0 = *(const bf16x8*)kp; k1 = *(const bf16x8*)(kp + 32);
;             }
;             f32x4 a = (f32x4){0.f, 0.f, 0.f, 0.f};
;             a = __builtin_amdgcn_mfma_f32_16x16x32_bf16(k0, q0, a, 0, 0, 0);
;             a = __builtin_amdgcn_mfma_f32_16x16x32_bf16(k1, q1, a, 0, 0, 0);
;             S[kt] = a;
;         }
	v_mfma_f32_16x16x32_bf16 v[104:107], v[124:127], v[20:23], 0
	v_mfma_f32_16x16x32_bf16 v[104:107], v[210:213], v[16:19], v[104:107]
	v_lshlrev_b32_e32 v214, s20, v199
	v_sub_u32_e32 v214, s29, v214
	v_lshlrev_b32_e32 v214, 11, v214
	v_mov_b32_e32 v215, 0
	v_lshl_add_u64 v[214:215], v[214:215], 0, v[168:169]
	global_load_dwordx4 v[124:127], v[214:215], off nt
	global_load_dwordx4 v[128:131], v[214:215], off offset:16 nt
	global_load_dwordx4 v[210:213], v[214:215], off offset:128 nt
	global_load_dwordx4 v[214:217], v[214:215], off offset:144 nt
	s_waitcnt vmcnt(4)
	v_cvt_pk_bf16_f32 v234, v234, v235
	v_cvt_pk_bf16_f32 v235, v236, v237
	v_cvt_pk_bf16_f32 v236, v238, v239
	v_cvt_pk_bf16_f32 v237, v240, v241
	v_cvt_pk_bf16_f32 v242, v242, v243
	v_cvt_pk_bf16_f32 v243, v244, v245
	v_cvt_pk_bf16_f32 v244, v246, v247
	v_cvt_pk_bf16_f32 v245, v248, v249
	ds_bpermute_b32 v234, v255, v234
	ds_bpermute_b32 v235, v255, v235
	ds_bpermute_b32 v236, v255, v236
	ds_bpermute_b32 v237, v255, v237
	ds_bpermute_b32 v242, v255, v242
	ds_bpermute_b32 v243, v255, v243
	ds_bpermute_b32 v244, v255, v244
	ds_bpermute_b32 v245, v255, v245
	s_waitcnt lgkmcnt(0)
	v_mfma_f32_16x16x32_bf16 v[108:111], v[234:237], v[20:23], 0
	v_mfma_f32_16x16x32_bf16 v[108:111], v[242:245], v[16:19], v[108:111]
	v_lshlrev_b32_e32 v246, s20, v200
	v_sub_u32_e32 v246, s29, v246
	v_lshlrev_b32_e32 v246, 11, v246
	v_mov_b32_e32 v247, 0
	v_lshl_add_u64 v[246:247], v[246:247], 0, v[168:169]
	global_load_dwordx4 v[234:237], v[246:247], off nt
	global_load_dwordx4 v[238:241], v[246:247], off offset:16 nt
	global_load_dwordx4 v[242:245], v[246:247], off offset:128 nt
	global_load_dwordx4 v[246:249], v[246:247], off offset:144 nt
	s_waitcnt vmcnt(4)
	v_cvt_pk_bf16_f32 v124, v124, v125
	v_cvt_pk_bf16_f32 v125, v126, v127
	v_cvt_pk_bf16_f32 v126, v128, v129
	v_cvt_pk_bf16_f32 v127, v130, v131
	v_cvt_pk_bf16_f32 v210, v210, v211
	v_cvt_pk_bf16_f32 v211, v212, v213
	v_cvt_pk_bf16_f32 v212, v214, v215
	v_cvt_pk_bf16_f32 v213, v216, v217
	ds_bpermute_b32 v124, v255, v124
	ds_bpermute_b32 v125, v255, v125
	ds_bpermute_b32 v126, v255, v126
	ds_bpermute_b32 v127, v255, v127
	ds_bpermute_b32 v210, v255, v210
	ds_bpermute_b32 v211, v255, v211
	ds_bpermute_b32 v212, v255, v212
	ds_bpermute_b32 v213, v255, v213
	s_waitcnt lgkmcnt(0)
	v_mfma_f32_16x16x32_bf16 v[120:123], v[124:127], v[20:23], 0
	v_mfma_f32_16x16x32_bf16 v[120:123], v[210:213], v[16:19], v[120:123]
	v_lshlrev_b32_e32 v214, s20, v201
	v_sub_u32_e32 v214, s29, v214
	v_lshlrev_b32_e32 v214, 11, v214
	v_mov_b32_e32 v215, 0
	v_lshl_add_u64 v[214:215], v[214:215], 0, v[168:169]
	global_load_dwordx4 v[124:127], v[214:215], off nt
	global_load_dwordx4 v[128:131], v[214:215], off offset:16 nt
	global_load_dwordx4 v[210:213], v[214:215], off offset:128 nt
	global_load_dwordx4 v[214:217], v[214:215], off offset:144 nt
	s_waitcnt vmcnt(4)
	v_cvt_pk_bf16_f32 v234, v234, v235
	v_cvt_pk_bf16_f32 v235, v236, v237
	v_cvt_pk_bf16_f32 v236, v238, v239
	v_cvt_pk_bf16_f32 v237, v240, v241
	v_cvt_pk_bf16_f32 v242, v242, v243
	v_cvt_pk_bf16_f32 v243, v244, v245
	v_cvt_pk_bf16_f32 v244, v246, v247
	v_cvt_pk_bf16_f32 v245, v248, v249
	ds_bpermute_b32 v234, v255, v234
	ds_bpermute_b32 v235, v255, v235
	ds_bpermute_b32 v236, v255, v236
	ds_bpermute_b32 v237, v255, v237
	ds_bpermute_b32 v242, v255, v242
	ds_bpermute_b32 v243, v255, v243
	ds_bpermute_b32 v244, v255, v244
	ds_bpermute_b32 v245, v255, v245
	s_waitcnt lgkmcnt(0)
	v_mfma_f32_16x16x32_bf16 v[112:115], v[234:237], v[20:23], 0
	v_mfma_f32_16x16x32_bf16 v[112:115], v[242:245], v[16:19], v[112:115]
	s_waitcnt vmcnt(0)
	v_cvt_pk_bf16_f32 v124, v124, v125
	v_cvt_pk_bf16_f32 v125, v126, v127
	v_cvt_pk_bf16_f32 v126, v128, v129
	v_cvt_pk_bf16_f32 v127, v130, v131
	v_cvt_pk_bf16_f32 v210, v210, v211
	v_cvt_pk_bf16_f32 v211, v212, v213
	v_cvt_pk_bf16_f32 v212, v214, v215
	v_cvt_pk_bf16_f32 v213, v216, v217
	ds_bpermute_b32 v124, v255, v124
	ds_bpermute_b32 v125, v255, v125
	ds_bpermute_b32 v126, v255, v126
	ds_bpermute_b32 v127, v255, v127
	ds_bpermute_b32 v210, v255, v210
	ds_bpermute_b32 v211, v255, v211
	ds_bpermute_b32 v212, v255, v212
	ds_bpermute_b32 v213, v255, v213
	s_waitcnt lgkmcnt(0)
	v_mfma_f32_16x16x32_bf16 v[116:119], v[124:127], v[20:23], 0
	v_mfma_f32_16x16x32_bf16 v[116:119], v[210:213], v[16:19], v[116:119]
	s_lshl_b32 s0, 0xffffff80, s20
	s_add_i32 s0, s29, s0
	s_mov_b64 s[10:11], -1
	s_cmp_lt_i32 s0, s23
	s_cbranch_scc1 .LBB0_1703
	s_sub_i32 s1, s0, s23
	s_add_u32 s1, s6, s1
	s_addc_u32 s4, s7, 0
	s_mulk_i32 s4, 0x600
	v_mad_u64_u32 v[0:1], s[10:11], s1, v231, v[0:1]
	v_add_u32_e32 v1, s4, v1
	global_load_dwordx4 v[128:131], v[0:1], off
	global_load_dwordx4 v[124:127], v[0:1], off offset:64
	s_mov_b64 s[10:11], 0

; #define LAS __attribute__((address_space(3)))
; __device__ __forceinline__ unsigned pk2(float lo, float hi) { const f32x2_t v = {lo, hi}; const bf16x2_t b = __builtin_convertvector(v, bf16x2_t); return __builtin_bit_cast(unsigned, b); }
; template <bool SAMPLE> ...
;     ...
;     if (SAMPLE) {
; #pragma unroll
;         for (int j = 0; j < 4; ++j) if (4 * fq + j > 0) S[8][j] = -1e30f;
;     } else {
; #pragma unroll
;         for (int j = 0; j < 4; ++j) { if (4 * fq + j < fr) S[0][j] = -1e30f; if (4 * fq + j > fr) S[8][j] = -1e30f; }
;     }
;     float m = -1e30f;
; #pragma unroll
;     for (int kt = 0; kt < 9; ++kt) m = fmaxf(m, fmaxf(fmaxf(S[kt].x, S[kt].y), fmaxf(S[kt].z, S[kt].w)));
;     m = fmaxf(m, __shfl_xor(m, 16)); m = fmaxf(m, __shfl_xor(m, 32));
;     float den = 0.f;
; #pragma unroll
;     for (int kt = 0; kt < 9; ++kt) { S[kt].x = __builtin_amdgcn_exp2f(S[kt].x - m); S[kt].y = __builtin_amdgcn_exp2f(S[kt].y - m); S[kt].z = __builtin_amdgcn_exp2f(S[kt].z - m); S[kt].w = __builtin_amdgcn_exp2f(S[kt].w - m); den += (S[kt].x + S[kt].y) + (S[kt].z + S[kt].w); }
;     den += __shfl_xor(den, 16); den += __shfl_xor(den, 32);
;     f32x4 O[4];
; #pragma unroll
;     for (int n = 0; n < 4; ++n) O[n] = (f32x4){0.f, 0.f, 0.f, 0.f};
;     const LAS unsigned char* trp = vl + (4 * fq + (fr >> 2)) * 160 + (lane & 3) * 8;
; #pragma unroll
;     for (int kk = 0; kk < 5; ++kk) {
;         if (2 * kk + 1 >= kt0) {
; #pragma unroll
;             for (int it = 0; it < 4; ++it) *(LAS u32x4*)(vl + ((lane >> 3) + 8 * it) * 160 + (lane & 7) * 16) = vr[kk][it];
;             LDS_WAIT();
;             u32x4 pw; pw.x = pk2(S[2 * kk].x, S[2 * kk].y); pw.y = pk2(S[2 * kk].z, S[2 * kk].w);
;             if (kk < 4) { pw.z = pk2(S[(2 * kk + 1) % 9].x, S[(2 * kk + 1) % 9].y); pw.w = pk2(S[(2 * kk + 1) % 9].z, S[(2 * kk + 1) % 9].w); } else { pw.z = 0u; pw.w = 0u; }
;             const bf16x8 pb = __builtin_bit_cast(bf16x8, pw);
; #pragma unroll
;             for (int n = 0; n < 4; ++n) {
;                 const s16x4 lo = vtr(trp + n * 32), hi = vtr(trp + 16 * 160 + n * 32);
;                 bf16x8 va; va[0] = lo[0]; va[1] = lo[1]; va[2] = lo[2]; va[3] = lo[3]; va[4] = hi[0]; va[5] = hi[1]; va[6] = hi[2]; va[7] = hi[3];
;                 O[n] = __builtin_amdgcn_mfma_f32_16x16x32_bf16(va, pb, O[n], 0, 0, 0);
;             }
;             LDS_WAIT();
;         }
;     }
.LBB0_1705:
	s_waitcnt vmcnt(1)
	v_mfma_f32_16x16x32_bf16 v[20:23], v[128:131], v[20:23], 0
	v_max_f32_e32 v0, v93, v93
	v_max_f32_e32 v1, v92, v92
	v_max_f32_e32 v0, v1, v0
	s_waitcnt vmcnt(0)
	v_mfma_f32_16x16x32_bf16 v[16:19], v[124:127], v[16:19], v[20:23]
	ds_write_b128 v205, v[4:7]
	ds_write_b128 v205, v[8:11] offset:1280
	ds_write_b128 v205, v[12:15] offset:2560
	ds_write_b128 v205, v[24:27] offset:3840
	s_waitcnt lgkmcnt(0)
	ds_read_b64_tr_b16 v[10:11], v206 offset:2560
	ds_read_b64_tr_b16 v[8:9], v206
	s_nop 1
	v_cndmask_b32_e64 v1, v16, v232, s[38:39]
	v_cndmask_b32_e64 v3, v232, v17, s[40:41]
	v_cndmask_b32_e64 v1, v1, v16, s[40:41]
	v_max_f32_e32 v16, v95, v95
	v_max_f32_e32 v17, v94, v94
	v_max_f32_e32 v16, v17, v16
	v_max3_f32 v0, v0, v16, s31
	v_max_f32_e32 v16, v99, v99
	v_max_f32_e32 v17, v98, v98
	v_cndmask_b32_e64 v21, v232, v18, s[40:41]
	v_max_f32_e32 v16, v17, v16
	v_max_f32_e32 v17, v103, v103
	v_max_f32_e32 v18, v102, v102
	v_max_f32_e32 v17, v18, v17
	v_max3_f32 v16, v96, v97, v16
	v_max3_f32 v17, v100, v101, v17
	v_max3_f32 v0, v0, v16, v17
	v_max_f32_e32 v16, v107, v107
	v_max_f32_e32 v17, v106, v106
	v_max_f32_e32 v16, v17, v16
	v_max_f32_e32 v17, v111, v111
	v_max_f32_e32 v18, v110, v110
	v_max_f32_e32 v17, v18, v17
	v_max3_f32 v16, v104, v105, v16
	v_max3_f32 v17, v108, v109, v17
	v_max3_f32 v0, v0, v16, v17
	v_max_f32_e32 v16, v123, v123
	v_max_f32_e32 v17, v122, v122
	v_max_f32_e32 v16, v17, v16
	v_max_f32_e32 v17, v115, v115
	v_max_f32_e32 v18, v114, v114
	v_max_f32_e32 v17, v18, v17
	v_max3_f32 v16, v120, v121, v16
	v_max3_f32 v17, v112, v113, v17
	v_cndmask_b32_e64 v124, v232, v19, s[40:41]
	v_max3_f32 v0, v0, v16, v17
	v_max_f32_e32 v16, v119, v119
	v_max_f32_e32 v17, v118, v118
	v_max_f32_e32 v16, v17, v16
	v_max_f32_e32 v17, v124, v124
	v_max_f32_e32 v18, v21, v21
	v_max_f32_e32 v17, v18, v17
	v_max3_f32 v16, v116, v117, v16
	v_max3_f32 v17, v1, v3, v17
	v_max3_f32 v0, v0, v16, v17
	ds_bpermute_b32 v16, v155, v0
	s_waitcnt lgkmcnt(0)
	v_max_f32_e32 v16, v16, v16
	v_max_f32_e32 v0, v0, v16
	ds_bpermute_b32 v16, v208, v0
	s_waitcnt lgkmcnt(0)
	v_max_f32_e32 v16, v16, v16
	v_max_f32_e32 v20, v0, v16
	v_sub_f32_e32 v0, v92, v20
	v_sub_f32_e32 v16, v93, v20
	v_sub_f32_e32 v17, v94, v20
	v_sub_f32_e32 v18, v95, v20
	v_exp_f32_e32 v0, v0
	v_exp_f32_e32 v16, v16
	v_exp_f32_e32 v17, v17
	v_exp_f32_e32 v18, v18
	v_sub_f32_e32 v23, v96, v20
	v_sub_f32_e32 v92, v97, v20
	v_sub_f32_e32 v93, v98, v20
	v_sub_f32_e32 v94, v99, v20
	v_exp_f32_e32 v23, v23
	v_exp_f32_e32 v92, v92
	v_exp_f32_e32 v93, v93
	v_exp_f32_e32 v94, v94
	v_sub_f32_e32 v96, v100, v20
	v_sub_f32_e32 v97, v101, v20
	v_sub_f32_e32 v98, v102, v20
	v_sub_f32_e32 v99, v103, v20
	v_exp_f32_e32 v96, v96
	v_exp_f32_e32 v97, v97
	v_exp_f32_e32 v98, v98
	v_exp_f32_e32 v99, v99
	v_add_f32_e32 v19, v0, v16
	v_add_f32_e32 v22, v17, v18
	v_sub_f32_e32 v100, v104, v20
	v_sub_f32_e32 v101, v105, v20
	v_sub_f32_e32 v102, v106, v20
	v_sub_f32_e32 v103, v107, v20
	v_add_f32_e32 v19, v19, v22
	v_add_f32_e32 v22, v23, v92
	v_add_f32_e32 v95, v93, v94
	v_exp_f32_e32 v100, v100
	v_exp_f32_e32 v101, v101
	v_exp_f32_e32 v102, v102
	v_exp_f32_e32 v103, v103
	v_add_f32_e32 v19, 0, v19
	v_add_f32_e32 v22, v22, v95
	v_sub_f32_e32 v104, v108, v20
	v_sub_f32_e32 v105, v109, v20
	v_sub_f32_e32 v106, v110, v20
	v_sub_f32_e32 v107, v111, v20
	v_add_f32_e32 v19, v22, v19
	v_add_f32_e32 v22, v96, v97
	v_add_f32_e32 v95, v98, v99
	v_exp_f32_e32 v104, v104
	v_exp_f32_e32 v105, v105
	v_exp_f32_e32 v106, v106
	v_exp_f32_e32 v107, v107
	v_add_f32_e32 v22, v22, v95
	v_add_f32_e32 v19, v22, v19
	v_add_f32_e32 v22, v100, v101
	v_add_f32_e32 v95, v102, v103
	v_add_f32_e32 v22, v22, v95
	v_add_f32_e32 v95, v22, v19
	v_add_f32_e32 v19, v104, v105
	v_add_f32_e32 v22, v106, v107
	v_add_f32_e32 v108, v19, v22
	v_sub_f32_e32 v19, v120, v20
	v_exp_f32_e32 v109, v19
	v_sub_f32_e32 v19, v121, v20
	v_exp_f32_e32 v110, v19
	v_sub_f32_e32 v19, v122, v20
	v_sub_f32_e32 v120, v123, v20
	v_exp_f32_e32 v111, v19
	v_cvt_pk_bf16_f32 v4, v0, v16
	v_exp_f32_e32 v0, v120
	v_add_f32_e32 v26, v109, v110
	v_cvt_pk_bf16_f32 v5, v17, v18
	v_cvt_pk_bf16_f32 v6, v23, v92
	v_add_f32_e32 v27, v111, v0
	v_cvt_pk_bf16_f32 v7, v93, v94
	ds_read_b64_tr_b16 v[14:15], v206 offset:2592
	ds_read_b64_tr_b16 v[12:13], v206 offset:32
	ds_read_b64_tr_b16 v[16:17], v206 offset:64
	ds_read_b64_tr_b16 v[22:23], v206 offset:96
	ds_read_b64_tr_b16 v[18:19], v206 offset:2624
	ds_read_b64_tr_b16 v[24:25], v206 offset:2656
	v_add_f32_e32 v93, v26, v27
	v_sub_f32_e32 v26, v112, v20
	s_waitcnt lgkmcnt(0)
	ds_write_b128 v205, v[28:31]
	ds_write_b128 v205, v[32:35] offset:1280
	ds_write_b128 v205, v[36:39] offset:2560
	ds_write_b128 v205, v[40:43] offset:3840
	v_exp_f32_e32 v94, v26
	v_sub_f32_e32 v26, v113, v20
	s_waitcnt lgkmcnt(0)
	v_add_f32_e32 v92, v108, v95
	v_exp_f32_e32 v95, v26
	ds_read_b64_tr_b16 v[28:29], v206 offset:2560
	ds_read_b64_tr_b16 v[26:27], v206
	v_mfma_f32_16x16x32_bf16 v[8:11], v[8:11], v[4:7], 0
	ds_read_b64_tr_b16 v[32:33], v206 offset:2592
	ds_read_b64_tr_b16 v[30:31], v206 offset:32
	ds_read_b64_tr_b16 v[34:35], v206 offset:64
	ds_read_b64_tr_b16 v[38:39], v206 offset:96
	ds_read_b64_tr_b16 v[36:37], v206 offset:2624
	ds_read_b64_tr_b16 v[40:41], v206 offset:2656
	s_waitcnt lgkmcnt(0)
	ds_write_b128 v205, v[44:47]
	ds_write_b128 v205, v[48:51] offset:1280
	ds_write_b128 v205, v[52:55] offset:2560
	ds_write_b128 v205, v[56:59] offset:3840
	s_waitcnt lgkmcnt(14)
	v_mfma_f32_16x16x32_bf16 v[12:15], v[12:15], v[4:7], 0
	s_waitcnt lgkmcnt(0)
; #define LAS __attribute__((address_space(3)))
; __device__ __forceinline__ unsigned pk2(float lo, float hi) { const f32x2_t v = {lo, hi}; const bf16x2_t b = __builtin_convertvector(v, bf16x2_t); return __builtin_bit_cast(unsigned, b); }
; __device__ __forceinline__ u32x2 pk4(f32x4 v) { u32x2 r; r.x = pk2(v.x, v.y); r.y = pk2(v.z, v.w); return r; }
; #define LDS_WAIT() asm volatile("s_waitcnt lgkmcnt(0)" ::: "memory")
; template <bool SAMPLE> ...
;     ...
;     for (int kk = 0; kk < 5; ++kk) {
;         if (2 * kk + 1 >= kt0) {
; #pragma unroll
;             for (int it = 0; it < 4; ++it) *(LAS u32x4*)(vl + ((lane >> 3) + 8 * it) * 160 + (lane & 7) * 16) = vr[kk][it];
;             LDS_WAIT();
;             u32x4 pw; pw.x = pk2(S[2 * kk].x, S[2 * kk].y); pw.y = pk2(S[2 * kk].z, S[2 * kk].w);
;             if (kk < 4) { pw.z = pk2(S[(2 * kk + 1) % 9].x, S[(2 * kk + 1) % 9].y); pw.w = pk2(S[(2 * kk + 1) % 9].z, S[(2 * kk + 1) % 9].w); } else { pw.z = 0u; pw.w = 0u; }
;             const bf16x8 pb = __builtin_bit_cast(bf16x8, pw);
; #pragma unroll
;             for (int n = 0; n < 4; ++n) {
;                 const s16x4 lo = vtr(trp + n * 32), hi = vtr(trp + 16 * 160 + n * 32);
;                 bf16x8 va; va[0] = lo[0]; va[1] = lo[1]; va[2] = lo[2]; va[3] = lo[3]; va[4] = hi[0]; va[5] = hi[1]; va[6] = hi[2]; va[7] = hi[3];
;                 O[n] = __builtin_amdgcn_mfma_f32_16x16x32_bf16(va, pb, O[n], 0, 0, 0);
;             }
;             LDS_WAIT();
;         }
;     }
;     const float inv = __builtin_amdgcn_rcpf(den);
;     if (!SAMPLE || fr == 0) {
; #pragma unroll
;         for (int n = 0; n < 4; ++n) *(LAS u32x2*)(orow + 32 * n + 8 * fq) = pk4(O[n] * inv);
;         if (fq == 0) *lsep = m * LN2 + __logf(den);
;     }
	v_mfma_f32_16x16x32_bf16 v[16:19], v[16:19], v[4:7], 0
	v_mfma_f32_16x16x32_bf16 v[4:7], v[22:25], v[4:7], 0
	v_cvt_pk_bf16_f32 v22, v96, v97
	v_cvt_pk_bf16_f32 v23, v98, v99
	v_cvt_pk_bf16_f32 v24, v100, v101
	v_cvt_pk_bf16_f32 v25, v102, v103
	s_waitcnt lgkmcnt(10)
	s_nop 0
	v_mfma_f32_16x16x32_bf16 v[8:11], v[26:29], v[22:25], v[8:11]
	v_sub_f32_e32 v26, v114, v20
	v_exp_f32_e32 v42, v26
	v_sub_f32_e32 v26, v115, v20
	v_exp_f32_e32 v43, v26
	v_add_f32_e32 v27, v94, v95
	v_add_f32_e32 v26, v93, v92
	s_waitcnt lgkmcnt(8)
	v_mfma_f32_16x16x32_bf16 v[12:15], v[30:33], v[22:25], v[12:15]
	v_add_f32_e32 v28, v42, v43
	v_add_f32_e32 v27, v27, v28
	v_add_f32_e32 v92, v27, v26
	ds_read_b64_tr_b16 v[28:29], v206 offset:2560
	ds_read_b64_tr_b16 v[26:27], v206
	s_waitcnt lgkmcnt(7)
	v_mfma_f32_16x16x32_bf16 v[16:19], v[34:37], v[22:25], v[16:19]
	s_waitcnt lgkmcnt(6)
	v_mfma_f32_16x16x32_bf16 v[4:7], v[38:41], v[22:25], v[4:7]
	v_cvt_pk_bf16_f32 v22, v104, v105
	v_cvt_pk_bf16_f32 v23, v106, v107
	v_cvt_pk_bf16_f32 v24, v109, v110
	v_cvt_pk_bf16_f32 v25, v111, v0
	ds_read_b64_tr_b16 v[32:33], v206 offset:2592
	ds_read_b64_tr_b16 v[30:31], v206 offset:32
	ds_read_b64_tr_b16 v[34:35], v206 offset:64
	ds_read_b64_tr_b16 v[38:39], v206 offset:96
	ds_read_b64_tr_b16 v[36:37], v206 offset:2624
	ds_read_b64_tr_b16 v[40:41], v206 offset:2656
	s_waitcnt lgkmcnt(6)
	v_mfma_f32_16x16x32_bf16 v[8:11], v[26:29], v[22:25], v[8:11]
	v_sub_f32_e32 v0, v116, v20
	v_sub_f32_e32 v26, v117, v20
	v_exp_f32_e32 v0, v0
	s_waitcnt lgkmcnt(4)
	v_mfma_f32_16x16x32_bf16 v[12:15], v[30:33], v[22:25], v[12:15]
	v_exp_f32_e32 v30, v26
	v_sub_f32_e32 v26, v118, v20
	v_exp_f32_e32 v44, v26
	v_sub_f32_e32 v26, v119, v20
	s_waitcnt lgkmcnt(0)
	ds_write_b128 v205, v[60:63]
	ds_write_b128 v205, v[64:67] offset:1280
	ds_write_b128 v205, v[68:71] offset:2560
	ds_write_b128 v205, v[72:75] offset:3840
	v_exp_f32_e32 v45, v26
	s_waitcnt lgkmcnt(0)
	s_waitcnt lgkmcnt(5)
	v_mfma_f32_16x16x32_bf16 v[16:19], v[34:37], v[22:25], v[16:19]
	v_add_f32_e32 v46, v0, v30
	ds_read_b64_tr_b16 v[28:29], v206 offset:2560
	ds_read_b64_tr_b16 v[26:27], v206
	s_waitcnt lgkmcnt(6)
	v_mfma_f32_16x16x32_bf16 v[4:7], v[38:41], v[22:25], v[4:7]
	v_cvt_pk_bf16_f32 v24, v0, v30
	ds_read_b64_tr_b16 v[32:33], v206 offset:2592
	ds_read_b64_tr_b16 v[30:31], v206 offset:32
	ds_read_b64_tr_b16 v[34:35], v206 offset:64
	ds_read_b64_tr_b16 v[38:39], v206 offset:96
	ds_read_b64_tr_b16 v[36:37], v206 offset:2624
	ds_read_b64_tr_b16 v[40:41], v206 offset:2656
	v_sub_f32_e32 v0, v1, v20
	v_cvt_pk_bf16_f32 v23, v42, v43
	v_exp_f32_e32 v43, v0
	v_sub_f32_e32 v0, v3, v20
	v_cvt_pk_bf16_f32 v25, v44, v45
	v_add_f32_e32 v42, v44, v45
	v_exp_f32_e32 v44, v0
	v_sub_f32_e32 v0, v21, v20
	s_waitcnt lgkmcnt(0)
	ds_write_b128 v205, v[76:79]
	ds_write_b128 v205, v[80:83] offset:1280
	ds_write_b128 v205, v[84:87] offset:2560
	ds_write_b128 v205, v[88:91] offset:3840
	v_cvt_pk_bf16_f32 v22, v94, v95
	v_exp_f32_e32 v21, v0
	v_sub_f32_e32 v0, v124, v20
	s_waitcnt lgkmcnt(0)
	s_waitcnt lgkmcnt(8)
	v_mfma_f32_16x16x32_bf16 v[12:15], v[30:33], v[22:25], v[12:15]
	v_exp_f32_e32 v45, v0
	v_cvt_pk_bf16_f32 v0, v43, v44
	v_mov_b32_e32 v3, v2
	s_waitcnt lgkmcnt(4)
	v_mfma_f32_16x16x32_bf16 v[30:33], v[38:41], v[22:25], v[4:7]
	s_nop 2
	ds_read_b64_tr_b16 v[6:7], v206 offset:2560
	ds_read_b64_tr_b16 v[4:5], v206
	v_cvt_pk_bf16_f32 v1, v21, v45
	v_mfma_f32_16x16x32_bf16 v[8:11], v[26:29], v[22:25], v[8:11]
	v_mfma_f32_16x16x32_bf16 v[26:29], v[34:37], v[22:25], v[16:19]
	ds_read_b64_tr_b16 v[24:25], v206 offset:2592
	ds_read_b64_tr_b16 v[22:23], v206 offset:32
	ds_read_b64_tr_b16 v[34:35], v206 offset:64
	ds_read_b64_tr_b16 v[38:39], v206 offset:96
	ds_read_b64_tr_b16 v[36:37], v206 offset:2624
	ds_read_b64_tr_b16 v[40:41], v206 offset:2656
	s_waitcnt lgkmcnt(0)
	s_waitcnt lgkmcnt(6)
	v_mfma_f32_16x16x32_bf16 v[16:19], v[4:7], v[0:3], v[8:11]
	v_add_f32_e32 v4, v46, v42
	v_add_f32_e32 v5, v43, v44
	v_add_f32_e32 v6, v21, v45
	v_add_f32_e32 v4, v4, v92
	v_add_f32_e32 v5, v5, v6
	v_add_f32_e32 v8, v5, v4
	ds_bpermute_b32 v9, v155, v8
	s_waitcnt lgkmcnt(5)
	v_mfma_f32_16x16x32_bf16 v[12:15], v[22:25], v[0:3], v[12:15]
	s_waitcnt lgkmcnt(0)
	v_add_f32_e32 v21, v8, v9
	ds_bpermute_b32 v22, v208, v21
	v_mfma_f32_16x16x32_bf16 v[4:7], v[34:37], v[0:3], v[26:29]
	v_mfma_f32_16x16x32_bf16 v[8:11], v[38:41], v[0:3], v[30:33]
	s_and_saveexec_b64 s[54:55], s[42:43]
	s_cbranch_execz .LBB0_1588
	s_waitcnt lgkmcnt(0)
	v_add_f32_e32 v0, v21, v22
	v_rcp_f32_e32 v22, v0
	s_nop 1
	v_pk_mul_f32 v[6:7], v[22:23], v[6:7] op_sel_hi:[0,1]
	v_pk_mul_f32 v[4:5], v[22:23], v[4:5] op_sel_hi:[0,1]
	v_pk_mul_f32 v[18:19], v[22:23], v[18:19] op_sel_hi:[0,1]
	v_pk_mul_f32 v[16:17], v[22:23], v[16:17] op_sel_hi:[0,1]
	v_pk_mul_f32 v[14:15], v[22:23], v[14:15] op_sel_hi:[0,1]
	v_pk_mul_f32 v[12:13], v[22:23], v[12:13] op_sel_hi:[0,1]
	v_cvt_pk_bf16_f32 v4, v4, v5
	v_cvt_pk_bf16_f32 v5, v6, v7
	v_pk_mul_f32 v[6:7], v[22:23], v[10:11] op_sel_hi:[0,1]
	v_pk_mul_f32 v[8:9], v[22:23], v[8:9] op_sel_hi:[0,1]
	v_cvt_pk_bf16_f32 v16, v16, v17
	v_cvt_pk_bf16_f32 v17, v18, v19
	v_cvt_pk_bf16_f32 v12, v12, v13
	v_cvt_pk_bf16_f32 v13, v14, v15
	v_cvt_pk_bf16_f32 v8, v8, v9
	v_cvt_pk_bf16_f32 v9, v6, v7
	ds_write2_b64 v209, v[16:17], v[12:13] offset1:4
	ds_write2_b64 v209, v[4:5], v[8:9] offset0:8 offset1:12
	s_and_b64 exec, exec, s[36:37]
	s_cbranch_execz .LBB0_1588
	s_mov_b32 s0, 0x800000
	v_cmp_gt_f32_e32 vcc, s0, v0
	s_lshl_b32 s0, s22, 2
	s_lshl_b32 s1, s33, 2
	s_add_i32 s1, s1, 0x22000
	v_cndmask_b32_e64 v1, 0, 32, vcc
	v_ldexp_f32 v0, v0, v1
	v_log_f32_e32 v0, v0
	s_add_i32 s0, s1, s0
	s_mov_b32 s1, 0x3f317217
	v_mul_f32_e32 v1, 0x3f317217, v0
	v_fma_f32 v1, v0, s1, -v1
	v_fmac_f32_e32 v1, 0x3377d1cf, v0
	s_mov_b32 s1, 0x7f800000
	v_fmac_f32_e32 v1, 0x3f317217, v0
	v_cmp_lt_f32_e64 s[50:51], |v0|, s1
	s_nop 1
	v_cndmask_b32_e64 v0, v0, v1, s[50:51]
	v_cndmask_b32_e32 v1, 0, v233, vcc
	v_sub_f32_e32 v0, v0, v1
	v_fmac_f32_e32 v0, 0x3f317218, v20
	v_mov_b32_e32 v1, s0
	ds_write_b32 v1, v0
	s_branch .LBB0_1588
; #define LAS __attribute__((address_space(3)))
; __device__ __forceinline__ unsigned pk2(float lo, float hi) { const f32x2_t v = {lo, hi}; const bf16x2_t b = __builtin_convertvector(v, bf16x2_t); return __builtin_bit_cast(unsigned, b); }
; __global__ void __launch_bounds__(NWAVES * 64, 2) mega(Args args) {
;     ...
;                 if (tid < 96) {
;                     const int j = tid >> 3, seg = tid & 7, g = j >> 2, qi = j & 3;
;                     const float l0 = lsel[qi], l1 = lsel[4 + qi], l2 = lsel[8 + qi], mx = fmaxf(l0, fmaxf(l1, l2));
;                     const float e0 = __expf(l0 - mx), e1 = __expf(l1 - mx), e2 = __expf(l2 - mx);
;                     const float w = (g == 0 ? e0 : (g == 1 ? e1 : e2)) * __builtin_amdgcn_rcpf(e0 + e1 + e2);
;                     const u32x4 v = *(const LAS u32x4*)(otile + j * 128 + seg * 16);
;                     u32x4 o; o.x = pk2(bflo(v.x) * w, bfhi(v.x) * w); o.y = pk2(bflo(v.y) * w, bfhi(v.y) * w); o.z = pk2(bflo(v.z) * w, bfhi(v.z) * w); o.w = pk2(bflo(v.w) * w, bfhi(v.w) * w);
;                     *(u32x4*)(CAT + ((size_t)MP + b * 4 + qi) * DM + (g * 4 + hs) * 64 + seg * 8) = o;
;                 }
.LBB0_1708:
	s_and_b32 s33, s86, 3
	s_waitcnt lgkmcnt(0)
	s_barrier
	s_and_saveexec_b64 s[6:7], s[44:45]
	s_cbranch_execz .LBB0_1585
	ds_read2_b32 v[0:1], v202 offset1:4
	ds_read_b32 v3, v202 offset:32
	ds_read_b128 v[4:7], v207 offset:40960
	s_and_b32 s0, s8, -4
	s_ashr_i32 s1, s0, 31
	v_mov_b32_e32 v155, v2
	s_waitcnt lgkmcnt(1)
	v_max3_f32 v8, v0, v1, v3
	v_sub_f32_e32 v0, v0, v8
	v_sub_f32_e32 v1, v1, v8
	v_mul_f32_e32 v0, 0x3fb8aa3b, v0
	v_mul_f32_e32 v1, 0x3fb8aa3b, v1
	v_sub_f32_e32 v3, v3, v8
	v_exp_f32_e32 v0, v0
	v_exp_f32_e32 v1, v1
	v_mul_f32_e32 v3, 0x3fb8aa3b, v3
	v_exp_f32_e32 v3, v3
	s_waitcnt lgkmcnt(0)
	v_and_b32_e32 v9, 0xffff0000, v4
	v_add_f32_e32 v8, v0, v1
	v_add_f32_e32 v8, v3, v8
	v_rcp_f32_e32 v8, v8
	v_cndmask_b32_e64 v1, v3, v1, s[48:49]
	v_cndmask_b32_e64 v0, v1, v0, s[46:47]
	v_mul_f32_e32 v0, v0, v8
	v_lshlrev_b32_e32 v8, 16, v4
	v_pk_mul_f32 v[8:9], v[0:1], v[8:9] op_sel_hi:[0,1]
	v_cvt_pk_bf16_f32 v4, v8, v9
	v_lshlrev_b32_e32 v8, 16, v5
	v_and_b32_e32 v9, 0xffff0000, v5
	v_pk_mul_f32 v[8:9], v[0:1], v[8:9] op_sel_hi:[0,1]
	v_cvt_pk_bf16_f32 v5, v8, v9
	v_lshlrev_b32_e32 v8, 16, v6
	v_and_b32_e32 v9, 0xffff0000, v6
	v_pk_mul_f32 v[8:9], v[0:1], v[8:9] op_sel_hi:[0,1]
	v_cvt_pk_bf16_f32 v6, v8, v9
	v_lshlrev_b32_e32 v8, 16, v7
	v_and_b32_e32 v9, 0xffff0000, v7
	v_pk_mul_f32 v[0:1], v[0:1], v[8:9] op_sel_hi:[0,1]
	v_cvt_pk_bf16_f32 v7, v0, v1
	v_lshl_add_u64 v[0:1], s[0:1], 0, v[150:151]
	v_lshlrev_b64 v[0:1], 11, v[0:1]
	v_lshl_or_b32 v8, s9, 6, v203
	v_lshl_add_u64 v[0:1], s[74:75], 0, v[0:1]
	v_ashrrev_i32_e32 v9, 31, v8
	v_lshl_add_u64 v[0:1], v[8:9], 1, v[0:1]
	v_lshl_add_u64 v[0:1], v[0:1], 0, v[154:155]
	global_store_dwordx4 v[0:1], v[4:7], off sc1
	s_branch .LBB0_1585

; __device__ __forceinline__ unsigned pk2(float lo, float hi) { const f32x2_t v = {lo, hi}; const bf16x2_t b = __builtin_convertvector(v, bf16x2_t); return __builtin_bit_cast(unsigned, b); }
; template <bool SAMPLE> ...
;     ...
;     if (SAMPLE) { qi = rq; qrow = (size_t)MP + b * 4 + qi; }
;     else { r = rq; s0 = sb * 16; kt0 = sb >= 8 ? 0 : 8 - sb; qrow = (size_t)b * SEQ + (((s0 + fr) << dsh) + r); }
;     const float* cbase = SAMPLE ? (g == 0 ? c0 : (g == 1 ? c1 : c2)) + (size_t)(l * DECB + b) * npre * 512 : nullptr;
;     const bf16_t* qp = Qb + qrow * ATT + h * 64 + fq * 8;
;     const bf16x8 q0 = *(const bf16x8*)qp, q1 = *(const bf16x8*)(qp + 32);
;     u32x4 vr[5][4];
; #pragma unroll
;     for (int kk = 0; kk < 5; ++kk) {
; #pragma unroll
;         for (int it = 0; it < 4; ++it) vr[kk][it] = (u32x4){0u, 0u, 0u, 0u};
;         if (2 * kk + 1 >= kt0) {
; #pragma unroll
;             for (int it = 0; it < 4; ++it) {
;                 const int rl = (lane >> 3) + 8 * it, ch = lane & 7;
;                 u32x4 w;
;                 if (SAMPLE) {
;                     int j = 32 * kk + rl; j = j > 128 ? 128 : j;
;                     const int rr = npre + qi - (j << dsh);
;                     if (rr >= npre) w = *(const u32x4*)(Vb + ((size_t)MP + b * 4 + (rr - npre)) * ATT + h * 64 + ch * 8);
;                     else { const float* vp = cbase + (size_t)rr * 512 + 256 + hs * 64 + ch * 8; const f32x4 a0 = __builtin_nontemporal_load((const f32x4*)vp), a1 = __builtin_nontemporal_load((const f32x4*)(vp + 4));
;                         w.x = pk2(a0.x, a0.y); w.y = pk2(a0.z, a0.w); w.z = pk2(a1.x, a1.y); w.w = pk2(a1.z, a1.w); }
;                 } else {
;                     int sk = s0 - 128 + 32 * kk + rl; sk = sk < 0 ? 0 : sk; sk = sk > s0 + 15 ? s0 + 15 : sk;
;                     w = *(const u32x4*)(Vb + ((size_t)b * SEQ + ((sk << dsh) + r)) * ATT + h * 64 + ch * 8);
;                 }
.LBB0_1714:
	s_bfe_u32 s4, s22, 0x20002
	s_lshr_b32 s23, s22, 4
	s_and_b32 s0, s22, 15
	s_add_i32 s1, s11, s22
	s_or_b32 s4, s4, s10
	s_cmp_eq_u32 s23, 1
	s_cselect_b32 s0, s33, s0
	s_cselect_b32 s4, s4, s8
	s_cmp_lt_u32 s22, 16
	s_cselect_b32 s1, s1, s4
	s_cselect_b32 s29, 0, s0
	s_lshl_b32 s55, s1, 4
	v_or_b32_e32 v0, s55, v160
	s_lshl_b32 s0, s23, 1
	v_lshlrev_b32_e32 v129, s0, v0
	s_sub_i32 s4, 8, s1
	v_add_u32_e32 v0, s29, v129
	s_cmp_lt_u32 s1, 8
	v_ashrrev_i32_e32 v1, 31, v0
	s_cselect_b32 s1, s4, 0
	v_lshl_add_u64 v[0:1], s[70:71], 0, v[0:1]
	v_mov_b64_e32 v[4:5], s[88:89]
	s_lshl_b32 s4, s23, 8
	v_mad_u64_u32 v[4:5], s[6:7], v0, s28, v[4:5]
	s_or_b32 s4, s4, s9
	v_mad_i32_i24 v5, v1, s28, v5
	s_lshl_b32 s4, s4, 1
	v_lshl_add_u64 v[0:1], v[4:5], 0, s[4:5]
	v_lshl_add_u64 v[0:1], v[138:139], 1, v[0:1]
	v_lshrrev_b32_e32 v202, 2, v219
	v_and_b32_e32 v203, 15, v219
	v_sub_u32_e32 v202, v202, v203
	v_mul_i32_i24_e32 v202, 0x600, v202
	v_lshlrev_b32_e32 v202, s0, v202
	v_and_b32_e32 v204, 3, v219
	v_lshrrev_b32_e32 v203, 4, v219
	v_sub_u32_e32 v204, v204, v203
	v_lshl_add_u32 v202, v204, 4, v202
	v_ashrrev_i32_e32 v203, 31, v202
	v_lshl_add_u64 v[204:205], v[202:203], 0, v[0:1]
	global_load_dwordx4 v[88:91], v[204:205], off
	global_load_dwordx4 v[84:87], v[204:205], off offset:64
	s_add_i32 s30, s55, 0xffffff80
	s_or_b32 s54, s55, 15
	s_cmp_lt_u32 s1, 2
	v_add_u32_e32 v3, s30, v133
	v_lshl_add_u64 v[0:1], v[124:125], 0, s[4:5]
	v_mov_b32_e32 v4, 0
	s_cselect_b64 s[6:7], -1, 0
	s_cmp_gt_u32 s1, 1
	v_mov_b32_e32 v16, 0
	v_mov_b32_e32 v17, 0
	v_mov_b32_e32 v18, 0
	v_mov_b32_e32 v19, 0
	v_mov_b32_e32 v20, 0
	v_mov_b32_e32 v21, 0
	v_mov_b32_e32 v22, 0
	v_mov_b32_e32 v23, 0
	v_mov_b32_e32 v8, 0
	v_mov_b32_e32 v9, 0
	v_mov_b32_e32 v10, 0
	v_mov_b32_e32 v11, 0
	v_mov_b32_e32 v12, 0
	v_mov_b32_e32 v13, 0
	v_mov_b32_e32 v14, 0
	v_mov_b32_e32 v15, 0
	s_cbranch_scc1 .LBB0_1716
	v_max_i32_e32 v5, 0, v3
	v_min_i32_e32 v5, s54, v5
	v_lshlrev_b32_e32 v5, s0, v5
	v_add_u32_e32 v6, s29, v5
	v_max_i32_e32 v5, -8, v3
	v_add_u32_e32 v5, 8, v5
	v_ashrrev_i32_e32 v7, 31, v6
	v_min_u32_e32 v5, s54, v5
	v_lshl_add_u64 v[6:7], s[70:71], 0, v[6:7]
	v_lshlrev_b32_e32 v5, s0, v5
	v_mad_u64_u32 v[8:9], s[52:53], v6, s28, v[0:1]
	v_add_u32_e32 v6, s29, v5
	v_max_i32_e32 v5, -16, v3
	v_add_u32_e32 v5, 16, v5
	v_mad_i32_i24 v9, v7, s28, v9
	v_ashrrev_i32_e32 v7, 31, v6
	v_min_u32_e32 v5, s54, v5
	v_lshl_add_u64 v[6:7], s[70:71], 0, v[6:7]
	v_lshlrev_b32_e32 v5, s0, v5
	v_mad_u64_u32 v[10:11], s[52:53], v6, s28, v[0:1]
	v_add_u32_e32 v6, s29, v5
	v_max_i32_e32 v5, 0xffffffe8, v3
	v_add_u32_e32 v5, 24, v5
	v_mad_i32_i24 v11, v7, s28, v11
	v_ashrrev_i32_e32 v7, 31, v6
	v_min_u32_e32 v5, s54, v5
	v_lshl_add_u64 v[6:7], s[70:71], 0, v[6:7]
	v_lshlrev_b32_e32 v5, s0, v5
	v_mad_u64_u32 v[16:17], s[52:53], v6, s28, v[0:1]
	v_add_u32_e32 v6, s29, v5
	v_mad_i32_i24 v17, v7, s28, v17
	v_ashrrev_i32_e32 v7, 31, v6
	v_lshl_add_u64 v[6:7], s[70:71], 0, v[6:7]
	v_mad_u64_u32 v[18:19], s[52:53], v6, s28, v[0:1]
	v_mad_i32_i24 v19, v7, s28, v19
	global_load_dwordx4 v[12:15], v[8:9], off
	s_nop 0
	global_load_dwordx4 v[8:11], v[10:11], off
	s_nop 0
	global_load_dwordx4 v[20:23], v[16:17], off
	s_nop 0
	global_load_dwordx4 v[16:19], v[18:19], off

; template <bool SAMPLE> ...
;     ...
;             } else {
;                 const int sk = s0 - 128 + 16 * kt + fr;
;                 const bf16_t* kp = Kb + ((size_t)b * SEQ + ((sk << dsh) + r)) * ATT + h * 64 + fq * 8;
;                 k0 = *(const bf16x8*)kp; k1 = *(const bf16x8*)(kp + 32);
;             }
;             f32x4 a = (f32x4){0.f, 0.f, 0.f, 0.f};
;             a = __builtin_amdgcn_mfma_f32_16x16x32_bf16(k0, q0, a, 0, 0, 0);
;             a = __builtin_amdgcn_mfma_f32_16x16x32_bf16(k1, q1, a, 0, 0, 0);
.Lpk2_ah_7:
	ds_bpermute_b32 v146, v199, v146
	ds_bpermute_b32 v147, v199, v147
	ds_bpermute_b32 v148, v199, v148
	ds_bpermute_b32 v149, v199, v149
	ds_bpermute_b32 v150, v199, v150
	ds_bpermute_b32 v151, v199, v151
	ds_bpermute_b32 v152, v199, v152
	ds_bpermute_b32 v153, v199, v153
	ds_bpermute_b32 v84, v199, v84
	ds_bpermute_b32 v85, v199, v85
	ds_bpermute_b32 v86, v199, v86
	ds_bpermute_b32 v87, v199, v87
	ds_bpermute_b32 v88, v199, v88
	ds_bpermute_b32 v89, v199, v89
	ds_bpermute_b32 v90, v199, v90
	ds_bpermute_b32 v91, v199, v91
	s_waitcnt lgkmcnt(0)
	s_cmp_gt_u32 s1, 0
	s_cbranch_scc1 .Lpk2_bh_0
	v_mfma_f32_16x16x32_bf16 v[108:111], v[108:111], v[88:91], 0
	v_mfma_f32_16x16x32_bf16 v[108:111], v[182:185], v[84:87], v[108:111]

; #define LAS __attribute__((address_space(3)))
; __device__ __forceinline__ unsigned pk2(float lo, float hi) { const f32x2_t v = {lo, hi}; const bf16x2_t b = __builtin_convertvector(v, bf16x2_t); return __builtin_bit_cast(unsigned, b); }
; __global__ void __launch_bounds__(NWAVES * 64, 2) mega(Args args) {
;     ...
;                 for (int p = 0; p < 12; ++p) {
;                     const int rowi = (tid >> 3) + 64 * p, seg = tid & 7, j = rowi >> 4, q = rowi & 15, g = j >> 4, idx = j & 15;
;                     const int r = g == 0 ? 0 : (g == 1 ? (idx & 3) : idx), sb = g == 0 ? blk * 16 + idx : (g == 1 ? blk * 4 + (idx >> 2) : blk);
;                     const int tk = (((16 * sb + q) << (2 * g)) + r) - 256 * blk;
;                     const float l0 = lsel[tk], l1 = lsel[256 + tk], l2 = lsel[512 + tk], mx = fmaxf(l0, fmaxf(l1, l2));
;                     const float e0 = __expf(l0 - mx), e1 = __expf(l1 - mx), e2 = __expf(l2 - mx);
;                     const float w = (g == 0 ? e0 : (g == 1 ? e1 : e2)) * __builtin_amdgcn_rcpf(e0 + e1 + e2);
;                     const u32x4 v = *(const LAS u32x4*)(otile + rowi * 128 + seg * 16);
;                     u32x4 o; o.x = pk2(bflo(v.x) * w, bfhi(v.x) * w); o.y = pk2(bflo(v.y) * w, bfhi(v.y) * w); o.z = pk2(bflo(v.z) * w, bfhi(v.z) * w); o.w = pk2(bflo(v.w) * w, bfhi(v.w) * w);
;                     *(u32x4*)(CAT + ((size_t)b * SEQ + 256 * blk + tk) * DM + (g * 4 + hs) * 64 + seg * 8) = o;
;                 }
.LBB0_1749:
	v_ashrrev_i32_e32 v3, 8, v0
	v_lshrrev_b32_e32 v1, 4, v0
	v_bfe_u32 v4, v0, 4, 4
	v_cmp_eq_u32_e64 s[52:53], 1, v3
	v_bfe_u32 v5, v0, 4, 2
	v_mov_b32_e32 v14, s8
	v_cndmask_b32_e64 v4, v4, v5, s[52:53]
	v_add_u32_e32 v5, s11, v1
	v_bfe_u32 v1, v1, 2, 2
	v_or_b32_e32 v1, s10, v1
	v_cmp_gt_u32_e32 vcc, s3, v0
	v_cndmask_b32_e64 v1, v14, v1, s[52:53]
	v_lshlrev_b32_e32 v3, 1, v3
	v_cndmask_b32_e64 v4, v4, 0, vcc
	v_cndmask_b32_e32 v1, v1, v5, vcc
	v_lshl_or_b32 v1, v1, 4, v137
	v_subrev_u32_e32 v4, s0, v4
	v_lshl_add_u32 v8, v1, v3, v4
	s_add_i32 s4, 0, 0x22000
	v_lshl_add_u32 v1, v8, 2, s4
	ds_read2st64_b32 v[4:5], v1 offset1:4
	ds_read_b32 v1, v1 offset:2048
	v_ashrrev_i32_e32 v9, 31, v8
	v_lshl_add_u64 v[8:9], s[70:71], 0, v[8:9]
	v_lshlrev_b64 v[8:9], 11, v[8:9]
	v_lshl_add_u64 v[8:9], s[74:75], 0, v[8:9]
	s_waitcnt lgkmcnt(0)
	v_max3_f32 v3, v4, v5, v1
	v_sub_f32_e32 v5, v5, v3
	v_sub_f32_e32 v1, v1, v3
	v_sub_f32_e32 v4, v4, v3
	v_mul_f32_e32 v5, 0x3fb8aa3b, v5
	v_mul_f32_e32 v1, 0x3fb8aa3b, v1
	v_mul_f32_e32 v4, 0x3fb8aa3b, v4
	v_exp_f32_e32 v5, v5
	v_exp_f32_e32 v1, v1
	v_exp_f32_e32 v4, v4
	v_mov_b32_e32 v129, v2
	v_cndmask_b32_e64 v3, v1, v5, s[52:53]
	v_cndmask_b32_e32 v3, v3, v4, vcc
	v_add_f32_e32 v4, v4, v5
	v_add_f32_e32 v1, v1, v4
	v_rcp_f32_e32 v1, v1
	s_nop 0
	v_mul_f32_e32 v10, v3, v1
	v_add_u32_e32 v1, s1, v143
	ds_read_b128 v[4:7], v1
	v_and_b32_e32 v3, 0xffffff00, v0
	s_addk_i32 s1, 0x4000
	s_cmp_eq_u32 s1, 0x18000
	s_waitcnt lgkmcnt(0)
	v_lshlrev_b32_e32 v12, 16, v4
	v_and_b32_e32 v13, 0xffff0000, v4
	v_pk_mul_f32 v[12:13], v[10:11], v[12:13] op_sel_hi:[0,1]
	v_cvt_pk_bf16_f32 v4, v12, v13
	v_lshlrev_b32_e32 v12, 16, v5
	v_and_b32_e32 v13, 0xffff0000, v5
	v_pk_mul_f32 v[12:13], v[10:11], v[12:13] op_sel_hi:[0,1]
	v_cvt_pk_bf16_f32 v5, v12, v13
	v_lshlrev_b32_e32 v12, 16, v6
	v_and_b32_e32 v13, 0xffff0000, v6
	v_pk_mul_f32 v[12:13], v[10:11], v[12:13] op_sel_hi:[0,1]
	v_cvt_pk_bf16_f32 v6, v12, v13
	v_lshlrev_b32_e32 v12, 16, v7
	v_and_b32_e32 v13, 0xffff0000, v7
	v_pk_mul_f32 v[10:11], v[10:11], v[12:13] op_sel_hi:[0,1]
	v_cvt_pk_bf16_f32 v7, v10, v11
	v_or_b32_e32 v10, s9, v3
	v_ashrrev_i32_e32 v11, 31, v10
	v_lshl_add_u64 v[8:9], v[10:11], 1, v[8:9]
	v_lshl_add_u64 v[8:9], v[8:9], 0, v[128:129]
	v_add_u32_e32 v3, 64, v0
	global_store_dwordx4 v[8:9], v[4:7], off sc1
	v_cmp_gt_u32_e32 vcc, s3, v3
	v_add_u32_e32 v0, 0x80, v0
	v_ashrrev_i32_e32 v5, 8, v3
	v_lshrrev_b32_e32 v4, 4, v3
	v_bfe_u32 v6, v3, 4, 4
	v_cmp_eq_u32_e64 s[52:53], 1, v5
	v_bfe_u32 v7, v3, 4, 2
	v_lshlrev_b32_e32 v5, 1, v5
	v_cndmask_b32_e64 v6, v6, v7, s[52:53]
	v_add_u32_e32 v7, s11, v4
	v_bfe_u32 v4, v4, 2, 2
	v_or_b32_e32 v4, s10, v4
	v_cndmask_b32_e64 v4, v14, v4, s[52:53]
	v_cndmask_b32_e64 v6, v6, 0, vcc
	v_cndmask_b32_e32 v4, v4, v7, vcc
	v_lshl_or_b32 v4, v4, 4, v137
	v_subrev_u32_e32 v6, s0, v6
	v_lshl_add_u32 v8, v4, v5, v6
	v_lshl_add_u32 v6, v8, 2, s4
	ds_read2st64_b32 v[4:5], v6 offset1:4
	ds_read_b32 v6, v6 offset:2048
	v_ashrrev_i32_e32 v9, 31, v8
	v_lshl_add_u64 v[8:9], s[70:71], 0, v[8:9]
	v_lshlrev_b64 v[8:9], 11, v[8:9]
	v_lshl_add_u64 v[8:9], s[74:75], 0, v[8:9]
	s_waitcnt lgkmcnt(0)
	v_max3_f32 v7, v4, v5, v6
	v_sub_f32_e32 v5, v5, v7
	v_sub_f32_e32 v6, v6, v7
	v_sub_f32_e32 v4, v4, v7
	v_mul_f32_e32 v5, 0x3fb8aa3b, v5
	v_mul_f32_e32 v6, 0x3fb8aa3b, v6
	v_mul_f32_e32 v4, 0x3fb8aa3b, v4
	v_exp_f32_e32 v5, v5
	v_exp_f32_e32 v6, v6
	v_exp_f32_e32 v4, v4
	v_cndmask_b32_e64 v7, v6, v5, s[52:53]
	v_cndmask_b32_e32 v7, v7, v4, vcc
	v_add_f32_e32 v4, v4, v5
	v_add_f32_e32 v4, v6, v4
	v_rcp_f32_e32 v4, v4
	s_nop 0
	v_mul_f32_e32 v10, v7, v4
	ds_read_b128 v[4:7], v1 offset:8192
	v_and_b32_e32 v1, 0xffffff00, v3
	s_waitcnt lgkmcnt(0)
	v_lshlrev_b32_e32 v12, 16, v4
	v_and_b32_e32 v13, 0xffff0000, v4
	v_pk_mul_f32 v[12:13], v[10:11], v[12:13] op_sel_hi:[0,1]
	v_cvt_pk_bf16_f32 v4, v12, v13
	v_lshlrev_b32_e32 v12, 16, v5
	v_and_b32_e32 v13, 0xffff0000, v5
	v_pk_mul_f32 v[12:13], v[10:11], v[12:13] op_sel_hi:[0,1]
	v_cvt_pk_bf16_f32 v5, v12, v13
	v_lshlrev_b32_e32 v12, 16, v6
	v_and_b32_e32 v13, 0xffff0000, v6
	v_pk_mul_f32 v[12:13], v[10:11], v[12:13] op_sel_hi:[0,1]
	v_cvt_pk_bf16_f32 v6, v12, v13
	v_lshlrev_b32_e32 v12, 16, v7
	v_and_b32_e32 v13, 0xffff0000, v7
	v_pk_mul_f32 v[10:11], v[10:11], v[12:13] op_sel_hi:[0,1]
	v_cvt_pk_bf16_f32 v7, v10, v11
	v_or_b32_e32 v10, s9, v1
	v_ashrrev_i32_e32 v11, 31, v10
	v_lshl_add_u64 v[8:9], v[10:11], 1, v[8:9]
	v_lshl_add_u64 v[8:9], v[8:9], 0, v[128:129]
	global_store_dwordx4 v[8:9], v[4:7], off sc1
	s_cbranch_scc0 .LBB0_1749
	v_readlane_b32 s8, v251, 0
	v_readlane_b32 s10, v251, 2
	s_add_i32 s2, s2, s10
	s_cmpk_gt_i32 s2, 0xff
	v_readlane_b32 s9, v251, 1
	v_readlane_b32 s11, v251, 3
	s_cbranch_scc0 .LBB0_1712

; __global__ void __launch_bounds__(NWAVES * 64, 2) mega(Args args) {
;     ...
;             for (int b = gw; b < DECB; b += NGW) {
;                 const f32x4 gg = *(const f32x4*)(sg + 4 * lane), bb = *(const f32x4*)(sb_ + 4 * lane);
;                 const int g = lane >> 4;
;                 f32x4 gvv[4];
; #pragma unroll
;                 for (int i = 0; i < 4; ++i) {
;                     const size_t row = (size_t)MP + b * 4 + i;
;                     const u32x2 raw = *((const u32x2*)(Gb + row * 256) + lane);
;                     f32x4 v = (f32x4){bflo(raw.x), bfhi(raw.x), bflo(raw.y), bfhi(raw.y)};
;                     const float mean = wave_sum((v.x + v.y) + (v.z + v.w)) * (1.f / 256.f);
;                     v = v - mean;
;                     const float rstd = __builtin_amdgcn_rsqf(wave_sum((v.x * v.x + v.y * v.y) + (v.z * v.z + v.w * v.w)) * (1.f / 256.f) + LN_EPS);
;                     gvv[i] = v * rstd * gg + bb;
;                     *(f32x4*)(out + O9 + (((size_t)l * DECB + b) * 4 + i) * 256 + 4 * lane) = gvv[i];
;                 }
.LBB0_1753:
	s_ashr_i32 s1, s0, 31
	s_add_u32 s36, s0, 0x4000
	s_addc_u32 s37, s1, 0
	s_lshl_b64 s[48:49], s[36:37], 9
	v_lshl_add_u64 v[4:5], v[26:27], 0, s[48:49]
	global_load_dwordx4 v[12:15], v[0:1], off
	global_load_dwordx4 v[16:19], v[24:25], off
	s_add_u32 s42, s0, 0x4001
	global_load_dwordx2 v[4:5], v[4:5], off
	s_addc_u32 s43, s1, 0
	s_lshl_b64 s[46:47], s[42:43], 9
	s_add_u32 s44, s0, 0x4002
	s_addc_u32 s45, s1, 0
	s_lshl_b64 s[50:51], s[44:45], 9
	s_add_u32 s52, s0, 0x4003
	s_addc_u32 s53, s1, 0
	s_lshl_b64 s[54:55], s[52:53], 9
	s_lshl_b64 s[8:9], s[36:37], 11
	s_add_i32 s68, s68, s20
	s_add_i32 s0, s0, s4
	s_waitcnt vmcnt(0)
	v_lshlrev_b32_e32 v7, 16, v5
	v_lshlrev_b32_e32 v6, 16, v4
	v_and_b32_e32 v5, 0xffff0000, v5
	v_and_b32_e32 v4, 0xffff0000, v4
	v_pk_add_f32 v[8:9], v[6:7], v[4:5]
	s_nop 0
	v_add_f32_e32 v8, v8, v9
	ds_bpermute_b32 v9, v3, v8
	s_waitcnt lgkmcnt(0)
	v_add_f32_e32 v8, v8, v9
	ds_bpermute_b32 v9, v44, v8
	s_waitcnt lgkmcnt(0)
	v_add_f32_e32 v8, v8, v9
	ds_bpermute_b32 v9, v45, v8
	s_waitcnt lgkmcnt(0)
	v_add_f32_e32 v8, v8, v9
	ds_bpermute_b32 v9, v46, v8
	s_waitcnt lgkmcnt(0)
	v_add_f32_e32 v8, v8, v9
	ds_bpermute_b32 v9, v47, v8
	s_waitcnt lgkmcnt(0)
	v_add_f32_e32 v8, v8, v9
	ds_bpermute_b32 v9, v48, v8
	s_waitcnt lgkmcnt(0)
	v_add_f32_e32 v8, v8, v9
	v_fmac_f32_e32 v4, 0xbb800000, v8
	v_fmac_f32_e32 v5, 0xbb800000, v8
	v_fmac_f32_e32 v7, 0xbb800000, v8
	v_fmac_f32_e32 v6, 0xbb800000, v8
	v_mov_b32_e32 v8, v7
	v_mov_b32_e32 v9, v5
	v_mov_b32_e32 v7, v4
	v_pk_mul_f32 v[10:11], v[8:9], v[8:9]
	v_pk_mul_f32 v[4:5], v[6:7], v[6:7]
	s_nop 0
	v_pk_mov_b32 v[20:21], v[4:5], v[10:11] op_sel:[1,0]
	v_mov_b32_e32 v5, v11
	v_pk_add_f32 v[4:5], v[20:21], v[4:5]
	s_nop 0
	v_add_f32_e32 v4, v4, v5
	ds_bpermute_b32 v5, v3, v4
	s_waitcnt lgkmcnt(0)
	v_add_f32_e32 v4, v4, v5
	ds_bpermute_b32 v5, v44, v4
	s_waitcnt lgkmcnt(0)
	v_add_f32_e32 v4, v4, v5
	ds_bpermute_b32 v5, v45, v4
	s_waitcnt lgkmcnt(0)
	v_add_f32_e32 v4, v4, v5
	ds_bpermute_b32 v5, v46, v4
	s_waitcnt lgkmcnt(0)
	v_add_f32_e32 v4, v4, v5
	ds_bpermute_b32 v5, v47, v4
	s_waitcnt lgkmcnt(0)
	v_add_f32_e32 v4, v4, v5
	ds_bpermute_b32 v5, v48, v4
	s_waitcnt lgkmcnt(0)
	v_add_f32_e32 v4, v4, v5
	v_fmamk_f32 v4, v4, 0x3b800000, v221
	v_rsq_f32_e32 v4, v4
	s_nop 0
	v_pk_mul_f32 v[10:11], v[6:7], v[4:5] op_sel_hi:[1,0]
	v_pk_mul_f32 v[4:5], v[8:9], v[4:5] op_sel_hi:[1,0]
	v_lshl_add_u64 v[8:9], v[26:27], 0, s[46:47]
	v_pk_fma_f32 v[6:7], v[14:15], v[4:5], v[18:19]
	v_pk_fma_f32 v[4:5], v[12:13], v[10:11], v[16:17]
	global_store_dwordx4 v[42:43], v[4:7], off offset:-2048 sc1
	global_load_dwordx2 v[8:9], v[8:9], off
	s_waitcnt vmcnt(0)
	v_lshlrev_b32_e32 v11, 16, v9
	v_lshlrev_b32_e32 v10, 16, v8
	v_and_b32_e32 v9, 0xffff0000, v9
	v_and_b32_e32 v8, 0xffff0000, v8
	v_pk_add_f32 v[20:21], v[10:11], v[8:9]
	s_nop 0
	v_add_f32_e32 v20, v20, v21
	ds_bpermute_b32 v21, v3, v20
	s_waitcnt lgkmcnt(0)
	v_add_f32_e32 v20, v20, v21
	ds_bpermute_b32 v21, v44, v20
	s_waitcnt lgkmcnt(0)
	v_add_f32_e32 v20, v20, v21
	ds_bpermute_b32 v21, v45, v20
	s_waitcnt lgkmcnt(0)
	v_add_f32_e32 v20, v20, v21
	ds_bpermute_b32 v21, v46, v20
	s_waitcnt lgkmcnt(0)
	v_add_f32_e32 v20, v20, v21
	ds_bpermute_b32 v21, v47, v20
	s_waitcnt lgkmcnt(0)
	v_add_f32_e32 v20, v20, v21
	ds_bpermute_b32 v21, v48, v20
	s_waitcnt lgkmcnt(0)
	v_add_f32_e32 v20, v20, v21
	v_fmac_f32_e32 v8, 0xbb800000, v20
	v_fmac_f32_e32 v9, 0xbb800000, v20
	v_fmac_f32_e32 v11, 0xbb800000, v20
	v_fmac_f32_e32 v10, 0xbb800000, v20
	v_mov_b32_e32 v20, v11
	v_mov_b32_e32 v21, v9
	v_mov_b32_e32 v11, v8
	v_pk_mul_f32 v[22:23], v[20:21], v[20:21]
	v_pk_mul_f32 v[8:9], v[10:11], v[10:11]
	s_nop 0
	v_pk_mov_b32 v[50:51], v[8:9], v[22:23] op_sel:[1,0]
	v_mov_b32_e32 v9, v23
	v_pk_add_f32 v[8:9], v[50:51], v[8:9]
	s_nop 0
	v_add_f32_e32 v8, v8, v9
	ds_bpermute_b32 v9, v3, v8
	s_waitcnt lgkmcnt(0)
	v_add_f32_e32 v8, v8, v9
	ds_bpermute_b32 v9, v44, v8
	s_waitcnt lgkmcnt(0)
	v_add_f32_e32 v8, v8, v9
	ds_bpermute_b32 v9, v45, v8
	s_waitcnt lgkmcnt(0)
	v_add_f32_e32 v8, v8, v9
	ds_bpermute_b32 v9, v46, v8
	s_waitcnt lgkmcnt(0)
	v_add_f32_e32 v8, v8, v9
	ds_bpermute_b32 v9, v47, v8
	s_waitcnt lgkmcnt(0)
	v_add_f32_e32 v8, v8, v9
	ds_bpermute_b32 v9, v48, v8
	s_waitcnt lgkmcnt(0)
	v_add_f32_e32 v8, v8, v9
	v_fmamk_f32 v8, v8, 0x3b800000, v221
	v_rsq_f32_e32 v8, v8
	s_nop 0
	v_pk_mul_f32 v[22:23], v[10:11], v[8:9] op_sel_hi:[1,0]
	v_pk_mul_f32 v[8:9], v[20:21], v[8:9] op_sel_hi:[1,0]
	v_lshl_add_u64 v[20:21], v[26:27], 0, s[50:51]
	v_pk_fma_f32 v[10:11], v[14:15], v[8:9], v[18:19]
	v_pk_fma_f32 v[8:9], v[12:13], v[22:23], v[16:17]
	global_store_dwordx4 v[42:43], v[8:11], off offset:-1024 sc1
	global_load_dwordx2 v[20:21], v[20:21], off
	s_waitcnt vmcnt(0)
	v_lshlrev_b32_e32 v23, 16, v21
	v_lshlrev_b32_e32 v22, 16, v20
	v_and_b32_e32 v21, 0xffff0000, v21
	v_and_b32_e32 v20, 0xffff0000, v20
	v_pk_add_f32 v[50:51], v[22:23], v[20:21]
	s_nop 0
	v_add_f32_e32 v49, v50, v51
	ds_bpermute_b32 v50, v3, v49
	s_waitcnt lgkmcnt(0)
	v_add_f32_e32 v49, v49, v50
	ds_bpermute_b32 v50, v44, v49
	s_waitcnt lgkmcnt(0)
	v_add_f32_e32 v49, v49, v50
	ds_bpermute_b32 v50, v45, v49
	s_waitcnt lgkmcnt(0)
	v_add_f32_e32 v49, v49, v50
	ds_bpermute_b32 v50, v46, v49
	s_waitcnt lgkmcnt(0)
	v_add_f32_e32 v49, v49, v50
	ds_bpermute_b32 v50, v47, v49
	s_waitcnt lgkmcnt(0)
	v_add_f32_e32 v49, v49, v50
	ds_bpermute_b32 v50, v48, v49
	s_waitcnt lgkmcnt(0)
; __global__ void __launch_bounds__(NWAVES * 64, 2) mega(Args args) {
;     ...
;                     const size_t row = (size_t)MP + b * 4 + i;
;                     const u32x2 raw = *((const u32x2*)(Gb + row * 256) + lane);
;                     f32x4 v = (f32x4){bflo(raw.x), bfhi(raw.x), bflo(raw.y), bfhi(raw.y)};
;                     const float mean = wave_sum((v.x + v.y) + (v.z + v.w)) * (1.f / 256.f);
;                     v = v - mean;
;                     const float rstd = __builtin_amdgcn_rsqf(wave_sum((v.x * v.x + v.y * v.y) + (v.z * v.z + v.w * v.w)) * (1.f / 256.f) + LN_EPS);
;                     gvv[i] = v * rstd * gg + bb;
;                     *(f32x4*)(out + O9 + (((size_t)l * DECB + b) * 4 + i) * 256 + 4 * lane) = gvv[i];
;                 }
; #pragma unroll
;                 for (int i = 0; i < 4; ++i) {
;                     const size_t row = (size_t)MP + b * 4 + i;
;                     const float* wsp = args.in[10] + (((size_t)l * 4 + g) * 128 + i) * 128;
;                     const float bs = args.in[11][((size_t)l * 4 + g) * 128 + i];
;                     f32x4 mx = (f32x4){bs, bs, bs, bs};
; #pragma unroll
;                     for (int s = 0; s <= i; ++s) mx = mx + gvv[s] * wsp[s];
	v_add_f32_e32 v49, v49, v50
	v_fmac_f32_e32 v20, 0xbb800000, v49
	v_fmac_f32_e32 v21, 0xbb800000, v49
	v_fmac_f32_e32 v23, 0xbb800000, v49
	v_fmac_f32_e32 v22, 0xbb800000, v49
	v_mov_b32_e32 v50, v23
	v_mov_b32_e32 v51, v21
	v_mov_b32_e32 v23, v20
	v_pk_mul_f32 v[52:53], v[50:51], v[50:51]
	v_pk_mul_f32 v[20:21], v[22:23], v[22:23]
	s_nop 0
	v_pk_mov_b32 v[54:55], v[20:21], v[52:53] op_sel:[1,0]
	v_mov_b32_e32 v21, v53
	v_pk_add_f32 v[20:21], v[54:55], v[20:21]
	s_nop 0
	v_add_f32_e32 v20, v20, v21
	ds_bpermute_b32 v21, v3, v20
	s_waitcnt lgkmcnt(0)
	v_add_f32_e32 v20, v20, v21
	ds_bpermute_b32 v21, v44, v20
	s_waitcnt lgkmcnt(0)
	v_add_f32_e32 v20, v20, v21
	ds_bpermute_b32 v21, v45, v20
	s_waitcnt lgkmcnt(0)
	v_add_f32_e32 v20, v20, v21
	ds_bpermute_b32 v21, v46, v20
	s_waitcnt lgkmcnt(0)
	v_add_f32_e32 v20, v20, v21
	ds_bpermute_b32 v21, v47, v20
	s_waitcnt lgkmcnt(0)
	v_add_f32_e32 v20, v20, v21
	ds_bpermute_b32 v21, v48, v20
	s_waitcnt lgkmcnt(0)
	v_add_f32_e32 v20, v20, v21
	v_fmamk_f32 v20, v20, 0x3b800000, v221
	v_rsq_f32_e32 v20, v20
	s_nop 0
	v_pk_mul_f32 v[52:53], v[22:23], v[20:21] op_sel_hi:[1,0]
	v_pk_mul_f32 v[20:21], v[50:51], v[20:21] op_sel_hi:[1,0]
	v_lshl_add_u64 v[50:51], v[26:27], 0, s[54:55]
	v_pk_fma_f32 v[22:23], v[14:15], v[20:21], v[18:19]
	v_pk_fma_f32 v[20:21], v[12:13], v[52:53], v[16:17]
	global_store_dwordx4 v[42:43], v[20:23], off sc1
	global_load_dwordx2 v[50:51], v[50:51], off
	s_waitcnt vmcnt(0)
	v_lshlrev_b32_e32 v53, 16, v51
	v_lshlrev_b32_e32 v52, 16, v50
	v_and_b32_e32 v51, 0xffff0000, v51
	v_and_b32_e32 v50, 0xffff0000, v50
	v_pk_add_f32 v[54:55], v[52:53], v[50:51]
	s_nop 0
	v_add_f32_e32 v49, v54, v55
	ds_bpermute_b32 v54, v3, v49
	s_waitcnt lgkmcnt(0)
	v_add_f32_e32 v49, v49, v54
	ds_bpermute_b32 v54, v44, v49
	s_waitcnt lgkmcnt(0)
	v_add_f32_e32 v49, v49, v54
	ds_bpermute_b32 v54, v45, v49
	s_waitcnt lgkmcnt(0)
	v_add_f32_e32 v49, v49, v54
	ds_bpermute_b32 v54, v46, v49
	s_waitcnt lgkmcnt(0)
	v_add_f32_e32 v49, v49, v54
	ds_bpermute_b32 v54, v47, v49
	s_waitcnt lgkmcnt(0)
	v_add_f32_e32 v49, v49, v54
	ds_bpermute_b32 v54, v48, v49
	s_waitcnt lgkmcnt(0)
	v_add_f32_e32 v49, v49, v54
	v_fmac_f32_e32 v50, 0xbb800000, v49
	v_fmac_f32_e32 v51, 0xbb800000, v49
	v_fmac_f32_e32 v53, 0xbb800000, v49
	v_fmac_f32_e32 v52, 0xbb800000, v49
	v_mov_b32_e32 v54, v53
	v_mov_b32_e32 v55, v51
	v_mov_b32_e32 v53, v50
	v_pk_mul_f32 v[56:57], v[54:55], v[54:55]
	v_pk_mul_f32 v[50:51], v[52:53], v[52:53]
	s_nop 0
	v_pk_mov_b32 v[58:59], v[50:51], v[56:57] op_sel:[1,0]
	v_mov_b32_e32 v51, v57
	v_pk_add_f32 v[50:51], v[58:59], v[50:51]
	s_nop 0
	v_add_f32_e32 v49, v50, v51
	ds_bpermute_b32 v50, v3, v49
	s_waitcnt lgkmcnt(0)
	v_add_f32_e32 v49, v49, v50
	ds_bpermute_b32 v50, v44, v49
	s_waitcnt lgkmcnt(0)
	v_add_f32_e32 v49, v49, v50
	ds_bpermute_b32 v50, v45, v49
	s_waitcnt lgkmcnt(0)
	v_add_f32_e32 v49, v49, v50
	ds_bpermute_b32 v50, v46, v49
	s_waitcnt lgkmcnt(0)
	v_add_f32_e32 v49, v49, v50
	ds_bpermute_b32 v50, v47, v49
	s_waitcnt lgkmcnt(0)
	v_add_f32_e32 v49, v49, v50
	ds_bpermute_b32 v50, v48, v49
	s_waitcnt lgkmcnt(0)
	v_add_f32_e32 v49, v49, v50
	v_fmamk_f32 v49, v49, 0x3b800000, v221
	v_rsq_f32_e32 v50, v49
	s_nop 0
	v_pk_mul_f32 v[52:53], v[52:53], v[50:51] op_sel_hi:[1,0]
	v_pk_mul_f32 v[50:51], v[54:55], v[50:51] op_sel_hi:[1,0]
	v_pk_fma_f32 v[12:13], v[12:13], v[52:53], v[16:17]
	v_pk_fma_f32 v[14:15], v[14:15], v[50:51], v[18:19]
	global_store_dwordx4 v[42:43], v[12:15], off offset:1024 sc1
	global_load_dword v18, v[30:31], off
	global_load_dword v50, v[32:33], off
	v_lshl_add_u64 v[42:43], v[42:43], 0, s[24:25]
	s_waitcnt vmcnt(0)
	v_pk_fma_f32 v[16:17], v[4:5], v[50:51], v[18:19] op_sel_hi:[1,0,0]
	v_pk_fma_f32 v[18:19], v[6:7], v[50:51], v[18:19] op_sel_hi:[1,0,0]
	v_lshl_add_u64 v[50:51], v[28:29], 0, s[48:49]
	global_load_dwordx2 v[50:51], v[50:51], off
	s_waitcnt vmcnt(0)
; __device__ __forceinline__ u32x2 pk4(f32x4 v) { u32x2 r; r.x = pk2(v.x, v.y); r.y = pk2(v.z, v.w); return r; }
; __global__ void __launch_bounds__(NWAVES * 64, 2) mega(Args args) {
;     ...
;                 for (int i = 0; i < 4; ++i) {
;                     const size_t row = (size_t)MP + b * 4 + i;
;                     const float* wsp = args.in[10] + (((size_t)l * 4 + g) * 128 + i) * 128;
;                     const float bs = args.in[11][((size_t)l * 4 + g) * 128 + i];
;                     f32x4 mx = (f32x4){bs, bs, bs, bs};
; #pragma unroll
;                     for (int s = 0; s <= i; ++s) mx = mx + gvv[s] * wsp[s];
;                     const u32x2 ur = *((const u32x2*)(Ub + row * 256) + lane);
;                     f32x4 u = (f32x4){bflo(ur.x), bfhi(ur.x), bflo(ur.y), bfhi(ur.y)};
;                     *((u32x2*)(CAT + row * DM + ATT) + lane) = pk4(u * mx);
;                 }
	v_lshlrev_b32_e32 v52, 16, v50
	v_and_b32_e32 v53, 0xffff0000, v50
	v_lshlrev_b32_e32 v50, 16, v51
	v_and_b32_e32 v51, 0xffff0000, v51
	v_pk_mul_f32 v[18:19], v[18:19], v[50:51]
	v_pk_mul_f32 v[16:17], v[16:17], v[52:53]
	s_nop 0
	v_cvt_pk_bf16_f32 v16, v16, v17
	v_cvt_pk_bf16_f32 v17, v18, v19
	v_lshl_add_u64 v[18:19], v[40:41], 0, s[8:9]
	global_store_dwordx2 v[18:19], v[16:17], off offset:1536
	global_load_dword v16, v[30:31], off offset:4
	s_nop 0
	global_load_dwordx2 v[18:19], v[34:35], off
	s_lshl_b64 s[8:9], s[42:43], 11
	s_waitcnt vmcnt(0)
	v_pk_fma_f32 v[50:51], v[6:7], v[18:19], v[16:17] op_sel_hi:[1,0,0]
	v_pk_fma_f32 v[16:17], v[4:5], v[18:19], v[16:17] op_sel_hi:[1,0,0]
	s_nop 0
	v_pk_fma_f32 v[16:17], v[8:9], v[18:19], v[16:17] op_sel:[0,1,0]
	v_pk_fma_f32 v[18:19], v[10:11], v[18:19], v[50:51] op_sel:[0,1,0]
	v_lshl_add_u64 v[50:51], v[28:29], 0, s[46:47]
	global_load_dwordx2 v[50:51], v[50:51], off
	s_waitcnt vmcnt(0)
	v_lshlrev_b32_e32 v52, 16, v50
	v_and_b32_e32 v53, 0xffff0000, v50
	v_lshlrev_b32_e32 v50, 16, v51
	v_and_b32_e32 v51, 0xffff0000, v51
	v_pk_mul_f32 v[18:19], v[18:19], v[50:51]
	v_pk_mul_f32 v[16:17], v[16:17], v[52:53]
	s_nop 0
	v_cvt_pk_bf16_f32 v16, v16, v17
	v_cvt_pk_bf16_f32 v17, v18, v19
	v_lshl_add_u64 v[18:19], v[40:41], 0, s[8:9]
	global_store_dwordx2 v[18:19], v[16:17], off offset:1536
	global_load_dword v50, v[30:31], off offset:8
	s_nop 0
	global_load_dwordx3 v[16:18], v[36:37], off
	s_lshl_b64 s[8:9], s[44:45], 11
	s_waitcnt vmcnt(0)
	v_pk_fma_f32 v[52:53], v[4:5], v[16:17], v[50:51] op_sel_hi:[1,0,0]
	v_pk_fma_f32 v[50:51], v[6:7], v[16:17], v[50:51] op_sel_hi:[1,0,0]
	s_nop 0
	v_pk_fma_f32 v[50:51], v[10:11], v[16:17], v[50:51] op_sel:[0,1,0]
	v_pk_fma_f32 v[16:17], v[8:9], v[16:17], v[52:53] op_sel:[0,1,0]
	s_nop 0
	v_pk_fma_f32 v[16:17], v[20:21], v[18:19], v[16:17] op_sel_hi:[1,0,1]
	v_pk_fma_f32 v[18:19], v[22:23], v[18:19], v[50:51] op_sel_hi:[1,0,1]
	v_lshl_add_u64 v[50:51], v[28:29], 0, s[50:51]
	global_load_dwordx2 v[50:51], v[50:51], off
	s_waitcnt vmcnt(0)
	v_lshlrev_b32_e32 v52, 16, v50
	v_and_b32_e32 v53, 0xffff0000, v50
	v_lshlrev_b32_e32 v50, 16, v51
	v_and_b32_e32 v51, 0xffff0000, v51
	v_pk_mul_f32 v[18:19], v[18:19], v[50:51]
	v_pk_mul_f32 v[16:17], v[16:17], v[52:53]
	s_nop 0
	v_cvt_pk_bf16_f32 v16, v16, v17
	v_cvt_pk_bf16_f32 v17, v18, v19
	v_lshl_add_u64 v[18:19], v[40:41], 0, s[8:9]
	global_store_dwordx2 v[18:19], v[16:17], off offset:1536
	global_load_dword v50, v[30:31], off offset:12
	s_nop 0
	global_load_dwordx4 v[16:19], v[38:39], off
	s_lshl_b64 s[8:9], s[52:53], 11
	s_cmp_gt_i32 s68, 31
	s_waitcnt vmcnt(0)
	v_pk_fma_f32 v[6:7], v[6:7], v[16:17], v[50:51] op_sel_hi:[1,0,0]
	v_pk_fma_f32 v[4:5], v[4:5], v[16:17], v[50:51] op_sel_hi:[1,0,0]
	v_pk_fma_f32 v[6:7], v[10:11], v[16:17], v[6:7] op_sel:[0,1,0]
	v_pk_fma_f32 v[4:5], v[8:9], v[16:17], v[4:5] op_sel:[0,1,0]
	v_pk_fma_f32 v[6:7], v[22:23], v[18:19], v[6:7] op_sel_hi:[1,0,1]
	v_pk_fma_f32 v[4:5], v[20:21], v[18:19], v[4:5] op_sel_hi:[1,0,1]
	v_mov_b32_e32 v8, v19
	v_pk_fma_f32 v[4:5], v[12:13], v[8:9], v[4:5] op_sel_hi:[1,0,1]
	v_pk_fma_f32 v[6:7], v[14:15], v[8:9], v[6:7] op_sel_hi:[1,0,1]
	v_lshl_add_u64 v[8:9], v[28:29], 0, s[54:55]
	global_load_dwordx2 v[8:9], v[8:9], off
	s_waitcnt vmcnt(0)
	v_lshlrev_b32_e32 v10, 16, v8
	v_and_b32_e32 v11, 0xffff0000, v8
	v_lshlrev_b32_e32 v8, 16, v9
	v_and_b32_e32 v9, 0xffff0000, v9
	v_pk_mul_f32 v[6:7], v[6:7], v[8:9]
	v_pk_mul_f32 v[4:5], v[4:5], v[10:11]
	s_nop 0
	v_cvt_pk_bf16_f32 v4, v4, v5
	v_cvt_pk_bf16_f32 v5, v6, v7
	v_lshl_add_u64 v[6:7], v[40:41], 0, s[8:9]
	global_store_dwordx2 v[6:7], v[4:5], off offset:1536
	s_cbranch_scc0 .LBB0_1753

; __device__ __forceinline__ void final_ln(const bf16_t* ZB, const float* gam, const float* bet, float* yout, int gw, int NGW, int lane) {
;     ...
;     for (int row = gw; row < MR; row += NGW) {
;         const u32x2* zr = (const u32x2*)(ZB + (size_t)row * DM) + lane;
;         f32x4 v[4]; float s = 0.f;
; #pragma unroll
;         for (int j = 0; j < 4; ++j) { const u32x2 raw = zr[64 * j]; v[j] = (f32x4){bflo(raw.x), bfhi(raw.x), bflo(raw.y), bfhi(raw.y)}; s += (v[j].x + v[j].y) + (v[j].z + v[j].w); }
;         const float mean = wave_sum(s) * (1.f / DM); float s2 = 0.f;
; #pragma unroll
;         for (int j = 0; j < 4; ++j) { v[j] = v[j] - mean; s2 += (v[j].x * v[j].x + v[j].y * v[j].y) + (v[j].z * v[j].z + v[j].w * v[j].w); }
;         const float rstd = __builtin_amdgcn_rsqf(wave_sum(s2) * (1.f / DM) + LN_EPS);
;         f32x4* o = (f32x4*)(yout + (size_t)row * DM) + lane;
; #pragma unroll
;         for (int j = 0; j < 4; ++j) o[64 * j] = v[j] * rstd * gv[j] + bv[j];
;     }
.LBB0_2458:
	global_load_dwordx2 v[80:81], v[32:33], off
	global_load_dwordx2 v[82:83], v[32:33], off offset:512
	global_load_dwordx2 v[84:85], v[32:33], off offset:1024
	global_load_dwordx2 v[86:87], v[32:33], off offset:1536
	s_add_i32 s8, s8, s10
	v_lshl_add_u64 v[32:33], v[32:33], 0, s[2:3]
	s_cmpk_lt_i32 s8, 0x4080
	v_lshlrev_b32_e32 v53, 16, v45
	v_lshlrev_b32_e32 v52, 16, v44
	v_and_b32_e32 v45, 0xffff0000, v45
	v_and_b32_e32 v44, 0xffff0000, v44
	v_lshlrev_b32_e32 v55, 16, v47
	v_lshlrev_b32_e32 v54, 16, v46
	v_and_b32_e32 v47, 0xffff0000, v47
	v_and_b32_e32 v46, 0xffff0000, v46
	v_pk_add_f32 v[64:65], v[52:53], v[44:45]
	v_pk_add_f32 v[66:67], v[54:55], v[46:47]
	v_lshlrev_b32_e32 v56, 16, v48
	v_and_b32_e32 v57, 0xffff0000, v48
	v_lshlrev_b32_e32 v48, 16, v49
	v_and_b32_e32 v49, 0xffff0000, v49
	v_and_b32_e32 v61, 0xffff0000, v50
	v_add_f32_e32 v43, v64, v65
	v_pk_add_f32 v[64:65], v[66:67], v[66:67] op_sel:[0,1] op_sel_hi:[1,0]
	v_lshlrev_b32_e32 v59, 16, v50
	v_lshlrev_b32_e32 v63, 16, v51
	v_and_b32_e32 v51, 0xffff0000, v51
	v_add_f32_e32 v62, v56, v57
	v_add_f32_e32 v50, v48, v49
	v_add_f32_e32 v58, 0, v43
	v_mov_b32_e32 v65, v61
	v_pk_add_f32 v[66:67], v[62:63], v[50:51]
	v_pk_add_f32 v[64:65], v[58:59], v[64:65]
	s_nop 0
	v_pk_add_f32 v[64:65], v[64:65], v[66:67]
	s_nop 0
	v_add_f32_e32 v43, v64, v65
	ds_bpermute_b32 v50, v36, v43
	s_waitcnt lgkmcnt(0)
	v_add_f32_e32 v43, v43, v50
	ds_bpermute_b32 v50, v37, v43
	s_waitcnt lgkmcnt(0)
	v_add_f32_e32 v43, v43, v50
	ds_bpermute_b32 v50, v38, v43
	s_waitcnt lgkmcnt(0)
	v_add_f32_e32 v43, v43, v50
	ds_bpermute_b32 v50, v39, v43
	s_waitcnt lgkmcnt(0)
	v_add_f32_e32 v43, v43, v50
	ds_bpermute_b32 v50, v40, v43
	s_waitcnt lgkmcnt(0)
	v_add_f32_e32 v43, v43, v50
	ds_bpermute_b32 v50, v41, v43
	s_waitcnt lgkmcnt(0)
	v_add_f32_e32 v43, v43, v50
	v_fmac_f32_e32 v44, 0xba800000, v43
	v_fmac_f32_e32 v45, 0xba800000, v43
	v_fmac_f32_e32 v53, 0xba800000, v43
	v_fmac_f32_e32 v46, 0xba800000, v43
	v_fmac_f32_e32 v47, 0xba800000, v43
	v_fmac_f32_e32 v55, 0xba800000, v43
	v_fmac_f32_e32 v52, 0xba800000, v43
	v_fmac_f32_e32 v54, 0xba800000, v43
	v_fmac_f32_e32 v56, 0xba800000, v43
	v_mov_b32_e32 v64, v53
	v_mov_b32_e32 v65, v45
	v_mov_b32_e32 v53, v44
	v_mov_b32_e32 v44, v55
	v_mov_b32_e32 v45, v47
	v_mov_b32_e32 v55, v46
	v_fmac_f32_e32 v57, 0xba800000, v43
	v_fmac_f32_e32 v48, 0xba800000, v43
	v_mul_f32_e32 v46, v56, v56
	v_pk_mul_f32 v[66:67], v[64:65], v[64:65]
	v_pk_mul_f32 v[68:69], v[52:53], v[52:53]
	v_pk_mul_f32 v[70:71], v[44:45], v[44:45]
	v_pk_mul_f32 v[72:73], v[54:55], v[54:55]
	v_fmac_f32_e32 v49, 0xba800000, v43
	v_fmac_f32_e32 v59, 0xba800000, v43
	v_mul_f32_e32 v58, v48, v48
	v_pk_fma_f32 v[46:47], v[56:57], v[56:57], v[46:47] op_sel_hi:[1,1,0]
	v_pk_mov_b32 v[76:77], v[68:69], v[66:67] op_sel:[1,0]
	v_mov_b32_e32 v69, v67
	v_pk_mov_b32 v[66:67], v[72:73], v[70:71] op_sel:[1,0]
	v_mov_b32_e32 v73, v71
	v_mov_b32_e32 v60, v59
	v_pk_fma_f32 v[74:75], v[48:49], v[48:49], v[58:59] op_sel_hi:[1,1,0]
	v_mul_f32_e32 v46, v59, v59
	v_pk_add_f32 v[58:59], v[76:77], v[68:69]
	v_pk_add_f32 v[66:67], v[66:67], v[72:73]
	v_fmac_f32_e32 v51, 0xba800000, v43
	v_fmac_f32_e32 v63, 0xba800000, v43
	v_fmac_f32_e32 v61, 0xba800000, v43
	v_pk_add_f32 v[58:59], v[58:59], v[58:59] op_sel_hi:[0,1]
	v_pk_add_f32 v[66:67], v[66:67], v[66:67] op_sel_hi:[0,1]
	v_mul_f32_e32 v74, v61, v61
	v_mul_f32_e32 v58, v63, v63
	v_mul_f32_e32 v66, v51, v51
	v_pk_add_f32 v[46:47], v[46:47], v[74:75]
	v_pk_add_f32 v[58:59], v[58:59], v[66:67]
	v_mov_b32_e32 v50, v63
	v_pk_add_f32 v[46:47], v[46:47], v[58:59]
	s_nop 0
	v_add_f32_e32 v43, v46, v47
	ds_bpermute_b32 v46, v36, v43
	s_waitcnt lgkmcnt(0)
	v_add_f32_e32 v43, v43, v46
	ds_bpermute_b32 v46, v37, v43
	s_waitcnt lgkmcnt(0)
	v_add_f32_e32 v43, v43, v46
	ds_bpermute_b32 v46, v38, v43
	s_waitcnt lgkmcnt(0)
	v_add_f32_e32 v43, v43, v46
	ds_bpermute_b32 v46, v39, v43
	s_waitcnt lgkmcnt(0)
	v_add_f32_e32 v43, v43, v46
	ds_bpermute_b32 v46, v40, v43
	s_waitcnt lgkmcnt(0)
	v_add_f32_e32 v43, v43, v46
	ds_bpermute_b32 v46, v41, v43
	s_waitcnt lgkmcnt(0)
	v_add_f32_e32 v43, v43, v46
	v_fmamk_f32 v43, v43, 0x3a800000, v42
	v_rsq_f32_e32 v46, v43
	s_nop 0
	v_pk_mul_f32 v[52:53], v[52:53], v[46:47] op_sel_hi:[1,0]
	v_pk_mul_f32 v[58:59], v[64:65], v[46:47] op_sel_hi:[1,0]
	v_pk_mul_f32 v[54:55], v[54:55], v[46:47] op_sel_hi:[1,0]
	v_pk_mul_f32 v[62:63], v[44:45], v[46:47] op_sel_hi:[1,0]
	v_pk_mul_f32 v[56:57], v[56:57], v[46:47] op_sel_hi:[1,0]
	v_pk_mul_f32 v[64:65], v[48:49], v[46:47] op_sel_hi:[1,0]
	v_pk_mul_f32 v[60:61], v[60:61], v[46:47] op_sel_hi:[1,0]
	v_pk_mul_f32 v[66:67], v[50:51], v[46:47] op_sel_hi:[1,0]
	v_pk_fma_f32 v[46:47], v[2:3], v[58:59], v[6:7]
	v_pk_fma_f32 v[44:45], v[0:1], v[52:53], v[4:5]
	v_pk_fma_f32 v[50:51], v[10:11], v[62:63], v[18:19]
	v_pk_fma_f32 v[48:49], v[8:9], v[54:55], v[16:17]
	v_pk_fma_f32 v[54:55], v[14:15], v[64:65], v[22:23]
	v_pk_fma_f32 v[52:53], v[12:13], v[56:57], v[20:21]
	v_pk_fma_f32 v[58:59], v[26:27], v[66:67], v[30:31]
	v_pk_fma_f32 v[56:57], v[24:25], v[60:61], v[28:29]
	s_waitcnt vmcnt(0)
	global_store_dwordx4 v[34:35], v[44:47], off offset:-3072 sc1
	global_store_dwordx4 v[34:35], v[48:51], off offset:-2048 sc1
	global_store_dwordx4 v[34:35], v[52:55], off offset:-1024 sc1
	global_store_dwordx4 v[34:35], v[56:59], off sc1
	v_lshl_add_u64 v[34:35], v[34:35], 0, s[4:5]
	s_nop 1
	v_mov_b64_e32 v[44:45], v[80:81]
	v_mov_b64_e32 v[46:47], v[82:83]
	v_mov_b64_e32 v[48:49], v[84:85]
	v_mov_b64_e32 v[50:51], v[86:87]
	s_cbranch_scc1 .LBB0_2458
